# redundant-wait elimination: 184 s_waitcnt lgkmcnt(0) with provably nothing outstanding since the previous full wait (straight-line tracking) removed, mostly behind the DPP-converted steps
# speedup vs baseline: 1.0017x; 1.0017x over previous
; __device__ __forceinline__ u32x2 pack4(f32x4 v) { u32x2 r; r.x = cvt_pk(v[0], v[1]); r.y = cvt_pk(v[2], v[3]); return r; }
; __device__ __forceinline__ void phaseA(const Params& p, const int wv, const int rep) {
;     ...
;     while (r_ < rend) {
;       const int rn = r_ + nw;
;       f32x4 vn[4] = {v[0], v[1], v[2], v[3]};
;       if (rn < rend) { const float* x = rowsrc(rn);
; #pragma unroll
;         for (int i = 0; i < 4; ++i) vn[i] = *(const f32x4*)(x + (i * 64 + lane) * 4); }
;       const int r = r_ >= T + 2048 ? r_ - (T + 2048) : r_;
;       const float* w = r < T ? p.in[7] : p.in[19];
;       u16* dst = r < T ? XN + (size_t)r * 1024 : MN + (size_t)(r - T) * 1024;
;       float ss = 0.f;
; #pragma unroll
;       for (int i = 0; i < 4; ++i) ss += v[i][0] * v[i][0] + v[i][1] * v[i][1] + v[i][2] * v[i][2] + v[i][3] * v[i][3];
;       ss = wave_sum(ss);
;       const float rstd = rsqrtf(ss * (1.f / 1024.f) + EPS);
; #pragma unroll
;       for (int i = 0; i < 4; ++i) { f32x4 wv4 = *(const f32x4*)(w + (i * 64 + lane) * 4); *(u32x2*)(dst + (i * 64 + lane) * 4) = pack4(v[i] * rstd * wv4); }
; #pragma unroll
;       for (int i = 0; i < 4; ++i) v[i] = vn[i];
;       r_ = rn;
;     }
.LBB0_100:
	s_add_i32 s0, s18, 0xffffb780
	s_cmpk_gt_i32 s18, 0x487f
	s_cselect_b32 s0, s0, s18
	s_add_i32 s8, s0, 0xffffbf80
	s_ashr_i32 s9, s0, 31
	v_readlane_b32 s56, v251, 6
	v_readlane_b32 s12, v251, 22
	s_cmpk_lt_i32 s0, 0x4080
	v_readlane_b32 s70, v251, 20
	v_readlane_b32 s71, v251, 21
	v_readlane_b32 s18, v251, 28
	v_readlane_b32 s19, v251, 29
	s_cselect_b32 s10, s71, s19
	s_cselect_b32 s11, s70, s18
	v_mov_b32_e32 v42, s11
	v_mov_b32_e32 v43, s10
	v_lshl_add_u64 v[42:43], v[34:35], 2, v[42:43]
	v_pk_mul_f32 v[44:45], v[38:39], v[38:39]
	v_pk_mul_f32 v[48:49], v[36:37], v[36:37]
	v_mbcnt_lo_u32_b32 v62, -1, 0
	v_mbcnt_hi_u32_b32 v62, -1, v62
	v_mbcnt_lo_u32_b32 v63, -1, 0
	v_mbcnt_hi_u32_b32 v63, -1, v63
	v_mbcnt_lo_u32_b32 v64, -1, 0
	v_mbcnt_hi_u32_b32 v64, -1, v64
	v_mbcnt_lo_u32_b32 v65, -1, 0
	v_mbcnt_hi_u32_b32 v65, -1, v65
	v_mbcnt_lo_u32_b32 v66, -1, 0
	v_mbcnt_hi_u32_b32 v66, -1, v66
	v_mbcnt_lo_u32_b32 v67, -1, 0
	v_mbcnt_hi_u32_b32 v67, -1, v67
	global_load_dwordx4 v[36:39], v[42:43], off
	v_pk_mul_f32 v[56:57], v[14:15], v[14:15]
	v_pk_mul_f32 v[58:59], v[10:11], v[10:11]
	v_pk_mul_f32 v[52:53], v[16:17], v[16:17]
	v_pk_mul_f32 v[54:55], v[12:13], v[12:13]
	v_mov_b32_e32 v60, v56
	v_mov_b32_e32 v61, v58
	v_mov_b32_e32 v58, v57
	v_pk_add_f32 v[56:57], v[60:61], v[58:59]
	v_mov_b32_e32 v58, v52
	v_mov_b32_e32 v59, v54
	v_pk_mul_f32 v[50:51], v[6:7], v[6:7]
	v_pk_add_f32 v[56:57], v[58:59], v[56:57]
	v_mov_b32_e32 v54, v53
	v_pk_mul_f32 v[46:47], v[8:9], v[8:9]
	v_pk_add_f32 v[52:53], v[54:55], v[56:57]
	v_mov_b32_e32 v54, v48
	v_mov_b32_e32 v55, v50
	v_mov_b32_e32 v50, v49
	v_pk_add_f32 v[48:49], v[54:55], v[50:51]
	v_mov_b32_e32 v50, v44
	v_mov_b32_e32 v51, v46
	v_pk_add_f32 v[48:49], v[50:51], v[48:49]
	v_mov_b32_e32 v46, v45
	v_pk_add_f32 v[44:45], v[46:47], v[48:49]
	v_add_f32_e32 v46, v52, v53
	v_add_f32_e32 v45, v45, v46
	v_add_f32_e32 v44, v44, v45
	v_lshlrev_b32_e32 v45, 2, v62
	v_xor_b32_e32 v45, 0x80, v45
	ds_bpermute_b32 v45, v45, v44
	v_lshlrev_b32_e32 v46, 2, v67
	v_xor_b32_e32 v46, 4, v46
	s_cselect_b32 s9, s9, 0
	s_cselect_b32 s8, s0, s8
	s_waitcnt lgkmcnt(0)
	v_add_f32_e32 v44, v44, v45
	v_lshlrev_b32_e32 v45, 2, v63
	v_xor_b32_e32 v45, 64, v45
	ds_bpermute_b32 v45, v45, v44
	s_cselect_b32 s0, s49, s55
	s_cselect_b32 s10, s48, s54
	s_lshl_b64 s[8:9], s[8:9], 11
	s_add_u32 s8, s10, s8
	s_waitcnt lgkmcnt(0)
	v_add_f32_e32 v44, v44, v45
	v_lshlrev_b32_e32 v45, 2, v64
	v_xor_b32_e32 v45, 32, v45
	s_nop 1
	v_mov_b32_dpp v45, v44 row_ror:8 row_mask:0xf bank_mask:0xf
	s_addc_u32 s9, s0, s9
	v_lshl_add_u64 v[48:49], v[34:35], 1, s[8:9]
	v_readlane_b32 s57, v251, 7
	v_readlane_b32 s58, v251, 8
	v_add_f32_e32 v44, v44, v45
	v_lshlrev_b32_e32 v45, 2, v65
	v_xor_b32_e32 v45, 16, v45
	s_nop 1
	v_mov_b32_dpp v45, v44 row_shl:4 row_mask:0xf bank_mask:0x5
	v_mov_b32_dpp v45, v44 row_shr:4 row_mask:0xf bank_mask:0xa
	v_readlane_b32 s59, v251, 9
	v_readlane_b32 s60, v251, 10
	v_readlane_b32 s61, v251, 11
	v_readlane_b32 s62, v251, 12
	v_add_f32_e32 v44, v44, v45
	v_lshlrev_b32_e32 v45, 2, v66
	v_xor_b32_e32 v45, 8, v45
	s_nop 1
	v_mov_b32_dpp v45, v44 quad_perm:[2,3,0,1] row_mask:0xf bank_mask:0xf
	v_readlane_b32 s63, v251, 13
	v_readlane_b32 s64, v251, 14
	v_readlane_b32 s65, v251, 15
	v_readlane_b32 s66, v251, 16
	v_add_f32_e32 v44, v44, v45
	ds_bpermute_b32 v45, v46, v44
	v_readlane_b32 s67, v251, 17
	v_readlane_b32 s68, v251, 18
	v_readlane_b32 s69, v251, 19
	v_readlane_b32 s56, v251, 38
	s_waitcnt lgkmcnt(0)
	v_add_f32_e32 v44, v44, v45
	v_fmamk_f32 v44, v44, 0x3a800000, v41
	v_mul_f32_e32 v45, 0x4b800000, v44
	v_cmp_gt_f32_e32 vcc, s30, v44
	s_mov_b32 s18, s28
	v_readlane_b32 s57, v251, 39
	v_cndmask_b32_e32 v44, v44, v45, vcc
	v_rsq_f32_e32 v44, v44
	v_readlane_b32 s62, v251, 44
	v_readlane_b32 s63, v251, 45
	v_readlane_b32 s13, v251, 23
	v_mul_f32_e32 v45, 0x45800000, v44
	v_cndmask_b32_e32 v46, v44, v45, vcc
	v_pk_mul_f32 v[14:15], v[14:15], v[46:47] op_sel_hi:[1,0]
	v_pk_mul_f32 v[16:17], v[16:17], v[46:47] op_sel_hi:[1,0]
	s_waitcnt vmcnt(0)
	v_pk_mul_f32 v[14:15], v[36:37], v[14:15]
	v_pk_mul_f32 v[16:17], v[38:39], v[16:17]
	v_cvt_pk_bf16_f32 v14, v14, v15
	v_cvt_pk_bf16_f32 v15, v16, v17
	global_store_dwordx2 v[48:49], v[14:15], off
	global_load_dwordx4 v[14:17], v[42:43], off offset:1024
	v_pk_mul_f32 v[10:11], v[10:11], v[46:47] op_sel_hi:[1,0]
	v_pk_mul_f32 v[12:13], v[12:13], v[46:47] op_sel_hi:[1,0]
	v_pk_mul_f32 v[6:7], v[6:7], v[46:47] op_sel_hi:[1,0]
	v_pk_mul_f32 v[8:9], v[8:9], v[46:47] op_sel_hi:[1,0]
	v_pk_mul_f32 v[50:51], v[2:3], v[46:47] op_sel_hi:[1,0]
	v_pk_mul_f32 v[46:47], v[4:5], v[46:47] op_sel_hi:[1,0]
	v_mov_b64_e32 v[2:3], v[18:19]
	v_mov_b32_e32 v36, v18
	v_mov_b32_e32 v37, v19
	v_mov_b32_e32 v38, v20
	s_andn2_b64 vcc, exec, s[2:3]
	v_mov_b64_e32 v[4:5], v[20:21]
	v_mov_b32_e32 v39, v21
	v_readlane_b32 s14, v251, 24
	v_readlane_b32 s15, v251, 25
	v_readlane_b32 s16, v251, 26
	v_readlane_b32 s17, v251, 27
	v_readlane_b32 s20, v251, 30
	v_readlane_b32 s21, v251, 31
	v_readlane_b32 s22, v251, 32
	v_readlane_b32 s23, v251, 33
	v_readlane_b32 s24, v251, 34
	v_readlane_b32 s25, v251, 35
	v_readlane_b32 s26, v251, 36
	v_readlane_b32 s27, v251, 37
	v_readlane_b32 s58, v251, 40
	v_readlane_b32 s59, v251, 41
	v_readlane_b32 s60, v251, 42
	v_readlane_b32 s61, v251, 43
	v_readlane_b32 s64, v251, 46
	v_readlane_b32 s65, v251, 47
	v_readlane_b32 s66, v251, 48
	v_readlane_b32 s67, v251, 49
	v_readlane_b32 s68, v251, 50
	v_readlane_b32 s69, v251, 51
	v_readlane_b32 s70, v251, 52
	v_readlane_b32 s71, v251, 53
	s_waitcnt vmcnt(0)
	v_pk_mul_f32 v[12:13], v[16:17], v[12:13]
	v_pk_mul_f32 v[10:11], v[14:15], v[10:11]
	v_mov_b32_e32 v14, v22
	v_cvt_pk_bf16_f32 v10, v10, v11
	v_cvt_pk_bf16_f32 v11, v12, v13
	global_store_dwordx2 v[48:49], v[10:11], off offset:512
	global_load_dwordx4 v[10:13], v[42:43], off offset:2048
	v_mov_b32_e32 v15, v23
	v_mov_b32_e32 v16, v24
	v_mov_b32_e32 v17, v25
	s_waitcnt vmcnt(0)
	v_pk_mul_f32 v[8:9], v[12:13], v[8:9]
	v_pk_mul_f32 v[6:7], v[10:11], v[6:7]
	v_mov_b32_e32 v10, v26
	v_cvt_pk_bf16_f32 v6, v6, v7
	v_cvt_pk_bf16_f32 v7, v8, v9
	global_store_dwordx2 v[48:49], v[6:7], off offset:1024
	global_load_dwordx4 v[42:45], v[42:43], off offset:3072
	v_mov_b32_e32 v11, v27
	v_mov_b32_e32 v12, v28
	v_mov_b32_e32 v13, v29
	v_mov_b32_e32 v6, v30
	v_mov_b32_e32 v7, v31
	v_mov_b32_e32 v8, v32
	v_mov_b32_e32 v9, v33
	s_waitcnt vmcnt(0)
	v_pk_mul_f32 v[22:23], v[44:45], v[46:47]
	v_pk_mul_f32 v[24:25], v[42:43], v[50:51]
	s_nop 0
	v_cvt_pk_bf16_f32 v24, v24, v25
	v_cvt_pk_bf16_f32 v25, v22, v23
	global_store_dwordx2 v[48:49], v[24:25], off offset:1536
	s_cbranch_vccz .LBB0_109

; __device__ __forceinline__ float shfl_idx_f(float v, int src) { return __int_as_float(__builtin_amdgcn_ds_bpermute(src << 2, __float_as_int(v))); }
; __device__ __forceinline__ void ssd_sample_item(const Params& p, int item, const int wv) {
;     ...
;   const float dt = DT[(size_t)tok * 16 + h];
;   const float dA = __expf(-dt * __expf(p.in[16][h]));
;   const float* st = p.in[6] + ((size_t)(b * 16 + h) * 64) * 128;
;   float* so = p.out + O_SSMS + ((size_t)(b * 16 + h) * 64) * 128;
;   float ymine = 0.f;
; #pragma unroll 8
;   for (int r = 0; r < 32; ++r) {
;     const int pp = 2 * r + hf;
;     f32x4 hv = *(const f32x4*)(st + (size_t)pp * 128 + n4);
;     const float xp = shfl_idx_f(x, pp) * dt;
;     f32x4 hn;
;     float yp = 0.f;
; #pragma unroll
;     for (int e = 0; e < 4; ++e) { hn[e] = dA * hv[e] + xp * Bv[e]; yp += hn[e] * Cv[e]; }
;     *(f32x4*)(so + (size_t)pp * 128 + n4) = hn;
.LBB0_457:
	v_subrev_u32_e32 v65, 56, v32
	v_mbcnt_lo_u32_b32 v3, -1, 0
	v_mbcnt_hi_u32_b32 v3, -1, v3
	v_lshlrev_b32_e32 v3, 2, v3
	v_xor_b32_e32 v22, 64, v3
	v_xor_b32_e32 v23, 32, v3
	v_xor_b32_e32 v24, 16, v3
	v_xor_b32_e32 v25, 8, v3
	v_xor_b32_e32 v26, 4, v3
	s_mov_b64 s[12:13], 0x0
	v_lshl_add_u64 v[66:67], v[18:19], 0, s[12:13]
	global_load_dwordx4 v[84:87], v[66:67], off
	global_load_dwordx4 v[88:91], v[66:67], off offset:1024
	global_load_dwordx4 v[92:95], v[66:67], off offset:2048
	global_load_dwordx4 v[96:99], v[66:67], off offset:3072
	s_mov_b64 s[12:13], 0x1000
	v_lshl_add_u64 v[66:67], v[18:19], 0, s[12:13]
	global_load_dwordx4 v[100:103], v[66:67], off
	global_load_dwordx4 v[104:107], v[66:67], off offset:1024
	global_load_dwordx4 v[108:111], v[66:67], off offset:2048
	global_load_dwordx4 v[112:115], v[66:67], off offset:3072
	s_mov_b64 s[12:13], 0x2000
	v_lshl_add_u64 v[66:67], v[18:19], 0, s[12:13]
	global_load_dwordx4 v[116:119], v[66:67], off
	global_load_dwordx4 v[120:123], v[66:67], off offset:1024
	global_load_dwordx4 v[124:127], v[66:67], off offset:2048
	global_load_dwordx4 v[128:131], v[66:67], off offset:3072
	s_mov_b64 s[12:13], 0x3000
	v_lshl_add_u64 v[66:67], v[18:19], 0, s[12:13]
	global_load_dwordx4 v[132:135], v[66:67], off
	global_load_dwordx4 v[136:139], v[66:67], off offset:1024
	global_load_dwordx4 v[140:143], v[66:67], off offset:2048
	global_load_dwordx4 v[144:147], v[66:67], off offset:3072
	s_mov_b64 s[12:13], 0x4000
	v_lshl_add_u64 v[66:67], v[18:19], 0, s[12:13]
	global_load_dwordx4 v[148:151], v[66:67], off
	global_load_dwordx4 v[152:155], v[66:67], off offset:1024
	global_load_dwordx4 v[156:159], v[66:67], off offset:2048
	global_load_dwordx4 v[164:167], v[66:67], off offset:3072
	s_mov_b64 s[12:13], 0x5000
	v_lshl_add_u64 v[66:67], v[18:19], 0, s[12:13]
	global_load_dwordx4 v[168:171], v[66:67], off
	global_load_dwordx4 v[172:175], v[66:67], off offset:1024
	global_load_dwordx4 v[176:179], v[66:67], off offset:2048
	global_load_dwordx4 v[180:183], v[66:67], off offset:3072
	s_mov_b64 s[12:13], 0x6000
	v_lshl_add_u64 v[66:67], v[18:19], 0, s[12:13]
	global_load_dwordx4 v[184:187], v[66:67], off
	global_load_dwordx4 v[188:191], v[66:67], off offset:1024
	global_load_dwordx4 v[192:195], v[66:67], off offset:2048
	global_load_dwordx4 v[196:199], v[66:67], off offset:3072
	s_mov_b64 s[12:13], 0x7000
	v_lshl_add_u64 v[66:67], v[18:19], 0, s[12:13]
	global_load_dwordx4 v[200:203], v[66:67], off
	global_load_dwordx4 v[204:207], v[66:67], off offset:1024
	global_load_dwordx4 v[208:211], v[66:67], off offset:2048
	global_load_dwordx4 v[212:215], v[66:67], off offset:3072
	ds_bpermute_b32 v33, v65, v31
	ds_bpermute_b32 v34, v65, v31 offset:8
	ds_bpermute_b32 v35, v65, v31 offset:16
	ds_bpermute_b32 v36, v65, v31 offset:24
	ds_bpermute_b32 v37, v65, v31 offset:32
	ds_bpermute_b32 v38, v65, v31 offset:40
	ds_bpermute_b32 v39, v65, v31 offset:48
	ds_bpermute_b32 v40, v65, v31 offset:56
	ds_bpermute_b32 v41, v65, v31 offset:64
	ds_bpermute_b32 v42, v65, v31 offset:72
	ds_bpermute_b32 v43, v65, v31 offset:80
	ds_bpermute_b32 v44, v65, v31 offset:88
	ds_bpermute_b32 v45, v65, v31 offset:96
	ds_bpermute_b32 v46, v65, v31 offset:104
	ds_bpermute_b32 v47, v65, v31 offset:112
	ds_bpermute_b32 v48, v65, v31 offset:120
	s_waitcnt lgkmcnt(0)
	ds_bpermute_b32 v49, v65, v31 offset:128
	ds_bpermute_b32 v50, v65, v31 offset:136
	ds_bpermute_b32 v51, v65, v31 offset:144
	ds_bpermute_b32 v52, v65, v31 offset:152
	ds_bpermute_b32 v53, v65, v31 offset:160
	ds_bpermute_b32 v54, v65, v31 offset:168
	ds_bpermute_b32 v55, v65, v31 offset:176
	ds_bpermute_b32 v56, v65, v31 offset:184
	ds_bpermute_b32 v57, v65, v31 offset:192
	ds_bpermute_b32 v58, v65, v31 offset:200
	ds_bpermute_b32 v59, v65, v31 offset:208
	ds_bpermute_b32 v60, v65, v31 offset:216
	ds_bpermute_b32 v61, v65, v31 offset:224
	ds_bpermute_b32 v62, v65, v31 offset:232
	ds_bpermute_b32 v63, v65, v31 offset:240
	ds_bpermute_b32 v64, v65, v31 offset:248
	s_waitcnt lgkmcnt(0)
	v_mul_f32_e32 v33, v30, v33
	v_mul_f32_e32 v34, v30, v34
	v_mul_f32_e32 v35, v30, v35
	v_mul_f32_e32 v36, v30, v36
	v_mul_f32_e32 v37, v30, v37
	v_mul_f32_e32 v38, v30, v38
	v_mul_f32_e32 v39, v30, v39
	v_mul_f32_e32 v40, v30, v40
	v_mul_f32_e32 v41, v30, v41
	v_mul_f32_e32 v42, v30, v42
	v_mul_f32_e32 v43, v30, v43
	v_mul_f32_e32 v44, v30, v44
	v_mul_f32_e32 v45, v30, v45
	v_mul_f32_e32 v46, v30, v46
	v_mul_f32_e32 v47, v30, v47
	v_mul_f32_e32 v48, v30, v48
	v_mul_f32_e32 v49, v30, v49
	v_mul_f32_e32 v50, v30, v50
	v_mul_f32_e32 v51, v30, v51
	v_mul_f32_e32 v52, v30, v52
	v_mul_f32_e32 v53, v30, v53
	v_mul_f32_e32 v54, v30, v54
	v_mul_f32_e32 v55, v30, v55
	v_mul_f32_e32 v56, v30, v56
	v_mul_f32_e32 v57, v30, v57
	v_mul_f32_e32 v58, v30, v58
	v_mul_f32_e32 v59, v30, v59
	v_mul_f32_e32 v60, v30, v60
	v_mul_f32_e32 v61, v30, v61
	v_mul_f32_e32 v62, v30, v62
	v_mul_f32_e32 v63, v30, v63
	v_mul_f32_e32 v64, v30, v64
	s_mov_b64 s[12:13], 0x4ee4000
	v_lshl_add_u64 v[68:69], v[20:21], 0, s[12:13]
	s_waitcnt vmcnt(31)
	v_mul_f32_e32 v216, v6, v33
	v_mul_f32_e32 v217, v7, v33
	v_mul_f32_e32 v218, v10, v33
	v_mul_f32_e32 v219, v11, v33
	v_fma_f32 v84, v12, v84, v216
	v_fma_f32 v85, v12, v85, v217
	v_fma_f32 v86, v12, v86, v218
	v_fma_f32 v87, v12, v87, v219
	global_store_dwordx4 v[68:69], v[84:87], off
	v_mul_f32_e32 v216, v8, v84
	v_mul_f32_e32 v217, v9, v85
	v_mul_f32_e32 v218, v14, v86
	v_mul_f32_e32 v219, v15, v87
	v_add_f32_e32 v33, 0, v216
	v_add_f32_e32 v33, v217, v33
	v_add_f32_e32 v33, v218, v33
	v_add_f32_e32 v33, v219, v33
	s_waitcnt vmcnt(31)
; __device__ __forceinline__ float shfl_idx_f(float v, int src) { return __int_as_float(__builtin_amdgcn_ds_bpermute(src << 2, __float_as_int(v))); }
; __device__ __forceinline__ void ssd_sample_item(const Params& p, int item, const int wv) {
;     ...
;   for (int r = 0; r < 32; ++r) {
;     const int pp = 2 * r + hf;
;     f32x4 hv = *(const f32x4*)(st + (size_t)pp * 128 + n4);
;     const float xp = shfl_idx_f(x, pp) * dt;
;     f32x4 hn;
;     float yp = 0.f;
; #pragma unroll
;     for (int e = 0; e < 4; ++e) { hn[e] = dA * hv[e] + xp * Bv[e]; yp += hn[e] * Cv[e]; }
;     *(f32x4*)(so + (size_t)pp * 128 + n4) = hn;
	v_mul_f32_e32 v216, v6, v34
	v_mul_f32_e32 v217, v7, v34
	v_mul_f32_e32 v218, v10, v34
	v_mul_f32_e32 v219, v11, v34
	v_fma_f32 v88, v12, v88, v216
	v_fma_f32 v89, v12, v89, v217
	v_fma_f32 v90, v12, v90, v218
	v_fma_f32 v91, v12, v91, v219
	global_store_dwordx4 v[68:69], v[88:91], off offset:1024
	v_mul_f32_e32 v216, v8, v88
	v_mul_f32_e32 v217, v9, v89
	v_mul_f32_e32 v218, v14, v90
	v_mul_f32_e32 v219, v15, v91
	v_add_f32_e32 v34, 0, v216
	v_add_f32_e32 v34, v217, v34
	v_add_f32_e32 v34, v218, v34
	v_add_f32_e32 v34, v219, v34
	s_waitcnt vmcnt(31)
	v_mul_f32_e32 v216, v6, v35
	v_mul_f32_e32 v217, v7, v35
	v_mul_f32_e32 v218, v10, v35
	v_mul_f32_e32 v219, v11, v35
	v_fma_f32 v92, v12, v92, v216
	v_fma_f32 v93, v12, v93, v217
	v_fma_f32 v94, v12, v94, v218
	v_fma_f32 v95, v12, v95, v219
	global_store_dwordx4 v[68:69], v[92:95], off offset:2048
	v_mul_f32_e32 v216, v8, v92
	v_mul_f32_e32 v217, v9, v93
	v_mul_f32_e32 v218, v14, v94
	v_mul_f32_e32 v219, v15, v95
	v_add_f32_e32 v35, 0, v216
	v_add_f32_e32 v35, v217, v35
	v_add_f32_e32 v35, v218, v35
	v_add_f32_e32 v35, v219, v35
	s_waitcnt vmcnt(31)
	v_mul_f32_e32 v216, v6, v36
	v_mul_f32_e32 v217, v7, v36
	v_mul_f32_e32 v218, v10, v36
	v_mul_f32_e32 v219, v11, v36
	v_fma_f32 v96, v12, v96, v216
	v_fma_f32 v97, v12, v97, v217
	v_fma_f32 v98, v12, v98, v218
	v_fma_f32 v99, v12, v99, v219
	global_store_dwordx4 v[68:69], v[96:99], off offset:3072
	v_mul_f32_e32 v216, v8, v96
	v_mul_f32_e32 v217, v9, v97
	v_mul_f32_e32 v218, v14, v98
	v_mul_f32_e32 v219, v15, v99
	v_add_f32_e32 v36, 0, v216
	v_add_f32_e32 v36, v217, v36
	v_add_f32_e32 v36, v218, v36
	v_add_f32_e32 v36, v219, v36
	s_mov_b64 s[12:13], 0x4ee5000
	v_lshl_add_u64 v[68:69], v[20:21], 0, s[12:13]
	s_waitcnt vmcnt(31)
	v_mul_f32_e32 v216, v6, v37
	v_mul_f32_e32 v217, v7, v37
	v_mul_f32_e32 v218, v10, v37
	v_mul_f32_e32 v219, v11, v37
	v_fma_f32 v100, v12, v100, v216
	v_fma_f32 v101, v12, v101, v217
	v_fma_f32 v102, v12, v102, v218
	v_fma_f32 v103, v12, v103, v219
	global_store_dwordx4 v[68:69], v[100:103], off
	v_mul_f32_e32 v216, v8, v100
	v_mul_f32_e32 v217, v9, v101
	v_mul_f32_e32 v218, v14, v102
	v_mul_f32_e32 v219, v15, v103
	v_add_f32_e32 v37, 0, v216
	v_add_f32_e32 v37, v217, v37
	v_add_f32_e32 v37, v218, v37
	v_add_f32_e32 v37, v219, v37
	s_waitcnt vmcnt(31)
	v_mul_f32_e32 v216, v6, v38
	v_mul_f32_e32 v217, v7, v38
	v_mul_f32_e32 v218, v10, v38
	v_mul_f32_e32 v219, v11, v38
	v_fma_f32 v104, v12, v104, v216
	v_fma_f32 v105, v12, v105, v217
	v_fma_f32 v106, v12, v106, v218
	v_fma_f32 v107, v12, v107, v219
	global_store_dwordx4 v[68:69], v[104:107], off offset:1024
	v_mul_f32_e32 v216, v8, v104
	v_mul_f32_e32 v217, v9, v105
	v_mul_f32_e32 v218, v14, v106
	v_mul_f32_e32 v219, v15, v107
	v_add_f32_e32 v38, 0, v216
	v_add_f32_e32 v38, v217, v38
	v_add_f32_e32 v38, v218, v38
	v_add_f32_e32 v38, v219, v38
	s_waitcnt vmcnt(31)
	v_mul_f32_e32 v216, v6, v39
	v_mul_f32_e32 v217, v7, v39
	v_mul_f32_e32 v218, v10, v39
	v_mul_f32_e32 v219, v11, v39
	v_fma_f32 v108, v12, v108, v216
	v_fma_f32 v109, v12, v109, v217
	v_fma_f32 v110, v12, v110, v218
	v_fma_f32 v111, v12, v111, v219
	global_store_dwordx4 v[68:69], v[108:111], off offset:2048
	v_mul_f32_e32 v216, v8, v108
	v_mul_f32_e32 v217, v9, v109
	v_mul_f32_e32 v218, v14, v110
	v_mul_f32_e32 v219, v15, v111
	v_add_f32_e32 v39, 0, v216
	v_add_f32_e32 v39, v217, v39
	v_add_f32_e32 v39, v218, v39
	v_add_f32_e32 v39, v219, v39
	s_waitcnt vmcnt(31)
	v_mul_f32_e32 v216, v6, v40
	v_mul_f32_e32 v217, v7, v40
	v_mul_f32_e32 v218, v10, v40
	v_mul_f32_e32 v219, v11, v40
	v_fma_f32 v112, v12, v112, v216
	v_fma_f32 v113, v12, v113, v217
	v_fma_f32 v114, v12, v114, v218
	v_fma_f32 v115, v12, v115, v219
	global_store_dwordx4 v[68:69], v[112:115], off offset:3072
	v_mul_f32_e32 v216, v8, v112
	v_mul_f32_e32 v217, v9, v113
	v_mul_f32_e32 v218, v14, v114
	v_mul_f32_e32 v219, v15, v115
	v_add_f32_e32 v40, 0, v216
	v_add_f32_e32 v40, v217, v40
	v_add_f32_e32 v40, v218, v40
	v_add_f32_e32 v40, v219, v40
	s_mov_b64 s[12:13], 0x4ee6000
	v_lshl_add_u64 v[68:69], v[20:21], 0, s[12:13]
	s_waitcnt vmcnt(31)
	v_mul_f32_e32 v216, v6, v41
	v_mul_f32_e32 v217, v7, v41
	v_mul_f32_e32 v218, v10, v41
	v_mul_f32_e32 v219, v11, v41
	v_fma_f32 v116, v12, v116, v216
	v_fma_f32 v117, v12, v117, v217
	v_fma_f32 v118, v12, v118, v218
	v_fma_f32 v119, v12, v119, v219
	global_store_dwordx4 v[68:69], v[116:119], off
	v_mul_f32_e32 v216, v8, v116
	v_mul_f32_e32 v217, v9, v117
	v_mul_f32_e32 v218, v14, v118
	v_mul_f32_e32 v219, v15, v119
	v_add_f32_e32 v41, 0, v216
	v_add_f32_e32 v41, v217, v41
	v_add_f32_e32 v41, v218, v41
	v_add_f32_e32 v41, v219, v41
	s_waitcnt vmcnt(31)
	v_mul_f32_e32 v216, v6, v42
	v_mul_f32_e32 v217, v7, v42
	v_mul_f32_e32 v218, v10, v42
	v_mul_f32_e32 v219, v11, v42
	v_fma_f32 v120, v12, v120, v216
	v_fma_f32 v121, v12, v121, v217
	v_fma_f32 v122, v12, v122, v218
	v_fma_f32 v123, v12, v123, v219
	global_store_dwordx4 v[68:69], v[120:123], off offset:1024
	v_mul_f32_e32 v216, v8, v120
	v_mul_f32_e32 v217, v9, v121
	v_mul_f32_e32 v218, v14, v122
	v_mul_f32_e32 v219, v15, v123
	v_add_f32_e32 v42, 0, v216
	v_add_f32_e32 v42, v217, v42
	v_add_f32_e32 v42, v218, v42
	v_add_f32_e32 v42, v219, v42
	s_waitcnt vmcnt(31)
	v_mul_f32_e32 v216, v6, v43
	v_mul_f32_e32 v217, v7, v43
	v_mul_f32_e32 v218, v10, v43
	v_mul_f32_e32 v219, v11, v43
	v_fma_f32 v124, v12, v124, v216
	v_fma_f32 v125, v12, v125, v217
	v_fma_f32 v126, v12, v126, v218
	v_fma_f32 v127, v12, v127, v219
	global_store_dwordx4 v[68:69], v[124:127], off offset:2048
	v_mul_f32_e32 v216, v8, v124
	v_mul_f32_e32 v217, v9, v125
	v_mul_f32_e32 v218, v14, v126
	v_mul_f32_e32 v219, v15, v127
	v_add_f32_e32 v43, 0, v216
	v_add_f32_e32 v43, v217, v43
	v_add_f32_e32 v43, v218, v43
	v_add_f32_e32 v43, v219, v43
	s_waitcnt vmcnt(31)
; __device__ __forceinline__ float shfl_idx_f(float v, int src) { return __int_as_float(__builtin_amdgcn_ds_bpermute(src << 2, __float_as_int(v))); }
; __device__ __forceinline__ void ssd_sample_item(const Params& p, int item, const int wv) {
;     ...
;   for (int r = 0; r < 32; ++r) {
;     const int pp = 2 * r + hf;
;     f32x4 hv = *(const f32x4*)(st + (size_t)pp * 128 + n4);
;     const float xp = shfl_idx_f(x, pp) * dt;
;     f32x4 hn;
;     float yp = 0.f;
; #pragma unroll
;     for (int e = 0; e < 4; ++e) { hn[e] = dA * hv[e] + xp * Bv[e]; yp += hn[e] * Cv[e]; }
;     *(f32x4*)(so + (size_t)pp * 128 + n4) = hn;
	v_mul_f32_e32 v216, v6, v44
	v_mul_f32_e32 v217, v7, v44
	v_mul_f32_e32 v218, v10, v44
	v_mul_f32_e32 v219, v11, v44
	v_fma_f32 v128, v12, v128, v216
	v_fma_f32 v129, v12, v129, v217
	v_fma_f32 v130, v12, v130, v218
	v_fma_f32 v131, v12, v131, v219
	global_store_dwordx4 v[68:69], v[128:131], off offset:3072
	v_mul_f32_e32 v216, v8, v128
	v_mul_f32_e32 v217, v9, v129
	v_mul_f32_e32 v218, v14, v130
	v_mul_f32_e32 v219, v15, v131
	v_add_f32_e32 v44, 0, v216
	v_add_f32_e32 v44, v217, v44
	v_add_f32_e32 v44, v218, v44
	v_add_f32_e32 v44, v219, v44
	s_mov_b64 s[12:13], 0x4ee7000
	v_lshl_add_u64 v[68:69], v[20:21], 0, s[12:13]
	s_waitcnt vmcnt(31)
	v_mul_f32_e32 v216, v6, v45
	v_mul_f32_e32 v217, v7, v45
	v_mul_f32_e32 v218, v10, v45
	v_mul_f32_e32 v219, v11, v45
	v_fma_f32 v132, v12, v132, v216
	v_fma_f32 v133, v12, v133, v217
	v_fma_f32 v134, v12, v134, v218
	v_fma_f32 v135, v12, v135, v219
	global_store_dwordx4 v[68:69], v[132:135], off
	v_mul_f32_e32 v216, v8, v132
	v_mul_f32_e32 v217, v9, v133
	v_mul_f32_e32 v218, v14, v134
	v_mul_f32_e32 v219, v15, v135
	v_add_f32_e32 v45, 0, v216
	v_add_f32_e32 v45, v217, v45
	v_add_f32_e32 v45, v218, v45
	v_add_f32_e32 v45, v219, v45
	s_waitcnt vmcnt(31)
	v_mul_f32_e32 v216, v6, v46
	v_mul_f32_e32 v217, v7, v46
	v_mul_f32_e32 v218, v10, v46
	v_mul_f32_e32 v219, v11, v46
	v_fma_f32 v136, v12, v136, v216
	v_fma_f32 v137, v12, v137, v217
	v_fma_f32 v138, v12, v138, v218
	v_fma_f32 v139, v12, v139, v219
	global_store_dwordx4 v[68:69], v[136:139], off offset:1024
	v_mul_f32_e32 v216, v8, v136
	v_mul_f32_e32 v217, v9, v137
	v_mul_f32_e32 v218, v14, v138
	v_mul_f32_e32 v219, v15, v139
	v_add_f32_e32 v46, 0, v216
	v_add_f32_e32 v46, v217, v46
	v_add_f32_e32 v46, v218, v46
	v_add_f32_e32 v46, v219, v46
	s_waitcnt vmcnt(31)
	v_mul_f32_e32 v216, v6, v47
	v_mul_f32_e32 v217, v7, v47
	v_mul_f32_e32 v218, v10, v47
	v_mul_f32_e32 v219, v11, v47
	v_fma_f32 v140, v12, v140, v216
	v_fma_f32 v141, v12, v141, v217
	v_fma_f32 v142, v12, v142, v218
	v_fma_f32 v143, v12, v143, v219
	global_store_dwordx4 v[68:69], v[140:143], off offset:2048
	v_mul_f32_e32 v216, v8, v140
	v_mul_f32_e32 v217, v9, v141
	v_mul_f32_e32 v218, v14, v142
	v_mul_f32_e32 v219, v15, v143
	v_add_f32_e32 v47, 0, v216
	v_add_f32_e32 v47, v217, v47
	v_add_f32_e32 v47, v218, v47
	v_add_f32_e32 v47, v219, v47
	s_waitcnt vmcnt(31)
	v_mul_f32_e32 v216, v6, v48
	v_mul_f32_e32 v217, v7, v48
	v_mul_f32_e32 v218, v10, v48
	v_mul_f32_e32 v219, v11, v48
	v_fma_f32 v144, v12, v144, v216
	v_fma_f32 v145, v12, v145, v217
	v_fma_f32 v146, v12, v146, v218
	v_fma_f32 v147, v12, v147, v219
	global_store_dwordx4 v[68:69], v[144:147], off offset:3072
	v_mul_f32_e32 v216, v8, v144
	v_mul_f32_e32 v217, v9, v145
	v_mul_f32_e32 v218, v14, v146
	v_mul_f32_e32 v219, v15, v147
	v_add_f32_e32 v48, 0, v216
	v_add_f32_e32 v48, v217, v48
	v_add_f32_e32 v48, v218, v48
	v_add_f32_e32 v48, v219, v48
	s_mov_b64 s[12:13], 0x4ee8000
	v_lshl_add_u64 v[68:69], v[20:21], 0, s[12:13]
	s_waitcnt vmcnt(31)
	v_mul_f32_e32 v216, v6, v49
	v_mul_f32_e32 v217, v7, v49
	v_mul_f32_e32 v218, v10, v49
	v_mul_f32_e32 v219, v11, v49
	v_fma_f32 v148, v12, v148, v216
	v_fma_f32 v149, v12, v149, v217
	v_fma_f32 v150, v12, v150, v218
	v_fma_f32 v151, v12, v151, v219
	global_store_dwordx4 v[68:69], v[148:151], off
	v_mul_f32_e32 v216, v8, v148
	v_mul_f32_e32 v217, v9, v149
	v_mul_f32_e32 v218, v14, v150
	v_mul_f32_e32 v219, v15, v151
	v_add_f32_e32 v49, 0, v216
	v_add_f32_e32 v49, v217, v49
	v_add_f32_e32 v49, v218, v49
	v_add_f32_e32 v49, v219, v49
	s_waitcnt vmcnt(31)
	v_mul_f32_e32 v216, v6, v50
	v_mul_f32_e32 v217, v7, v50
	v_mul_f32_e32 v218, v10, v50
	v_mul_f32_e32 v219, v11, v50
	v_fma_f32 v152, v12, v152, v216
	v_fma_f32 v153, v12, v153, v217
	v_fma_f32 v154, v12, v154, v218
	v_fma_f32 v155, v12, v155, v219
	global_store_dwordx4 v[68:69], v[152:155], off offset:1024
	v_mul_f32_e32 v216, v8, v152
	v_mul_f32_e32 v217, v9, v153
	v_mul_f32_e32 v218, v14, v154
	v_mul_f32_e32 v219, v15, v155
	v_add_f32_e32 v50, 0, v216
	v_add_f32_e32 v50, v217, v50
	v_add_f32_e32 v50, v218, v50
	v_add_f32_e32 v50, v219, v50
	s_waitcnt vmcnt(31)
	v_mul_f32_e32 v216, v6, v51
	v_mul_f32_e32 v217, v7, v51
	v_mul_f32_e32 v218, v10, v51
	v_mul_f32_e32 v219, v11, v51
	v_fma_f32 v156, v12, v156, v216
	v_fma_f32 v157, v12, v157, v217
	v_fma_f32 v158, v12, v158, v218
	v_fma_f32 v159, v12, v159, v219
	global_store_dwordx4 v[68:69], v[156:159], off offset:2048
	v_mul_f32_e32 v216, v8, v156
	v_mul_f32_e32 v217, v9, v157
	v_mul_f32_e32 v218, v14, v158
	v_mul_f32_e32 v219, v15, v159
	v_add_f32_e32 v51, 0, v216
	v_add_f32_e32 v51, v217, v51
	v_add_f32_e32 v51, v218, v51
	v_add_f32_e32 v51, v219, v51
	s_waitcnt vmcnt(31)
	v_mul_f32_e32 v216, v6, v52
	v_mul_f32_e32 v217, v7, v52
	v_mul_f32_e32 v218, v10, v52
	v_mul_f32_e32 v219, v11, v52
	v_fma_f32 v164, v12, v164, v216
	v_fma_f32 v165, v12, v165, v217
	v_fma_f32 v166, v12, v166, v218
	v_fma_f32 v167, v12, v167, v219
	global_store_dwordx4 v[68:69], v[164:167], off offset:3072
	v_mul_f32_e32 v216, v8, v164
	v_mul_f32_e32 v217, v9, v165
	v_mul_f32_e32 v218, v14, v166
	v_mul_f32_e32 v219, v15, v167
	v_add_f32_e32 v52, 0, v216
	v_add_f32_e32 v52, v217, v52
	v_add_f32_e32 v52, v218, v52
	v_add_f32_e32 v52, v219, v52
	s_mov_b64 s[12:13], 0x4ee9000
	v_lshl_add_u64 v[68:69], v[20:21], 0, s[12:13]
	s_waitcnt vmcnt(31)
	v_mul_f32_e32 v216, v6, v53
	v_mul_f32_e32 v217, v7, v53
	v_mul_f32_e32 v218, v10, v53
	v_mul_f32_e32 v219, v11, v53
	v_fma_f32 v168, v12, v168, v216
	v_fma_f32 v169, v12, v169, v217
	v_fma_f32 v170, v12, v170, v218
	v_fma_f32 v171, v12, v171, v219
	global_store_dwordx4 v[68:69], v[168:171], off
	v_mul_f32_e32 v216, v8, v168
	v_mul_f32_e32 v217, v9, v169
	v_mul_f32_e32 v218, v14, v170
	v_mul_f32_e32 v219, v15, v171
	v_add_f32_e32 v53, 0, v216
	v_add_f32_e32 v53, v217, v53
	v_add_f32_e32 v53, v218, v53
	v_add_f32_e32 v53, v219, v53
	s_waitcnt vmcnt(31)
; __device__ __forceinline__ float shfl_idx_f(float v, int src) { return __int_as_float(__builtin_amdgcn_ds_bpermute(src << 2, __float_as_int(v))); }
; __device__ __forceinline__ void ssd_sample_item(const Params& p, int item, const int wv) {
;     ...
;   for (int r = 0; r < 32; ++r) {
;     const int pp = 2 * r + hf;
;     f32x4 hv = *(const f32x4*)(st + (size_t)pp * 128 + n4);
;     const float xp = shfl_idx_f(x, pp) * dt;
;     f32x4 hn;
;     float yp = 0.f;
; #pragma unroll
;     for (int e = 0; e < 4; ++e) { hn[e] = dA * hv[e] + xp * Bv[e]; yp += hn[e] * Cv[e]; }
;     *(f32x4*)(so + (size_t)pp * 128 + n4) = hn;
	v_mul_f32_e32 v216, v6, v54
	v_mul_f32_e32 v217, v7, v54
	v_mul_f32_e32 v218, v10, v54
	v_mul_f32_e32 v219, v11, v54
	v_fma_f32 v172, v12, v172, v216
	v_fma_f32 v173, v12, v173, v217
	v_fma_f32 v174, v12, v174, v218
	v_fma_f32 v175, v12, v175, v219
	global_store_dwordx4 v[68:69], v[172:175], off offset:1024
	v_mul_f32_e32 v216, v8, v172
	v_mul_f32_e32 v217, v9, v173
	v_mul_f32_e32 v218, v14, v174
	v_mul_f32_e32 v219, v15, v175
	v_add_f32_e32 v54, 0, v216
	v_add_f32_e32 v54, v217, v54
	v_add_f32_e32 v54, v218, v54
	v_add_f32_e32 v54, v219, v54
	s_waitcnt vmcnt(31)
	v_mul_f32_e32 v216, v6, v55
	v_mul_f32_e32 v217, v7, v55
	v_mul_f32_e32 v218, v10, v55
	v_mul_f32_e32 v219, v11, v55
	v_fma_f32 v176, v12, v176, v216
	v_fma_f32 v177, v12, v177, v217
	v_fma_f32 v178, v12, v178, v218
	v_fma_f32 v179, v12, v179, v219
	global_store_dwordx4 v[68:69], v[176:179], off offset:2048
	v_mul_f32_e32 v216, v8, v176
	v_mul_f32_e32 v217, v9, v177
	v_mul_f32_e32 v218, v14, v178
	v_mul_f32_e32 v219, v15, v179
	v_add_f32_e32 v55, 0, v216
	v_add_f32_e32 v55, v217, v55
	v_add_f32_e32 v55, v218, v55
	v_add_f32_e32 v55, v219, v55
	s_waitcnt vmcnt(31)
	v_mul_f32_e32 v216, v6, v56
	v_mul_f32_e32 v217, v7, v56
	v_mul_f32_e32 v218, v10, v56
	v_mul_f32_e32 v219, v11, v56
	v_fma_f32 v180, v12, v180, v216
	v_fma_f32 v181, v12, v181, v217
	v_fma_f32 v182, v12, v182, v218
	v_fma_f32 v183, v12, v183, v219
	global_store_dwordx4 v[68:69], v[180:183], off offset:3072
	v_mul_f32_e32 v216, v8, v180
	v_mul_f32_e32 v217, v9, v181
	v_mul_f32_e32 v218, v14, v182
	v_mul_f32_e32 v219, v15, v183
	v_add_f32_e32 v56, 0, v216
	v_add_f32_e32 v56, v217, v56
	v_add_f32_e32 v56, v218, v56
	v_add_f32_e32 v56, v219, v56
	s_mov_b64 s[12:13], 0x4eea000
	v_lshl_add_u64 v[68:69], v[20:21], 0, s[12:13]
	s_waitcnt vmcnt(31)
	v_mul_f32_e32 v216, v6, v57
	v_mul_f32_e32 v217, v7, v57
	v_mul_f32_e32 v218, v10, v57
	v_mul_f32_e32 v219, v11, v57
	v_fma_f32 v184, v12, v184, v216
	v_fma_f32 v185, v12, v185, v217
	v_fma_f32 v186, v12, v186, v218
	v_fma_f32 v187, v12, v187, v219
	global_store_dwordx4 v[68:69], v[184:187], off
	v_mul_f32_e32 v216, v8, v184
	v_mul_f32_e32 v217, v9, v185
	v_mul_f32_e32 v218, v14, v186
	v_mul_f32_e32 v219, v15, v187
	v_add_f32_e32 v57, 0, v216
	v_add_f32_e32 v57, v217, v57
	v_add_f32_e32 v57, v218, v57
	v_add_f32_e32 v57, v219, v57
	s_waitcnt vmcnt(31)
	v_mul_f32_e32 v216, v6, v58
	v_mul_f32_e32 v217, v7, v58
	v_mul_f32_e32 v218, v10, v58
	v_mul_f32_e32 v219, v11, v58
	v_fma_f32 v188, v12, v188, v216
	v_fma_f32 v189, v12, v189, v217
	v_fma_f32 v190, v12, v190, v218
	v_fma_f32 v191, v12, v191, v219
	global_store_dwordx4 v[68:69], v[188:191], off offset:1024
	v_mul_f32_e32 v216, v8, v188
	v_mul_f32_e32 v217, v9, v189
	v_mul_f32_e32 v218, v14, v190
	v_mul_f32_e32 v219, v15, v191
	v_add_f32_e32 v58, 0, v216
	v_add_f32_e32 v58, v217, v58
	v_add_f32_e32 v58, v218, v58
	v_add_f32_e32 v58, v219, v58
	s_waitcnt vmcnt(31)
	v_mul_f32_e32 v216, v6, v59
	v_mul_f32_e32 v217, v7, v59
	v_mul_f32_e32 v218, v10, v59
	v_mul_f32_e32 v219, v11, v59
	v_fma_f32 v192, v12, v192, v216
	v_fma_f32 v193, v12, v193, v217
	v_fma_f32 v194, v12, v194, v218
	v_fma_f32 v195, v12, v195, v219
	global_store_dwordx4 v[68:69], v[192:195], off offset:2048
	v_mul_f32_e32 v216, v8, v192
	v_mul_f32_e32 v217, v9, v193
	v_mul_f32_e32 v218, v14, v194
	v_mul_f32_e32 v219, v15, v195
	v_add_f32_e32 v59, 0, v216
	v_add_f32_e32 v59, v217, v59
	v_add_f32_e32 v59, v218, v59
	v_add_f32_e32 v59, v219, v59
	s_waitcnt vmcnt(31)
	v_mul_f32_e32 v216, v6, v60
	v_mul_f32_e32 v217, v7, v60
	v_mul_f32_e32 v218, v10, v60
	v_mul_f32_e32 v219, v11, v60
	v_fma_f32 v196, v12, v196, v216
	v_fma_f32 v197, v12, v197, v217
	v_fma_f32 v198, v12, v198, v218
	v_fma_f32 v199, v12, v199, v219
	global_store_dwordx4 v[68:69], v[196:199], off offset:3072
	v_mul_f32_e32 v216, v8, v196
	v_mul_f32_e32 v217, v9, v197
	v_mul_f32_e32 v218, v14, v198
	v_mul_f32_e32 v219, v15, v199
	v_add_f32_e32 v60, 0, v216
	v_add_f32_e32 v60, v217, v60
	v_add_f32_e32 v60, v218, v60
	v_add_f32_e32 v60, v219, v60
	s_mov_b64 s[12:13], 0x4eeb000
	v_lshl_add_u64 v[68:69], v[20:21], 0, s[12:13]
	s_waitcnt vmcnt(31)
	v_mul_f32_e32 v216, v6, v61
	v_mul_f32_e32 v217, v7, v61
	v_mul_f32_e32 v218, v10, v61
	v_mul_f32_e32 v219, v11, v61
	v_fma_f32 v200, v12, v200, v216
	v_fma_f32 v201, v12, v201, v217
	v_fma_f32 v202, v12, v202, v218
	v_fma_f32 v203, v12, v203, v219
	global_store_dwordx4 v[68:69], v[200:203], off
	v_mul_f32_e32 v216, v8, v200
	v_mul_f32_e32 v217, v9, v201
	v_mul_f32_e32 v218, v14, v202
	v_mul_f32_e32 v219, v15, v203
	v_add_f32_e32 v61, 0, v216
	v_add_f32_e32 v61, v217, v61
	v_add_f32_e32 v61, v218, v61
	v_add_f32_e32 v61, v219, v61
	s_waitcnt vmcnt(31)
	v_mul_f32_e32 v216, v6, v62
	v_mul_f32_e32 v217, v7, v62
	v_mul_f32_e32 v218, v10, v62
	v_mul_f32_e32 v219, v11, v62
	v_fma_f32 v204, v12, v204, v216
	v_fma_f32 v205, v12, v205, v217
	v_fma_f32 v206, v12, v206, v218
	v_fma_f32 v207, v12, v207, v219
	global_store_dwordx4 v[68:69], v[204:207], off offset:1024
	v_mul_f32_e32 v216, v8, v204
	v_mul_f32_e32 v217, v9, v205
	v_mul_f32_e32 v218, v14, v206
	v_mul_f32_e32 v219, v15, v207
	v_add_f32_e32 v62, 0, v216
	v_add_f32_e32 v62, v217, v62
	v_add_f32_e32 v62, v218, v62
	v_add_f32_e32 v62, v219, v62
	s_waitcnt vmcnt(31)
	v_mul_f32_e32 v216, v6, v63
	v_mul_f32_e32 v217, v7, v63
	v_mul_f32_e32 v218, v10, v63
	v_mul_f32_e32 v219, v11, v63
	v_fma_f32 v208, v12, v208, v216
	v_fma_f32 v209, v12, v209, v217
	v_fma_f32 v210, v12, v210, v218
	v_fma_f32 v211, v12, v211, v219
	global_store_dwordx4 v[68:69], v[208:211], off offset:2048
	v_mul_f32_e32 v216, v8, v208
	v_mul_f32_e32 v217, v9, v209
	v_mul_f32_e32 v218, v14, v210
	v_mul_f32_e32 v219, v15, v211
	v_add_f32_e32 v63, 0, v216
	v_add_f32_e32 v63, v217, v63
	v_add_f32_e32 v63, v218, v63
	v_add_f32_e32 v63, v219, v63
	s_waitcnt vmcnt(31)
; __device__ __forceinline__ float shfl_xor_f(float v, int mask) { const int l = lane_fresh(); return __int_as_float(__builtin_amdgcn_ds_bpermute((l ^ mask) << 2, __float_as_int(v))); }
; __device__ __forceinline__ float shfl_idx_f(float v, int src) { return __int_as_float(__builtin_amdgcn_ds_bpermute(src << 2, __float_as_int(v))); }
; __device__ __forceinline__ void ssd_sample_item(const Params& p, int item, const int wv) {
;     ...
;   for (int r = 0; r < 32; ++r) {
;     const int pp = 2 * r + hf;
;     f32x4 hv = *(const f32x4*)(st + (size_t)pp * 128 + n4);
;     const float xp = shfl_idx_f(x, pp) * dt;
;     f32x4 hn;
;     float yp = 0.f;
; #pragma unroll
;     for (int e = 0; e < 4; ++e) { hn[e] = dA * hv[e] + xp * Bv[e]; yp += hn[e] * Cv[e]; }
;     *(f32x4*)(so + (size_t)pp * 128 + n4) = hn;
; #pragma unroll
;     for (int o = 16; o >= 1; o >>= 1) yp += shfl_xor_f(yp, o);
	v_mul_f32_e32 v216, v6, v64
	v_mul_f32_e32 v217, v7, v64
	v_mul_f32_e32 v218, v10, v64
	v_mul_f32_e32 v219, v11, v64
	v_fma_f32 v212, v12, v212, v216
	v_fma_f32 v213, v12, v213, v217
	v_fma_f32 v214, v12, v214, v218
	v_fma_f32 v215, v12, v215, v219
	global_store_dwordx4 v[68:69], v[212:215], off offset:3072
	v_mul_f32_e32 v216, v8, v212
	v_mul_f32_e32 v217, v9, v213
	v_mul_f32_e32 v218, v14, v214
	v_mul_f32_e32 v219, v15, v215
	v_add_f32_e32 v64, 0, v216
	v_add_f32_e32 v64, v217, v64
	v_add_f32_e32 v64, v218, v64
	v_add_f32_e32 v64, v219, v64
	ds_bpermute_b32 v66, v22, v33
	ds_bpermute_b32 v67, v22, v34
	ds_bpermute_b32 v68, v22, v35
	ds_bpermute_b32 v69, v22, v36
	ds_bpermute_b32 v70, v22, v37
	ds_bpermute_b32 v71, v22, v38
	ds_bpermute_b32 v72, v22, v39
	ds_bpermute_b32 v73, v22, v40
	ds_bpermute_b32 v74, v22, v41
	ds_bpermute_b32 v75, v22, v42
	ds_bpermute_b32 v76, v22, v43
	ds_bpermute_b32 v77, v22, v44
	ds_bpermute_b32 v78, v22, v45
	ds_bpermute_b32 v0, v22, v46
	ds_bpermute_b32 v1, v22, v47
	ds_bpermute_b32 v2, v22, v48
	s_waitcnt lgkmcnt(15)
	v_add_f32_e32 v33, v33, v66
	s_waitcnt lgkmcnt(14)
	v_add_f32_e32 v34, v34, v67
	s_waitcnt lgkmcnt(13)
	v_add_f32_e32 v35, v35, v68
	s_waitcnt lgkmcnt(12)
	v_add_f32_e32 v36, v36, v69
	s_waitcnt lgkmcnt(11)
	v_add_f32_e32 v37, v37, v70
	s_waitcnt lgkmcnt(10)
	v_add_f32_e32 v38, v38, v71
	s_waitcnt lgkmcnt(9)
	v_add_f32_e32 v39, v39, v72
	s_waitcnt lgkmcnt(8)
	v_add_f32_e32 v40, v40, v73
	s_waitcnt lgkmcnt(7)
	v_add_f32_e32 v41, v41, v74
	s_waitcnt lgkmcnt(6)
	v_add_f32_e32 v42, v42, v75
	s_waitcnt lgkmcnt(5)
	v_add_f32_e32 v43, v43, v76
	s_waitcnt lgkmcnt(4)
	v_add_f32_e32 v44, v44, v77
	s_waitcnt lgkmcnt(3)
	v_add_f32_e32 v45, v45, v78
	s_waitcnt lgkmcnt(2)
	v_add_f32_e32 v46, v46, v0
	s_waitcnt lgkmcnt(1)
	v_add_f32_e32 v47, v47, v1
	s_waitcnt lgkmcnt(0)
	v_add_f32_e32 v48, v48, v2
	ds_bpermute_b32 v66, v23, v33
	ds_bpermute_b32 v67, v23, v34
	ds_bpermute_b32 v68, v23, v35
	ds_bpermute_b32 v69, v23, v36
	ds_bpermute_b32 v70, v23, v37
	ds_bpermute_b32 v71, v23, v38
	ds_bpermute_b32 v72, v23, v39
	ds_bpermute_b32 v73, v23, v40
	ds_bpermute_b32 v74, v23, v41
	ds_bpermute_b32 v75, v23, v42
	ds_bpermute_b32 v76, v23, v43
	ds_bpermute_b32 v77, v23, v44
	ds_bpermute_b32 v78, v23, v45
	ds_bpermute_b32 v0, v23, v46
	ds_bpermute_b32 v1, v23, v47
	ds_bpermute_b32 v2, v23, v48
	s_waitcnt lgkmcnt(15)
	v_add_f32_e32 v33, v33, v66
	s_waitcnt lgkmcnt(14)
	v_add_f32_e32 v34, v34, v67
	s_waitcnt lgkmcnt(13)
	v_add_f32_e32 v35, v35, v68
	s_waitcnt lgkmcnt(12)
	v_add_f32_e32 v36, v36, v69
	s_waitcnt lgkmcnt(11)
	v_add_f32_e32 v37, v37, v70
	s_waitcnt lgkmcnt(10)
	v_add_f32_e32 v38, v38, v71
	s_waitcnt lgkmcnt(9)
	v_add_f32_e32 v39, v39, v72
	s_waitcnt lgkmcnt(8)
	v_add_f32_e32 v40, v40, v73
	s_waitcnt lgkmcnt(7)
	v_add_f32_e32 v41, v41, v74
	s_waitcnt lgkmcnt(6)
	v_add_f32_e32 v42, v42, v75
	s_waitcnt lgkmcnt(5)
	v_add_f32_e32 v43, v43, v76
	s_waitcnt lgkmcnt(4)
	v_add_f32_e32 v44, v44, v77
	s_waitcnt lgkmcnt(3)
	v_add_f32_e32 v45, v45, v78
	s_waitcnt lgkmcnt(2)
	v_add_f32_e32 v46, v46, v0
	s_waitcnt lgkmcnt(1)
	v_add_f32_e32 v47, v47, v1
	s_waitcnt lgkmcnt(0)
	v_add_f32_e32 v48, v48, v2
	ds_bpermute_b32 v66, v24, v33
	ds_bpermute_b32 v67, v24, v34
	ds_bpermute_b32 v68, v24, v35
	ds_bpermute_b32 v69, v24, v36
	ds_bpermute_b32 v70, v24, v37
	ds_bpermute_b32 v71, v24, v38
	ds_bpermute_b32 v72, v24, v39
	ds_bpermute_b32 v73, v24, v40
	ds_bpermute_b32 v74, v24, v41
	ds_bpermute_b32 v75, v24, v42
	ds_bpermute_b32 v76, v24, v43
	ds_bpermute_b32 v77, v24, v44
	ds_bpermute_b32 v78, v24, v45
	ds_bpermute_b32 v0, v24, v46
	ds_bpermute_b32 v1, v24, v47
	ds_bpermute_b32 v2, v24, v48
	s_waitcnt lgkmcnt(15)
	v_add_f32_e32 v33, v33, v66
	s_waitcnt lgkmcnt(14)
	v_add_f32_e32 v34, v34, v67
	s_waitcnt lgkmcnt(13)
	v_add_f32_e32 v35, v35, v68
	s_waitcnt lgkmcnt(12)
	v_add_f32_e32 v36, v36, v69
	s_waitcnt lgkmcnt(11)
	v_add_f32_e32 v37, v37, v70
	s_waitcnt lgkmcnt(10)
	v_add_f32_e32 v38, v38, v71
	s_waitcnt lgkmcnt(9)
	v_add_f32_e32 v39, v39, v72
	s_waitcnt lgkmcnt(8)
	v_add_f32_e32 v40, v40, v73
	s_waitcnt lgkmcnt(7)
	v_add_f32_e32 v41, v41, v74
	s_waitcnt lgkmcnt(6)
	v_add_f32_e32 v42, v42, v75
	s_waitcnt lgkmcnt(5)
	v_add_f32_e32 v43, v43, v76
	s_waitcnt lgkmcnt(4)
	v_add_f32_e32 v44, v44, v77
	s_waitcnt lgkmcnt(3)
	v_add_f32_e32 v45, v45, v78
	s_waitcnt lgkmcnt(2)
	v_add_f32_e32 v46, v46, v0
	s_waitcnt lgkmcnt(1)
	v_add_f32_e32 v47, v47, v1
	s_waitcnt lgkmcnt(0)
	v_add_f32_e32 v48, v48, v2
	ds_bpermute_b32 v66, v25, v33
	ds_bpermute_b32 v67, v25, v34
	ds_bpermute_b32 v68, v25, v35
	ds_bpermute_b32 v69, v25, v36
	ds_bpermute_b32 v70, v25, v37
	ds_bpermute_b32 v71, v25, v38
	ds_bpermute_b32 v72, v25, v39
	ds_bpermute_b32 v73, v25, v40
	ds_bpermute_b32 v74, v25, v41
	ds_bpermute_b32 v75, v25, v42
	ds_bpermute_b32 v76, v25, v43
	ds_bpermute_b32 v77, v25, v44
	ds_bpermute_b32 v78, v25, v45
	ds_bpermute_b32 v0, v25, v46
	ds_bpermute_b32 v1, v25, v47
	ds_bpermute_b32 v2, v25, v48
	s_waitcnt lgkmcnt(15)
	v_add_f32_e32 v33, v33, v66
	s_waitcnt lgkmcnt(14)
	v_add_f32_e32 v34, v34, v67
	s_waitcnt lgkmcnt(13)
	v_add_f32_e32 v35, v35, v68
	s_waitcnt lgkmcnt(12)
	v_add_f32_e32 v36, v36, v69
	s_waitcnt lgkmcnt(11)
	v_add_f32_e32 v37, v37, v70
	s_waitcnt lgkmcnt(10)
	v_add_f32_e32 v38, v38, v71
	s_waitcnt lgkmcnt(9)
	v_add_f32_e32 v39, v39, v72
	s_waitcnt lgkmcnt(8)
	v_add_f32_e32 v40, v40, v73
	s_waitcnt lgkmcnt(7)
	v_add_f32_e32 v41, v41, v74
	s_waitcnt lgkmcnt(6)
	v_add_f32_e32 v42, v42, v75
	s_waitcnt lgkmcnt(5)
	v_add_f32_e32 v43, v43, v76
	s_waitcnt lgkmcnt(4)
	v_add_f32_e32 v44, v44, v77
	s_waitcnt lgkmcnt(3)
; __device__ __forceinline__ float shfl_xor_f(float v, int mask) { const int l = lane_fresh(); return __int_as_float(__builtin_amdgcn_ds_bpermute((l ^ mask) << 2, __float_as_int(v))); }
; __device__ __forceinline__ void ssd_sample_item(const Params& p, int item, const int wv) {
;     ...
; #pragma unroll
;     for (int o = 16; o >= 1; o >>= 1) yp += shfl_xor_f(yp, o);
	v_add_f32_e32 v45, v45, v78
	s_waitcnt lgkmcnt(2)
	v_add_f32_e32 v46, v46, v0
	s_waitcnt lgkmcnt(1)
	v_add_f32_e32 v47, v47, v1
	s_waitcnt lgkmcnt(0)
	v_add_f32_e32 v48, v48, v2
	ds_bpermute_b32 v66, v26, v33
	ds_bpermute_b32 v67, v26, v34
	ds_bpermute_b32 v68, v26, v35
	ds_bpermute_b32 v69, v26, v36
	ds_bpermute_b32 v70, v26, v37
	ds_bpermute_b32 v71, v26, v38
	ds_bpermute_b32 v72, v26, v39
	ds_bpermute_b32 v73, v26, v40
	ds_bpermute_b32 v74, v26, v41
	ds_bpermute_b32 v75, v26, v42
	ds_bpermute_b32 v76, v26, v43
	ds_bpermute_b32 v77, v26, v44
	ds_bpermute_b32 v78, v26, v45
	ds_bpermute_b32 v0, v26, v46
	ds_bpermute_b32 v1, v26, v47
	ds_bpermute_b32 v2, v26, v48
	s_waitcnt lgkmcnt(15)
	v_add_f32_e32 v33, v33, v66
	s_waitcnt lgkmcnt(14)
	v_add_f32_e32 v34, v34, v67
	s_waitcnt lgkmcnt(13)
	v_add_f32_e32 v35, v35, v68
	s_waitcnt lgkmcnt(12)
	v_add_f32_e32 v36, v36, v69
	s_waitcnt lgkmcnt(11)
	v_add_f32_e32 v37, v37, v70
	s_waitcnt lgkmcnt(10)
	v_add_f32_e32 v38, v38, v71
	s_waitcnt lgkmcnt(9)
	v_add_f32_e32 v39, v39, v72
	s_waitcnt lgkmcnt(8)
	v_add_f32_e32 v40, v40, v73
	s_waitcnt lgkmcnt(7)
	v_add_f32_e32 v41, v41, v74
	s_waitcnt lgkmcnt(6)
	v_add_f32_e32 v42, v42, v75
	s_waitcnt lgkmcnt(5)
	v_add_f32_e32 v43, v43, v76
	s_waitcnt lgkmcnt(4)
	v_add_f32_e32 v44, v44, v77
	s_waitcnt lgkmcnt(3)
	v_add_f32_e32 v45, v45, v78
	s_waitcnt lgkmcnt(2)
	v_add_f32_e32 v46, v46, v0
	s_waitcnt lgkmcnt(1)
	v_add_f32_e32 v47, v47, v1
	s_waitcnt lgkmcnt(0)
	v_add_f32_e32 v48, v48, v2
	ds_bpermute_b32 v66, v22, v49
	ds_bpermute_b32 v67, v22, v50
	ds_bpermute_b32 v68, v22, v51
	ds_bpermute_b32 v69, v22, v52
	ds_bpermute_b32 v70, v22, v53
	ds_bpermute_b32 v71, v22, v54
	ds_bpermute_b32 v72, v22, v55
	ds_bpermute_b32 v73, v22, v56
	ds_bpermute_b32 v74, v22, v57
	ds_bpermute_b32 v75, v22, v58
	ds_bpermute_b32 v76, v22, v59
	ds_bpermute_b32 v77, v22, v60
	ds_bpermute_b32 v78, v22, v61
	ds_bpermute_b32 v0, v22, v62
	ds_bpermute_b32 v1, v22, v63
	ds_bpermute_b32 v2, v22, v64
	s_waitcnt lgkmcnt(15)
	v_add_f32_e32 v49, v49, v66
	s_waitcnt lgkmcnt(14)
	v_add_f32_e32 v50, v50, v67
	s_waitcnt lgkmcnt(13)
	v_add_f32_e32 v51, v51, v68
	s_waitcnt lgkmcnt(12)
	v_add_f32_e32 v52, v52, v69
	s_waitcnt lgkmcnt(11)
	v_add_f32_e32 v53, v53, v70
	s_waitcnt lgkmcnt(10)
	v_add_f32_e32 v54, v54, v71
	s_waitcnt lgkmcnt(9)
	v_add_f32_e32 v55, v55, v72
	s_waitcnt lgkmcnt(8)
	v_add_f32_e32 v56, v56, v73
	s_waitcnt lgkmcnt(7)
	v_add_f32_e32 v57, v57, v74
	s_waitcnt lgkmcnt(6)
	v_add_f32_e32 v58, v58, v75
	s_waitcnt lgkmcnt(5)
	v_add_f32_e32 v59, v59, v76
	s_waitcnt lgkmcnt(4)
	v_add_f32_e32 v60, v60, v77
	s_waitcnt lgkmcnt(3)
	v_add_f32_e32 v61, v61, v78
	s_waitcnt lgkmcnt(2)
	v_add_f32_e32 v62, v62, v0
	s_waitcnt lgkmcnt(1)
	v_add_f32_e32 v63, v63, v1
	s_waitcnt lgkmcnt(0)
	v_add_f32_e32 v64, v64, v2
	ds_bpermute_b32 v66, v23, v49
	ds_bpermute_b32 v67, v23, v50
	ds_bpermute_b32 v68, v23, v51
	ds_bpermute_b32 v69, v23, v52
	ds_bpermute_b32 v70, v23, v53
	ds_bpermute_b32 v71, v23, v54
	ds_bpermute_b32 v72, v23, v55
	ds_bpermute_b32 v73, v23, v56
	ds_bpermute_b32 v74, v23, v57
	ds_bpermute_b32 v75, v23, v58
	ds_bpermute_b32 v76, v23, v59
	ds_bpermute_b32 v77, v23, v60
	ds_bpermute_b32 v78, v23, v61
	ds_bpermute_b32 v0, v23, v62
	ds_bpermute_b32 v1, v23, v63
	ds_bpermute_b32 v2, v23, v64
	s_waitcnt lgkmcnt(15)
	v_add_f32_e32 v49, v49, v66
	s_waitcnt lgkmcnt(14)
	v_add_f32_e32 v50, v50, v67
	s_waitcnt lgkmcnt(13)
	v_add_f32_e32 v51, v51, v68
	s_waitcnt lgkmcnt(12)
	v_add_f32_e32 v52, v52, v69
	s_waitcnt lgkmcnt(11)
	v_add_f32_e32 v53, v53, v70
	s_waitcnt lgkmcnt(10)
	v_add_f32_e32 v54, v54, v71
	s_waitcnt lgkmcnt(9)
	v_add_f32_e32 v55, v55, v72
	s_waitcnt lgkmcnt(8)
	v_add_f32_e32 v56, v56, v73
	s_waitcnt lgkmcnt(7)
	v_add_f32_e32 v57, v57, v74
	s_waitcnt lgkmcnt(6)
	v_add_f32_e32 v58, v58, v75
	s_waitcnt lgkmcnt(5)
	v_add_f32_e32 v59, v59, v76
	s_waitcnt lgkmcnt(4)
	v_add_f32_e32 v60, v60, v77
	s_waitcnt lgkmcnt(3)
	v_add_f32_e32 v61, v61, v78
	s_waitcnt lgkmcnt(2)
	v_add_f32_e32 v62, v62, v0
	s_waitcnt lgkmcnt(1)
	v_add_f32_e32 v63, v63, v1
	s_waitcnt lgkmcnt(0)
	v_add_f32_e32 v64, v64, v2
	ds_bpermute_b32 v66, v24, v49
	ds_bpermute_b32 v67, v24, v50
	ds_bpermute_b32 v68, v24, v51
	ds_bpermute_b32 v69, v24, v52
	ds_bpermute_b32 v70, v24, v53
	ds_bpermute_b32 v71, v24, v54
	ds_bpermute_b32 v72, v24, v55
	ds_bpermute_b32 v73, v24, v56
	ds_bpermute_b32 v74, v24, v57
	ds_bpermute_b32 v75, v24, v58
	ds_bpermute_b32 v76, v24, v59
	ds_bpermute_b32 v77, v24, v60
	ds_bpermute_b32 v78, v24, v61
	ds_bpermute_b32 v0, v24, v62
	ds_bpermute_b32 v1, v24, v63
	ds_bpermute_b32 v2, v24, v64
	s_waitcnt lgkmcnt(15)
	v_add_f32_e32 v49, v49, v66
	s_waitcnt lgkmcnt(14)
	v_add_f32_e32 v50, v50, v67
	s_waitcnt lgkmcnt(13)
	v_add_f32_e32 v51, v51, v68
	s_waitcnt lgkmcnt(12)
	v_add_f32_e32 v52, v52, v69
	s_waitcnt lgkmcnt(11)
	v_add_f32_e32 v53, v53, v70
	s_waitcnt lgkmcnt(10)
	v_add_f32_e32 v54, v54, v71
	s_waitcnt lgkmcnt(9)
	v_add_f32_e32 v55, v55, v72
	s_waitcnt lgkmcnt(8)
	v_add_f32_e32 v56, v56, v73
	s_waitcnt lgkmcnt(7)
	v_add_f32_e32 v57, v57, v74
	s_waitcnt lgkmcnt(6)
	v_add_f32_e32 v58, v58, v75
	s_waitcnt lgkmcnt(5)
	v_add_f32_e32 v59, v59, v76
	s_waitcnt lgkmcnt(4)
	v_add_f32_e32 v60, v60, v77
	s_waitcnt lgkmcnt(3)
	v_add_f32_e32 v61, v61, v78
	s_waitcnt lgkmcnt(2)
	v_add_f32_e32 v62, v62, v0
	s_waitcnt lgkmcnt(1)
	v_add_f32_e32 v63, v63, v1
	s_waitcnt lgkmcnt(0)
; __device__ __forceinline__ float shfl_xor_f(float v, int mask) { const int l = lane_fresh(); return __int_as_float(__builtin_amdgcn_ds_bpermute((l ^ mask) << 2, __float_as_int(v))); }
; __device__ __forceinline__ void ssd_sample_item(const Params& p, int item, const int wv) {
;     ...
; #pragma unroll
;     for (int o = 16; o >= 1; o >>= 1) yp += shfl_xor_f(yp, o);
	v_add_f32_e32 v64, v64, v2
	ds_bpermute_b32 v66, v25, v49
	ds_bpermute_b32 v67, v25, v50
	ds_bpermute_b32 v68, v25, v51
	ds_bpermute_b32 v69, v25, v52
	ds_bpermute_b32 v70, v25, v53
	ds_bpermute_b32 v71, v25, v54
	ds_bpermute_b32 v72, v25, v55
	ds_bpermute_b32 v73, v25, v56
	ds_bpermute_b32 v74, v25, v57
	ds_bpermute_b32 v75, v25, v58
	ds_bpermute_b32 v76, v25, v59
	ds_bpermute_b32 v77, v25, v60
	ds_bpermute_b32 v78, v25, v61
	ds_bpermute_b32 v0, v25, v62
	ds_bpermute_b32 v1, v25, v63
	ds_bpermute_b32 v2, v25, v64
	s_waitcnt lgkmcnt(15)
	v_add_f32_e32 v49, v49, v66
	s_waitcnt lgkmcnt(14)
	v_add_f32_e32 v50, v50, v67
	s_waitcnt lgkmcnt(13)
	v_add_f32_e32 v51, v51, v68
	s_waitcnt lgkmcnt(12)
	v_add_f32_e32 v52, v52, v69
	s_waitcnt lgkmcnt(11)
	v_add_f32_e32 v53, v53, v70
	s_waitcnt lgkmcnt(10)
	v_add_f32_e32 v54, v54, v71
	s_waitcnt lgkmcnt(9)
	v_add_f32_e32 v55, v55, v72
	s_waitcnt lgkmcnt(8)
	v_add_f32_e32 v56, v56, v73
	s_waitcnt lgkmcnt(7)
	v_add_f32_e32 v57, v57, v74
	s_waitcnt lgkmcnt(6)
	v_add_f32_e32 v58, v58, v75
	s_waitcnt lgkmcnt(5)
	v_add_f32_e32 v59, v59, v76
	s_waitcnt lgkmcnt(4)
	v_add_f32_e32 v60, v60, v77
	s_waitcnt lgkmcnt(3)
	v_add_f32_e32 v61, v61, v78
	s_waitcnt lgkmcnt(2)
	v_add_f32_e32 v62, v62, v0
	s_waitcnt lgkmcnt(1)
	v_add_f32_e32 v63, v63, v1
	s_waitcnt lgkmcnt(0)
	v_add_f32_e32 v64, v64, v2
	ds_bpermute_b32 v66, v26, v49
	ds_bpermute_b32 v67, v26, v50
	ds_bpermute_b32 v68, v26, v51
	ds_bpermute_b32 v69, v26, v52
	ds_bpermute_b32 v70, v26, v53
	ds_bpermute_b32 v71, v26, v54
	ds_bpermute_b32 v72, v26, v55
	ds_bpermute_b32 v73, v26, v56
	ds_bpermute_b32 v74, v26, v57
	ds_bpermute_b32 v75, v26, v58
	ds_bpermute_b32 v76, v26, v59
	ds_bpermute_b32 v77, v26, v60
	ds_bpermute_b32 v78, v26, v61
	ds_bpermute_b32 v0, v26, v62
	ds_bpermute_b32 v1, v26, v63
	ds_bpermute_b32 v2, v26, v64
	s_waitcnt lgkmcnt(15)
	v_add_f32_e32 v49, v49, v66
	s_waitcnt lgkmcnt(14)
	v_add_f32_e32 v50, v50, v67
	s_waitcnt lgkmcnt(13)
	v_add_f32_e32 v51, v51, v68
	s_waitcnt lgkmcnt(12)
	v_add_f32_e32 v52, v52, v69
	s_waitcnt lgkmcnt(11)
	v_add_f32_e32 v53, v53, v70
	s_waitcnt lgkmcnt(10)
	v_add_f32_e32 v54, v54, v71
	s_waitcnt lgkmcnt(9)
	v_add_f32_e32 v55, v55, v72
	s_waitcnt lgkmcnt(8)
	v_add_f32_e32 v56, v56, v73
	s_waitcnt lgkmcnt(7)
	v_add_f32_e32 v57, v57, v74
	s_waitcnt lgkmcnt(6)
	v_add_f32_e32 v58, v58, v75
	s_waitcnt lgkmcnt(5)
	v_add_f32_e32 v59, v59, v76
	s_waitcnt lgkmcnt(4)
	v_add_f32_e32 v60, v60, v77
	s_waitcnt lgkmcnt(3)
	v_add_f32_e32 v61, v61, v78
	s_waitcnt lgkmcnt(2)
	v_add_f32_e32 v62, v62, v0
	s_waitcnt lgkmcnt(1)
	v_add_f32_e32 v63, v63, v1
	s_waitcnt lgkmcnt(0)
; __device__ __forceinline__ u16 f2bf(float f) { return (u16)(cvt_pk(f, 0.f) & 0xffffu); }
; __device__ __forceinline__ float bf2f(u16 h) { return __uint_as_float(((unsigned)h) << 16); }
; __device__ __forceinline__ float shfl_idx_f(float v, int src) { return __int_as_float(__builtin_amdgcn_ds_bpermute(src << 2, __float_as_int(v))); }
; __device__ __forceinline__ void ssd_sample_item(const Params& p, int item, const int wv) {
;     ...
;     if ((lane & 31) == r) ymine = yp;
;   }
;   const int pm = 2 * (lane & 31) + hf;
;   const float xm = shfl_idx_f(x, pm);
;   const float zs = bf2f(ZS[(size_t)tok * 1024 + h * 64 + pm]);
;   const float yg = (ymine + xm * p.in[17][h]) * zs;
;   float ss = wave_sum(yg * yg);
;   Y[(size_t)tok * 1024 + h * 64 + pm] = f2bf(yg);
;   if (lane == 0) { YPS[(size_t)tok * 32 + g * 16 + (h & 7) * 2] = ss; YPS[(size_t)tok * 32 + g * 16 + (h & 7) * 2 + 1] = 0.f; }
	v_add_f32_e32 v64, v64, v2
	v_cmp_eq_u32_e64 s[36:37], 0, v29
	v_cmp_eq_u32_e64 s[38:39], 1, v29
	v_cmp_eq_u32_e64 s[40:41], 2, v29
	v_cndmask_b32_e64 v17, v17, v33, s[36:37]
	v_cmp_eq_u32_e64 s[36:37], 3, v29
	v_cndmask_b32_e64 v17, v17, v34, s[38:39]
	v_cmp_eq_u32_e64 s[38:39], 4, v29
	v_cndmask_b32_e64 v17, v17, v35, s[40:41]
	v_cmp_eq_u32_e64 s[40:41], 5, v29
	v_cndmask_b32_e64 v17, v17, v36, s[36:37]
	v_cmp_eq_u32_e64 s[36:37], 6, v29
	v_cndmask_b32_e64 v17, v17, v37, s[38:39]
	v_cmp_eq_u32_e64 s[38:39], 7, v29
	v_cndmask_b32_e64 v17, v17, v38, s[40:41]
	v_cmp_eq_u32_e64 s[40:41], 8, v29
	v_cndmask_b32_e64 v17, v17, v39, s[36:37]
	v_cmp_eq_u32_e64 s[36:37], 9, v29
	v_cndmask_b32_e64 v17, v17, v40, s[38:39]
	v_cmp_eq_u32_e64 s[38:39], 10, v29
	v_cndmask_b32_e64 v17, v17, v41, s[40:41]
	v_cmp_eq_u32_e64 s[40:41], 11, v29
	v_cndmask_b32_e64 v17, v17, v42, s[36:37]
	v_cmp_eq_u32_e64 s[36:37], 12, v29
	v_cndmask_b32_e64 v17, v17, v43, s[38:39]
	v_cmp_eq_u32_e64 s[38:39], 13, v29
	v_cndmask_b32_e64 v17, v17, v44, s[40:41]
	v_cmp_eq_u32_e64 s[40:41], 14, v29
	v_cndmask_b32_e64 v17, v17, v45, s[36:37]
	v_cmp_eq_u32_e64 s[36:37], 15, v29
	v_cndmask_b32_e64 v17, v17, v46, s[38:39]
	v_cmp_eq_u32_e64 s[38:39], 16, v29
	v_cndmask_b32_e64 v17, v17, v47, s[40:41]
	v_cmp_eq_u32_e64 s[40:41], 17, v29
	v_cndmask_b32_e64 v17, v17, v48, s[36:37]
	v_cmp_eq_u32_e64 s[36:37], 18, v29
	v_cndmask_b32_e64 v17, v17, v49, s[38:39]
	v_cmp_eq_u32_e64 s[38:39], 19, v29
	v_cndmask_b32_e64 v17, v17, v50, s[40:41]
	v_cmp_eq_u32_e64 s[40:41], 20, v29
	v_cndmask_b32_e64 v17, v17, v51, s[36:37]
	v_cmp_eq_u32_e64 s[36:37], 21, v29
	v_cndmask_b32_e64 v17, v17, v52, s[38:39]
	v_cmp_eq_u32_e64 s[38:39], 22, v29
	v_cndmask_b32_e64 v17, v17, v53, s[40:41]
	v_cmp_eq_u32_e64 s[40:41], 23, v29
	v_cndmask_b32_e64 v17, v17, v54, s[36:37]
	v_cmp_eq_u32_e64 s[36:37], 24, v29
	v_cndmask_b32_e64 v17, v17, v55, s[38:39]
	v_cmp_eq_u32_e64 s[38:39], 25, v29
	v_cndmask_b32_e64 v17, v17, v56, s[40:41]
	v_cmp_eq_u32_e64 s[40:41], 26, v29
	v_cndmask_b32_e64 v17, v17, v57, s[36:37]
	v_cmp_eq_u32_e64 s[36:37], 27, v29
	v_cndmask_b32_e64 v17, v17, v58, s[38:39]
	v_cmp_eq_u32_e64 s[38:39], 28, v29
	v_cndmask_b32_e64 v17, v17, v59, s[40:41]
	v_cmp_eq_u32_e64 s[40:41], 29, v29
	v_cndmask_b32_e64 v17, v17, v60, s[36:37]
	v_cmp_eq_u32_e64 s[36:37], 30, v29
	v_cndmask_b32_e64 v17, v17, v61, s[38:39]
	v_cmp_eq_u32_e64 s[38:39], 31, v29
	v_cndmask_b32_e64 v17, v17, v62, s[40:41]
	s_nop 1
	v_cndmask_b32_e64 v17, v17, v63, s[36:37]
	v_cndmask_b32_e64 v17, v17, v64, s[38:39]
	v_add_u32_e32 v32, 0x100, v32
	s_mov_b32 s10, 32
	s_mov_b64 s[12:13], 0x8000
	s_lshl_b32 s10, s31, 11
	s_add_u32 s0, s17, s10
	v_lshl_add_u32 v0, v29, 1, v16
	s_addc_u32 s1, s18, 0
	s_lshl_b32 s12, s34, 1
	v_ashrrev_i32_e32 v1, 31, v0
	s_add_u32 s0, s0, s12
	s_addc_u32 s1, s1, 0
	v_lshlrev_b64 v[2:3], 1, v[0:1]
	v_lshl_add_u64 v[6:7], s[0:1], 0, v[2:3]
	s_lshl_b32 s0, s33, 2
	v_readlane_b32 s60, v251, 22
	v_mov_b32_e32 v4, s0
	v_readlane_b32 s62, v251, 24
	v_readlane_b32 s63, v251, 25
	global_load_ushort v1, v[6:7], off
	v_lshlrev_b32_e32 v0, 2, v0
	ds_bpermute_b32 v0, v0, v31
	s_add_u32 s0, s48, s10
	s_addc_u32 s1, s49, 0
	global_load_dword v4, v4, s[62:63]
	v_mbcnt_lo_u32_b32 v6, -1, 0
	v_mbcnt_hi_u32_b32 v6, -1, v6
	v_cmp_eq_u32_e32 vcc, 0, v28
	v_lshlrev_b32_e32 v6, 2, v6
	v_xor_b32_e32 v6, 0x80, v6
	v_readlane_b32 s61, v251, 23
	v_readlane_b32 s64, v251, 26
	v_readlane_b32 s65, v251, 27
	v_readlane_b32 s66, v251, 28
	v_readlane_b32 s67, v251, 29
	v_readlane_b32 s68, v251, 30
	v_readlane_b32 s69, v251, 31
	v_readlane_b32 s70, v251, 32
	v_readlane_b32 s71, v251, 33
	v_readlane_b32 s72, v251, 34
	v_readlane_b32 s73, v251, 35
	v_readlane_b32 s74, v251, 36
	v_readlane_b32 s75, v251, 37
	s_waitcnt vmcnt(1)
	v_lshlrev_b32_e32 v1, 16, v1
	s_waitcnt vmcnt(0) lgkmcnt(0)
	v_fmac_f32_e32 v17, v4, v0
	v_mul_f32_e32 v0, v17, v1
	v_mul_f32_e32 v1, v0, v0
	ds_bpermute_b32 v1, v6, v1
	v_mbcnt_lo_u32_b32 v4, -1, 0
	v_mbcnt_hi_u32_b32 v4, -1, v4
	v_mbcnt_lo_u32_b32 v6, -1, 0
	v_mbcnt_hi_u32_b32 v6, -1, v6
	s_waitcnt lgkmcnt(0)
	v_fmac_f32_e32 v1, v0, v0
	v_lshlrev_b32_e32 v4, 2, v4
	v_xor_b32_e32 v4, 64, v4
	ds_bpermute_b32 v4, v4, v1
	v_lshlrev_b32_e32 v6, 2, v6
	v_xor_b32_e32 v6, 32, v6
	s_waitcnt lgkmcnt(0)
	v_add_f32_e32 v1, v1, v4
	s_nop 1
	v_mov_b32_dpp v4, v1 row_ror:8 row_mask:0xf bank_mask:0xf
	v_mbcnt_lo_u32_b32 v6, -1, 0
	v_mbcnt_hi_u32_b32 v6, -1, v6
	v_add_f32_e32 v1, v1, v4
	v_lshlrev_b32_e32 v6, 2, v6
	v_xor_b32_e32 v6, 16, v6
	s_nop 1
	v_mov_b32_dpp v4, v1 row_shl:4 row_mask:0xf bank_mask:0x5
	v_mov_b32_dpp v4, v1 row_shr:4 row_mask:0xf bank_mask:0xa
	v_mbcnt_lo_u32_b32 v6, -1, 0
	v_mbcnt_hi_u32_b32 v6, -1, v6
	v_mbcnt_lo_u32_b32 v7, -1, 0
	v_mbcnt_hi_u32_b32 v7, -1, v7
	v_add_f32_e32 v1, v1, v4
	v_lshlrev_b32_e32 v6, 2, v6
	v_xor_b32_e32 v6, 8, v6
	s_nop 1
	v_mov_b32_dpp v4, v1 quad_perm:[2,3,0,1] row_mask:0xf bank_mask:0xf
	v_lshlrev_b32_e32 v6, 2, v7
	v_xor_b32_e32 v6, 4, v6
	v_cvt_pk_bf16_f32 v7, v0, s0
	s_add_u32 s0, s0, s12
	v_add_f32_e32 v0, v1, v4
	s_nop 1
	v_mov_b32_dpp v1, v0 quad_perm:[1,0,3,2] row_mask:0xf bank_mask:0xf
	s_addc_u32 s1, s1, 0
	v_lshl_add_u64 v[2:3], s[0:1], 0, v[2:3]
	global_store_short v[2:3], v7, off
	s_and_saveexec_b64 s[0:1], vcc
	s_cbranch_execz .LBB0_455
	s_lshl_b32 s10, s31, 7
	s_add_u32 s10, s19, s10
	s_addc_u32 s13, s20, 0
	s_lshl_b32 s12, s30, 6
	s_add_u32 s12, s10, s12
	s_addc_u32 s13, s13, 0
	s_lshl_b32 s10, s29, 3
	s_and_b32 s10, s10, 56
	s_waitcnt lgkmcnt(0)
	v_add_f32_e32 v4, v0, v1
	v_mov_b32_e32 v0, s10
	global_store_dwordx2 v0, v[4:5], s[12:13]
	s_branch .LBB0_455

; __device__ __forceinline__ float bflo(unsigned w) { return __uint_as_float(w << 16); }
; __device__ __forceinline__ float bfhi(unsigned w) { return __uint_as_float(w & 0xffff0000u); }
; __device__ __forceinline__ void attn_sample_item(const Params& p, int item, const int wv) {
;     ...
;   const int vdch = tid & 31, vmg = tid >> 5;
;   f32x4 vreg[16];
; #pragma unroll
;   for (int i = 0; i < 16; ++i) vreg[i] = *(const f32x4*)(Vc + (size_t)(vmg * 16 + i) * 512 + vdch * 4);
;   __syncthreads();
;   {
;     const int dch = lane & 15, ksub = lane >> 4;
;     u32x4 qw = *(const u32x4*)(Q + (size_t)tok * 512 + h * 128 + dch * 8);
;     float q[8] = {bflo(qw.x), bfhi(qw.x), bflo(qw.y), bfhi(qw.y), bflo(qw.z), bfhi(qw.z), bflo(qw.w), bfhi(qw.w)};
; #pragma unroll
;     for (int it = 0; it < 8; ++it) {
;       const int mm = wid * 32 + it * 4 + ksub;
;       f32x4 k0 = *(const f32x4*)(Kc + (size_t)mm * 512 + dch * 8), k1 = *(const f32x4*)(Kc + (size_t)mm * 512 + dch * 8 + 4);
.LBB0_464:
	s_ashr_i32 s0, s19, 2
	s_ashr_i32 s1, s0, 31
	s_and_b32 s22, s15, 0x180
	v_readlane_b32 s64, v251, 6
	s_lshl_b64 s[10:11], s[0:1], 19
	s_lshl_b32 s1, s22, 2
	v_readlane_b32 s72, v251, 14
	v_readlane_b32 s73, v251, 15
	s_or_b32 s1, s10, s1
	s_mov_b64 s[44:45], s[72:73]
	v_readlane_b32 s70, v251, 12
	v_readlane_b32 s71, v251, 13
	s_add_u32 s20, s44, s1
	v_mbcnt_lo_u32_b32 v72, -1, 0
	v_mbcnt_hi_u32_b32 v72, -1, v72
	s_mov_b64 s[42:43], s[70:71]
	v_add_u32_e32 v66, s82, v72
	s_addc_u32 s21, s45, s11
	s_addk_i32 s0, 0x4000
	v_and_b32_e32 v0, 31, v72
	v_ashrrev_i32_e32 v67, 5, v66
	s_add_u32 s10, s42, s1
	v_lshlrev_b32_e32 v56, 4, v67
	v_lshlrev_b32_e32 v64, 4, v0
	s_addc_u32 s11, s43, s11
	s_ashr_i32 s1, s0, 31
	v_lshl_add_u64 v[58:59], s[20:21], 0, v[64:65]
	v_ashrrev_i32_e32 v57, 31, v56
	s_lshl_b64 s[20:21], s[0:1], 10
	s_waitcnt lgkmcnt(0)
	v_lshlrev_b64 v[0:1], 11, v[56:57]
	v_or_b32_e32 v2, 1, v56
	v_or_b32_e32 v8, 2, v56
	v_or_b32_e32 v10, 3, v56
	v_or_b32_e32 v16, 4, v56
	v_or_b32_e32 v18, 5, v56
	v_or_b32_e32 v24, 6, v56
	v_or_b32_e32 v26, 7, v56
	v_or_b32_e32 v32, 8, v56
	v_or_b32_e32 v34, 9, v56
	v_or_b32_e32 v40, 10, v56
	v_or_b32_e32 v42, 11, v56
	v_or_b32_e32 v48, 12, v56
	v_or_b32_e32 v50, 13, v56
	v_or_b32_e32 v60, 14, v56
	v_or_b32_e32 v56, 15, v56
	s_add_u32 s23, s7, s20
	v_ashrrev_i32_e32 v3, 31, v2
	v_ashrrev_i32_e32 v9, 31, v8
	v_ashrrev_i32_e32 v11, 31, v10
	v_ashrrev_i32_e32 v17, 31, v16
	v_ashrrev_i32_e32 v19, 31, v18
	v_ashrrev_i32_e32 v25, 31, v24
	v_ashrrev_i32_e32 v27, 31, v26
	v_ashrrev_i32_e32 v33, 31, v32
	v_ashrrev_i32_e32 v35, 31, v34
	v_ashrrev_i32_e32 v41, 31, v40
	v_ashrrev_i32_e32 v43, 31, v42
	v_ashrrev_i32_e32 v49, 31, v48
	v_ashrrev_i32_e32 v51, 31, v50
	v_ashrrev_i32_e32 v61, 31, v60
	v_ashrrev_i32_e32 v57, 31, v56
	s_addc_u32 s21, s12, s21
	s_lshl_b32 s20, s22, 1
	v_lshlrev_b64 v[2:3], 11, v[2:3]
	v_lshlrev_b64 v[8:9], 11, v[8:9]
	v_lshlrev_b64 v[10:11], 11, v[10:11]
	v_lshlrev_b64 v[16:17], 11, v[16:17]
	v_lshlrev_b64 v[18:19], 11, v[18:19]
	v_lshlrev_b64 v[24:25], 11, v[24:25]
	v_lshlrev_b64 v[26:27], 11, v[26:27]
	v_lshlrev_b64 v[32:33], 11, v[32:33]
	v_lshlrev_b64 v[34:35], 11, v[34:35]
	v_lshlrev_b64 v[40:41], 11, v[40:41]
	v_lshlrev_b64 v[42:43], 11, v[42:43]
	v_lshlrev_b64 v[48:49], 11, v[48:49]
	v_lshlrev_b64 v[50:51], 11, v[50:51]
	v_lshlrev_b64 v[60:61], 11, v[60:61]
	v_lshlrev_b64 v[56:57], 11, v[56:57]
	v_and_b32_e32 v92, 15, v72
	v_ashrrev_i32_e32 v68, 4, v72
	s_add_u32 s22, s23, s20
	v_lshl_add_u64 v[0:1], v[58:59], 0, v[0:1]
	v_lshl_add_u64 v[2:3], v[58:59], 0, v[2:3]
	v_lshl_add_u64 v[8:9], v[58:59], 0, v[8:9]
	v_lshl_add_u64 v[10:11], v[58:59], 0, v[10:11]
	v_lshl_add_u64 v[16:17], v[58:59], 0, v[16:17]
	v_lshl_add_u64 v[18:19], v[58:59], 0, v[18:19]
	v_lshl_add_u64 v[24:25], v[58:59], 0, v[24:25]
	v_lshl_add_u64 v[26:27], v[58:59], 0, v[26:27]
	v_lshl_add_u64 v[32:33], v[58:59], 0, v[32:33]
	v_lshl_add_u64 v[34:35], v[58:59], 0, v[34:35]
	v_lshl_add_u64 v[40:41], v[58:59], 0, v[40:41]
	v_lshl_add_u64 v[42:43], v[58:59], 0, v[42:43]
	v_lshl_add_u64 v[48:49], v[58:59], 0, v[48:49]
	v_lshl_add_u64 v[50:51], v[58:59], 0, v[50:51]
	v_lshl_add_u64 v[60:61], v[58:59], 0, v[60:61]
	v_lshl_add_u64 v[56:57], v[58:59], 0, v[56:57]
	s_addc_u32 s23, s21, 0
	v_lshlrev_b32_e32 v69, 4, v92
	v_add_u32_e32 v70, s5, v68
	global_load_dwordx4 v[4:7], v[0:1], off
	s_nop 0
	global_load_dwordx4 v[0:3], v[2:3], off
	s_nop 0
	global_load_dwordx4 v[12:15], v[8:9], off
	s_nop 0
	global_load_dwordx4 v[8:11], v[10:11], off
	s_nop 0
	global_load_dwordx4 v[20:23], v[16:17], off
	s_nop 0
	global_load_dwordx4 v[16:19], v[18:19], off
	s_nop 0
	global_load_dwordx4 v[28:31], v[24:25], off
	s_nop 0
	global_load_dwordx4 v[24:27], v[26:27], off
	s_nop 0
	global_load_dwordx4 v[36:39], v[32:33], off
	s_nop 0
	global_load_dwordx4 v[32:35], v[34:35], off
	s_nop 0
	global_load_dwordx4 v[44:47], v[40:41], off
	s_nop 0
	global_load_dwordx4 v[40:43], v[42:43], off
	s_nop 0
	global_load_dwordx4 v[52:55], v[48:49], off
	s_nop 0
	global_load_dwordx4 v[48:51], v[50:51], off
	s_nop 0
	global_load_dwordx4 v[60:63], v[60:61], off
	s_nop 0
	global_load_dwordx4 v[56:59], v[56:57], off
	s_barrier
	global_load_dwordx4 v[80:83], v69, s[22:23]
	v_lshlrev_b32_e32 v68, 5, v92
	v_mov_b32_e32 v69, v65
	v_ashrrev_i32_e32 v71, 31, v70
	v_lshl_add_u64 v[68:69], s[10:11], 0, v[68:69]
	v_lshlrev_b64 v[74:75], 11, v[70:71]
	v_lshl_add_u64 v[74:75], v[68:69], 0, v[74:75]
	global_load_dwordx4 v[84:87], v[74:75], off
	global_load_dwordx4 v[88:91], v[74:75], off offset:16
	v_mov_b32_e32 v221, 0
	v_mov_b32_e32 v220, 0x2000
	v_lshl_add_u64 v[222:223], v[220:221], 0, v[74:75]
	global_load_dwordx4 v[164:167], v[222:223], off
	global_load_dwordx4 v[168:171], v[222:223], off offset:16
	v_mov_b32_e32 v220, 0x4000
	v_lshl_add_u64 v[222:223], v[220:221], 0, v[74:75]
	global_load_dwordx4 v[172:175], v[222:223], off
	global_load_dwordx4 v[176:179], v[222:223], off offset:16
	v_mov_b32_e32 v220, 0x6000
	v_lshl_add_u64 v[222:223], v[220:221], 0, v[74:75]
	global_load_dwordx4 v[180:183], v[222:223], off
	global_load_dwordx4 v[184:187], v[222:223], off offset:16
	v_mov_b32_e32 v220, 0x8000
	v_lshl_add_u64 v[222:223], v[220:221], 0, v[74:75]
	global_load_dwordx4 v[188:191], v[222:223], off
	global_load_dwordx4 v[192:195], v[222:223], off offset:16
	v_mov_b32_e32 v220, 0xa000
	v_lshl_add_u64 v[222:223], v[220:221], 0, v[74:75]
	global_load_dwordx4 v[196:199], v[222:223], off
	global_load_dwordx4 v[200:203], v[222:223], off offset:16
	v_mov_b32_e32 v220, 0xc000
	v_lshl_add_u64 v[222:223], v[220:221], 0, v[74:75]
	global_load_dwordx4 v[204:207], v[222:223], off
	global_load_dwordx4 v[208:211], v[222:223], off offset:16
	v_mov_b32_e32 v220, 0xe000
	v_lshl_add_u64 v[222:223], v[220:221], 0, v[74:75]
	global_load_dwordx4 v[212:215], v[222:223], off
	global_load_dwordx4 v[216:219], v[222:223], off offset:16
	v_cmp_eq_u32_e32 vcc, 0, v92
	v_readlane_b32 s65, v251, 7
	v_readlane_b32 s66, v251, 8
	v_readlane_b32 s67, v251, 9
	v_readlane_b32 s68, v251, 10
	v_readlane_b32 s69, v251, 11
	v_readlane_b32 s74, v251, 16
	v_readlane_b32 s75, v251, 17
	v_readlane_b32 s76, v251, 18
	v_readlane_b32 s77, v251, 19
	v_readlane_b32 s78, v251, 20
	v_readlane_b32 s79, v251, 21
	s_waitcnt vmcnt(16)
; __device__ __forceinline__ float shfl_xor_f(float v, int mask) { const int l = lane_fresh(); return __int_as_float(__builtin_amdgcn_ds_bpermute((l ^ mask) << 2, __float_as_int(v))); }
; __device__ __forceinline__ void attn_sample_item(const Params& p, int item, const int wv) {
;     ...
;     for (int it = 0; it < 8; ++it) {
;       const int mm = wid * 32 + it * 4 + ksub;
;       f32x4 k0 = *(const f32x4*)(Kc + (size_t)mm * 512 + dch * 8), k1 = *(const f32x4*)(Kc + (size_t)mm * 512 + dch * 8 + 4);
;       float d = q[0] * k0[0] + q[1] * k0[1] + q[2] * k0[2] + q[3] * k0[3] + q[4] * k1[0] + q[5] * k1[1] + q[6] * k1[2] + q[7] * k1[3];
;       d += shfl_xor_f(d, 1); d += shfl_xor_f(d, 2); d += shfl_xor_f(d, 4); d += shfl_xor_f(d, 8);
;       if (dch == 0) sc_l[mm] = d * 0.08838834764831845f;
;     }
	v_and_b32_e32 v79, 0xffff0000, v80
	v_lshlrev_b32_e32 v71, 16, v80
	v_lshlrev_b32_e32 v73, 16, v81
	v_and_b32_e32 v74, 0xffff0000, v81
	v_lshlrev_b32_e32 v75, 16, v82
	v_and_b32_e32 v76, 0xffff0000, v82
	s_waitcnt vmcnt(15)
	v_mul_f32_e32 v80, v85, v79
	v_fmac_f32_e32 v80, v84, v71
	v_fmac_f32_e32 v80, v86, v73
	v_fmac_f32_e32 v80, v87, v74
	s_waitcnt vmcnt(14)
	v_fmac_f32_e32 v80, v88, v75
	v_lshlrev_b32_e32 v77, 16, v83
	v_fmac_f32_e32 v80, v89, v76
	v_mbcnt_lo_u32_b32 v81, -1, 0
	v_mbcnt_hi_u32_b32 v81, -1, v81
	v_and_b32_e32 v78, 0xffff0000, v83
	v_fmac_f32_e32 v80, v90, v77
	v_lshlrev_b32_e32 v81, 2, v81
	v_fmac_f32_e32 v80, v91, v78
	v_xor_b32_e32 v81, 4, v81
	s_nop 1
	v_mov_b32_dpp v81, v80 quad_perm:[1,0,3,2] row_mask:0xf bank_mask:0xf
	v_add_f32_e32 v80, v80, v81
	v_mbcnt_lo_u32_b32 v81, -1, 0
	v_mbcnt_hi_u32_b32 v81, -1, v81
	s_nop 0
	v_lshlrev_b32_e32 v81, 2, v81
	v_xor_b32_e32 v81, 8, v81
	s_nop 1
	v_mov_b32_dpp v81, v80 quad_perm:[2,3,0,1] row_mask:0xf bank_mask:0xf
	v_add_f32_e32 v80, v80, v81
	v_mbcnt_lo_u32_b32 v81, -1, 0
	v_mbcnt_hi_u32_b32 v81, -1, v81
	s_nop 0
	v_lshlrev_b32_e32 v81, 2, v81
	v_xor_b32_e32 v81, 16, v81
	s_nop 1
	v_mov_b32_dpp v81, v80 row_shl:4 row_mask:0xf bank_mask:0x5
	v_mov_b32_dpp v81, v80 row_shr:4 row_mask:0xf bank_mask:0xa
	v_add_f32_e32 v81, v80, v81
	v_mbcnt_lo_u32_b32 v80, -1, 0
	v_mbcnt_hi_u32_b32 v80, -1, v80
	s_nop 0
	v_lshlrev_b32_e32 v80, 2, v80
	v_xor_b32_e32 v80, 32, v80
	s_nop 1
	v_mov_b32_dpp v82, v81 row_ror:8 row_mask:0xf bank_mask:0xf
	v_lshl_add_u32 v80, v70, 2, 16
	s_and_saveexec_b64 s[10:11], vcc
	s_cbranch_execz .LBB0_466
	s_waitcnt lgkmcnt(0)
	v_add_f32_e32 v81, v81, v82
	v_mul_f32_e32 v81, 0x3db504f3, v81
	ds_write_b32 v80, v81
.LBB0_466:
	s_or_b64 exec, exec, s[10:11]
	s_waitcnt lgkmcnt(0)
	v_add_u32_e32 v82, 4, v70
	v_ashrrev_i32_e32 v83, 31, v82
	v_lshlrev_b64 v[82:83], 11, v[82:83]
	v_lshl_add_u64 v[86:87], v[68:69], 0, v[82:83]
	s_nop 0
	v_mbcnt_lo_u32_b32 v81, -1, 0
	v_mbcnt_hi_u32_b32 v81, -1, v81
	s_waitcnt vmcnt(12)
	v_mul_f32_e32 v83, v165, v79
	v_fmac_f32_e32 v83, v164, v71
	v_fmac_f32_e32 v83, v166, v73
	v_fmac_f32_e32 v83, v167, v74
	v_fmac_f32_e32 v83, v168, v75
	v_fmac_f32_e32 v83, v169, v76
	v_lshlrev_b32_e32 v81, 2, v81
	v_fmac_f32_e32 v83, v170, v77
	v_xor_b32_e32 v81, 4, v81
	v_fmac_f32_e32 v83, v171, v78
	s_nop 1
	v_mov_b32_dpp v81, v83 quad_perm:[1,0,3,2] row_mask:0xf bank_mask:0xf
	v_mbcnt_lo_u32_b32 v82, -1, 0
	v_mbcnt_hi_u32_b32 v82, -1, v82
	v_add_f32_e32 v81, v83, v81
	v_lshlrev_b32_e32 v82, 2, v82
	v_xor_b32_e32 v82, 8, v82
	s_nop 1
	v_mov_b32_dpp v82, v81 quad_perm:[2,3,0,1] row_mask:0xf bank_mask:0xf
	v_mbcnt_lo_u32_b32 v83, -1, 0
	v_mbcnt_hi_u32_b32 v83, -1, v83
	v_add_f32_e32 v81, v81, v82
	v_lshlrev_b32_e32 v83, 2, v83
	v_xor_b32_e32 v83, 16, v83
	s_nop 1
	v_mov_b32_dpp v82, v81 row_shl:4 row_mask:0xf bank_mask:0x5
	v_mov_b32_dpp v82, v81 row_shr:4 row_mask:0xf bank_mask:0xa
	v_mbcnt_lo_u32_b32 v83, -1, 0
	v_mbcnt_hi_u32_b32 v83, -1, v83
	v_add_f32_e32 v81, v81, v82
	v_lshlrev_b32_e32 v83, 2, v83
	v_xor_b32_e32 v82, 32, v83
	s_nop 1
	v_mov_b32_dpp v82, v81 row_ror:8 row_mask:0xf bank_mask:0xf
	s_and_saveexec_b64 s[10:11], vcc
	s_cbranch_execz .LBB0_468
	s_waitcnt lgkmcnt(0)
	v_add_f32_e32 v81, v81, v82
	v_mul_f32_e32 v81, 0x3db504f3, v81
	ds_write_b32 v80, v81 offset:16
.LBB0_468:
	s_or_b64 exec, exec, s[10:11]
	s_waitcnt lgkmcnt(0)
	v_add_u32_e32 v82, 8, v70
	v_ashrrev_i32_e32 v83, 31, v82
	v_lshlrev_b64 v[82:83], 11, v[82:83]
	v_lshl_add_u64 v[86:87], v[68:69], 0, v[82:83]
	s_nop 0
	v_mbcnt_lo_u32_b32 v81, -1, 0
	v_mbcnt_hi_u32_b32 v81, -1, v81
	s_waitcnt vmcnt(10)
	v_mul_f32_e32 v83, v173, v79
	v_fmac_f32_e32 v83, v172, v71
	v_fmac_f32_e32 v83, v174, v73
	v_fmac_f32_e32 v83, v175, v74
	v_fmac_f32_e32 v83, v176, v75
	v_fmac_f32_e32 v83, v177, v76
	v_lshlrev_b32_e32 v81, 2, v81
	v_fmac_f32_e32 v83, v178, v77
	v_xor_b32_e32 v81, 4, v81
	v_fmac_f32_e32 v83, v179, v78
	s_nop 1
	v_mov_b32_dpp v81, v83 quad_perm:[1,0,3,2] row_mask:0xf bank_mask:0xf
	v_mbcnt_lo_u32_b32 v82, -1, 0
	v_mbcnt_hi_u32_b32 v82, -1, v82
	v_add_f32_e32 v81, v83, v81
	v_lshlrev_b32_e32 v82, 2, v82
	v_xor_b32_e32 v82, 8, v82
	s_nop 1
	v_mov_b32_dpp v82, v81 quad_perm:[2,3,0,1] row_mask:0xf bank_mask:0xf
	v_mbcnt_lo_u32_b32 v83, -1, 0
	v_mbcnt_hi_u32_b32 v83, -1, v83
	v_add_f32_e32 v81, v81, v82
	v_lshlrev_b32_e32 v83, 2, v83
	v_xor_b32_e32 v83, 16, v83
	s_nop 1
	v_mov_b32_dpp v82, v81 row_shl:4 row_mask:0xf bank_mask:0x5
	v_mov_b32_dpp v82, v81 row_shr:4 row_mask:0xf bank_mask:0xa
	v_mbcnt_lo_u32_b32 v83, -1, 0
	v_mbcnt_hi_u32_b32 v83, -1, v83
	v_add_f32_e32 v81, v81, v82
	v_lshlrev_b32_e32 v83, 2, v83
	v_xor_b32_e32 v82, 32, v83
	s_nop 1
	v_mov_b32_dpp v82, v81 row_ror:8 row_mask:0xf bank_mask:0xf
	s_and_saveexec_b64 s[10:11], vcc
	s_cbranch_execz .LBB0_470
	s_waitcnt lgkmcnt(0)
	v_add_f32_e32 v81, v81, v82
	v_mul_f32_e32 v81, 0x3db504f3, v81
	ds_write_b32 v80, v81 offset:32
; __device__ __forceinline__ float shfl_xor_f(float v, int mask) { const int l = lane_fresh(); return __int_as_float(__builtin_amdgcn_ds_bpermute((l ^ mask) << 2, __float_as_int(v))); }
; __device__ __forceinline__ void attn_sample_item(const Params& p, int item, const int wv) {
;     ...
;     for (int it = 0; it < 8; ++it) {
;       const int mm = wid * 32 + it * 4 + ksub;
;       f32x4 k0 = *(const f32x4*)(Kc + (size_t)mm * 512 + dch * 8), k1 = *(const f32x4*)(Kc + (size_t)mm * 512 + dch * 8 + 4);
;       float d = q[0] * k0[0] + q[1] * k0[1] + q[2] * k0[2] + q[3] * k0[3] + q[4] * k1[0] + q[5] * k1[1] + q[6] * k1[2] + q[7] * k1[3];
;       d += shfl_xor_f(d, 1); d += shfl_xor_f(d, 2); d += shfl_xor_f(d, 4); d += shfl_xor_f(d, 8);
;       if (dch == 0) sc_l[mm] = d * 0.08838834764831845f;
;     }
.LBB0_470:
	s_or_b64 exec, exec, s[10:11]
	s_waitcnt lgkmcnt(0)
	v_add_u32_e32 v82, 12, v70
	v_ashrrev_i32_e32 v83, 31, v82
	v_lshlrev_b64 v[82:83], 11, v[82:83]
	v_lshl_add_u64 v[86:87], v[68:69], 0, v[82:83]
	s_nop 0
	v_mbcnt_lo_u32_b32 v81, -1, 0
	v_mbcnt_hi_u32_b32 v81, -1, v81
	s_waitcnt vmcnt(8)
	v_mul_f32_e32 v83, v181, v79
	v_fmac_f32_e32 v83, v180, v71
	v_fmac_f32_e32 v83, v182, v73
	v_fmac_f32_e32 v83, v183, v74
	v_fmac_f32_e32 v83, v184, v75
	v_fmac_f32_e32 v83, v185, v76
	v_lshlrev_b32_e32 v81, 2, v81
	v_fmac_f32_e32 v83, v186, v77
	v_xor_b32_e32 v81, 4, v81
	v_fmac_f32_e32 v83, v187, v78
	s_nop 1
	v_mov_b32_dpp v81, v83 quad_perm:[1,0,3,2] row_mask:0xf bank_mask:0xf
	v_mbcnt_lo_u32_b32 v82, -1, 0
	v_mbcnt_hi_u32_b32 v82, -1, v82
	v_add_f32_e32 v81, v83, v81
	v_lshlrev_b32_e32 v82, 2, v82
	v_xor_b32_e32 v82, 8, v82
	s_nop 1
	v_mov_b32_dpp v82, v81 quad_perm:[2,3,0,1] row_mask:0xf bank_mask:0xf
	v_mbcnt_lo_u32_b32 v83, -1, 0
	v_mbcnt_hi_u32_b32 v83, -1, v83
	v_add_f32_e32 v81, v81, v82
	v_lshlrev_b32_e32 v83, 2, v83
	v_xor_b32_e32 v83, 16, v83
	s_nop 1
	v_mov_b32_dpp v82, v81 row_shl:4 row_mask:0xf bank_mask:0x5
	v_mov_b32_dpp v82, v81 row_shr:4 row_mask:0xf bank_mask:0xa
	v_mbcnt_lo_u32_b32 v83, -1, 0
	v_mbcnt_hi_u32_b32 v83, -1, v83
	v_add_f32_e32 v81, v81, v82
	v_lshlrev_b32_e32 v83, 2, v83
	v_xor_b32_e32 v82, 32, v83
	s_nop 1
	v_mov_b32_dpp v82, v81 row_ror:8 row_mask:0xf bank_mask:0xf
	s_and_saveexec_b64 s[10:11], vcc
	s_cbranch_execz .LBB0_472
	s_waitcnt lgkmcnt(0)
	v_add_f32_e32 v81, v81, v82
	v_mul_f32_e32 v81, 0x3db504f3, v81
	ds_write_b32 v80, v81 offset:48
.LBB0_472:
	s_or_b64 exec, exec, s[10:11]
	s_waitcnt lgkmcnt(0)
	v_add_u32_e32 v82, 16, v70
	v_ashrrev_i32_e32 v83, 31, v82
	v_lshlrev_b64 v[82:83], 11, v[82:83]
	v_lshl_add_u64 v[86:87], v[68:69], 0, v[82:83]
	s_nop 0
	v_mbcnt_lo_u32_b32 v81, -1, 0
	v_mbcnt_hi_u32_b32 v81, -1, v81
	s_waitcnt vmcnt(6)
	v_mul_f32_e32 v83, v189, v79
	v_fmac_f32_e32 v83, v188, v71
	v_fmac_f32_e32 v83, v190, v73
	v_fmac_f32_e32 v83, v191, v74
	v_fmac_f32_e32 v83, v192, v75
	v_fmac_f32_e32 v83, v193, v76
	v_lshlrev_b32_e32 v81, 2, v81
	v_fmac_f32_e32 v83, v194, v77
	v_xor_b32_e32 v81, 4, v81
	v_fmac_f32_e32 v83, v195, v78
	s_nop 1
	v_mov_b32_dpp v81, v83 quad_perm:[1,0,3,2] row_mask:0xf bank_mask:0xf
	v_mbcnt_lo_u32_b32 v82, -1, 0
	v_mbcnt_hi_u32_b32 v82, -1, v82
	v_add_f32_e32 v81, v83, v81
	v_lshlrev_b32_e32 v82, 2, v82
	v_xor_b32_e32 v82, 8, v82
	s_nop 1
	v_mov_b32_dpp v82, v81 quad_perm:[2,3,0,1] row_mask:0xf bank_mask:0xf
	v_mbcnt_lo_u32_b32 v83, -1, 0
	v_mbcnt_hi_u32_b32 v83, -1, v83
	v_add_f32_e32 v81, v81, v82
	v_lshlrev_b32_e32 v83, 2, v83
	v_xor_b32_e32 v83, 16, v83
	s_nop 1
	v_mov_b32_dpp v82, v81 row_shl:4 row_mask:0xf bank_mask:0x5
	v_mov_b32_dpp v82, v81 row_shr:4 row_mask:0xf bank_mask:0xa
	v_mbcnt_lo_u32_b32 v83, -1, 0
	v_mbcnt_hi_u32_b32 v83, -1, v83
	v_add_f32_e32 v81, v81, v82
	v_lshlrev_b32_e32 v83, 2, v83
	v_xor_b32_e32 v82, 32, v83
	s_nop 1
	v_mov_b32_dpp v82, v81 row_ror:8 row_mask:0xf bank_mask:0xf
	s_and_saveexec_b64 s[10:11], vcc
	s_cbranch_execz .LBB0_474
	s_waitcnt lgkmcnt(0)
	v_add_f32_e32 v81, v81, v82
	v_mul_f32_e32 v81, 0x3db504f3, v81
	ds_write_b32 v80, v81 offset:64
.LBB0_474:
	s_or_b64 exec, exec, s[10:11]
	s_waitcnt lgkmcnt(0)
	v_add_u32_e32 v82, 20, v70
	v_ashrrev_i32_e32 v83, 31, v82
	v_lshlrev_b64 v[82:83], 11, v[82:83]
	v_lshl_add_u64 v[86:87], v[68:69], 0, v[82:83]
	s_nop 0
	v_mbcnt_lo_u32_b32 v81, -1, 0
	v_mbcnt_hi_u32_b32 v81, -1, v81
	s_waitcnt vmcnt(4)
	v_mul_f32_e32 v83, v197, v79
	v_fmac_f32_e32 v83, v196, v71
	v_fmac_f32_e32 v83, v198, v73
	v_fmac_f32_e32 v83, v199, v74
	v_fmac_f32_e32 v83, v200, v75
	v_fmac_f32_e32 v83, v201, v76
	v_lshlrev_b32_e32 v81, 2, v81
	v_fmac_f32_e32 v83, v202, v77
	v_xor_b32_e32 v81, 4, v81
	v_fmac_f32_e32 v83, v203, v78
	s_nop 1
	v_mov_b32_dpp v81, v83 quad_perm:[1,0,3,2] row_mask:0xf bank_mask:0xf
	v_mbcnt_lo_u32_b32 v82, -1, 0
	v_mbcnt_hi_u32_b32 v82, -1, v82
	v_add_f32_e32 v81, v83, v81
	v_lshlrev_b32_e32 v82, 2, v82
	v_xor_b32_e32 v82, 8, v82
	s_nop 1
	v_mov_b32_dpp v82, v81 quad_perm:[2,3,0,1] row_mask:0xf bank_mask:0xf
	v_mbcnt_lo_u32_b32 v83, -1, 0
	v_mbcnt_hi_u32_b32 v83, -1, v83
	v_add_f32_e32 v81, v81, v82
	v_lshlrev_b32_e32 v83, 2, v83
	v_xor_b32_e32 v83, 16, v83
	s_nop 1
	v_mov_b32_dpp v82, v81 row_shl:4 row_mask:0xf bank_mask:0x5
	v_mov_b32_dpp v82, v81 row_shr:4 row_mask:0xf bank_mask:0xa
	v_mbcnt_lo_u32_b32 v83, -1, 0
	v_mbcnt_hi_u32_b32 v83, -1, v83
	v_add_f32_e32 v81, v81, v82
	v_lshlrev_b32_e32 v83, 2, v83
	v_xor_b32_e32 v82, 32, v83
	s_nop 1
	v_mov_b32_dpp v82, v81 row_ror:8 row_mask:0xf bank_mask:0xf
	s_and_saveexec_b64 s[10:11], vcc
	s_cbranch_execz .LBB0_476
	s_waitcnt lgkmcnt(0)
	v_add_f32_e32 v81, v81, v82
	v_mul_f32_e32 v81, 0x3db504f3, v81
	ds_write_b32 v80, v81 offset:80
.LBB0_476:
	s_or_b64 exec, exec, s[10:11]
	s_waitcnt lgkmcnt(0)
	v_add_u32_e32 v82, 24, v70
	v_ashrrev_i32_e32 v83, 31, v82
	v_lshlrev_b64 v[82:83], 11, v[82:83]
	v_lshl_add_u64 v[86:87], v[68:69], 0, v[82:83]
	s_nop 0
	v_mbcnt_lo_u32_b32 v81, -1, 0
	v_mbcnt_hi_u32_b32 v81, -1, v81
	s_waitcnt vmcnt(2)
	v_mul_f32_e32 v83, v205, v79
	v_fmac_f32_e32 v83, v204, v71
	v_fmac_f32_e32 v83, v206, v73
	v_fmac_f32_e32 v83, v207, v74
	v_fmac_f32_e32 v83, v208, v75
	v_fmac_f32_e32 v83, v209, v76
	v_lshlrev_b32_e32 v81, 2, v81
	v_fmac_f32_e32 v83, v210, v77
	v_xor_b32_e32 v81, 4, v81
	v_fmac_f32_e32 v83, v211, v78
	s_nop 1
	v_mov_b32_dpp v81, v83 quad_perm:[1,0,3,2] row_mask:0xf bank_mask:0xf
	v_mbcnt_lo_u32_b32 v82, -1, 0
	v_mbcnt_hi_u32_b32 v82, -1, v82
	v_add_f32_e32 v81, v83, v81
	v_lshlrev_b32_e32 v82, 2, v82
	v_xor_b32_e32 v82, 8, v82
	s_nop 1
	v_mov_b32_dpp v82, v81 quad_perm:[2,3,0,1] row_mask:0xf bank_mask:0xf
	v_mbcnt_lo_u32_b32 v83, -1, 0
	v_mbcnt_hi_u32_b32 v83, -1, v83
	v_add_f32_e32 v81, v81, v82
	v_lshlrev_b32_e32 v83, 2, v83
	v_xor_b32_e32 v83, 16, v83
	s_nop 1
	v_mov_b32_dpp v82, v81 row_shl:4 row_mask:0xf bank_mask:0x5
	v_mov_b32_dpp v82, v81 row_shr:4 row_mask:0xf bank_mask:0xa
	v_mbcnt_lo_u32_b32 v83, -1, 0
	v_mbcnt_hi_u32_b32 v83, -1, v83
	v_add_f32_e32 v81, v81, v82
	v_lshlrev_b32_e32 v83, 2, v83
	v_xor_b32_e32 v82, 32, v83
	s_nop 1
	v_mov_b32_dpp v82, v81 row_ror:8 row_mask:0xf bank_mask:0xf
	s_and_saveexec_b64 s[10:11], vcc
	s_cbranch_execz .LBB0_478
	s_waitcnt lgkmcnt(0)
	v_add_f32_e32 v81, v81, v82
	v_mul_f32_e32 v81, 0x3db504f3, v81
	ds_write_b32 v80, v81 offset:96
; __device__ __forceinline__ float shfl_xor_f(float v, int mask) { const int l = lane_fresh(); return __int_as_float(__builtin_amdgcn_ds_bpermute((l ^ mask) << 2, __float_as_int(v))); }
; __device__ __forceinline__ void attn_sample_item(const Params& p, int item, const int wv) {
;     ...
;     for (int it = 0; it < 8; ++it) {
;       const int mm = wid * 32 + it * 4 + ksub;
;       f32x4 k0 = *(const f32x4*)(Kc + (size_t)mm * 512 + dch * 8), k1 = *(const f32x4*)(Kc + (size_t)mm * 512 + dch * 8 + 4);
;       float d = q[0] * k0[0] + q[1] * k0[1] + q[2] * k0[2] + q[3] * k0[3] + q[4] * k1[0] + q[5] * k1[1] + q[6] * k1[2] + q[7] * k1[3];
;       d += shfl_xor_f(d, 1); d += shfl_xor_f(d, 2); d += shfl_xor_f(d, 4); d += shfl_xor_f(d, 8);
;       if (dch == 0) sc_l[mm] = d * 0.08838834764831845f;
;     }
;   }
;   __syncthreads();
;   float pv[4];
;   {
;     float mx = -1e30f;
; #pragma unroll
;     for (int i = 0; i < 4; ++i) { pv[i] = sc_l[lane + 64 * i]; mx = fmaxf(mx, pv[i]); }
;     mx = wave_max(mx);
;     float sum = 0.f;
; #pragma unroll
;     for (int i = 0; i < 4; ++i) { pv[i] = __expf(pv[i] - mx); sum += pv[i]; }
;     sum = wave_sum(sum);
;     const float inv = 1.f / sum;
; #pragma unroll
;     for (int i = 0; i < 4; ++i) pv[i] *= inv;
;   }
;   __syncthreads();
;   if (wid == 0) {
; #pragma unroll
;     for (int i = 0; i < 4; ++i) sc_l[lane + 64 * i] = pv[i];
;   }
.LBB0_478:
	s_or_b64 exec, exec, s[10:11]
	s_waitcnt lgkmcnt(0)
	v_add_u32_e32 v82, 28, v70
	v_ashrrev_i32_e32 v83, 31, v82
	v_lshlrev_b64 v[82:83], 11, v[82:83]
	v_lshl_add_u64 v[68:69], v[68:69], 0, v[82:83]
	v_mbcnt_lo_u32_b32 v68, -1, 0
	v_mbcnt_hi_u32_b32 v68, -1, v68
	v_mbcnt_lo_u32_b32 v70, -1, 0
	v_mbcnt_hi_u32_b32 v70, -1, v70
	s_waitcnt vmcnt(0)
	v_mul_f32_e32 v69, v213, v79
	v_fmac_f32_e32 v69, v212, v71
	v_fmac_f32_e32 v69, v214, v73
	v_fmac_f32_e32 v69, v215, v74
	v_fmac_f32_e32 v69, v216, v75
	v_fmac_f32_e32 v69, v217, v76
	v_lshlrev_b32_e32 v68, 2, v68
	v_fmac_f32_e32 v69, v218, v77
	v_xor_b32_e32 v68, 4, v68
	v_fmac_f32_e32 v69, v219, v78
	s_nop 1
	v_mov_b32_dpp v68, v69 quad_perm:[1,0,3,2] row_mask:0xf bank_mask:0xf
	v_lshlrev_b32_e32 v70, 2, v70
	v_xor_b32_e32 v70, 8, v70
	v_add_f32_e32 v68, v69, v68
	s_nop 1
	v_mov_b32_dpp v69, v68 quad_perm:[2,3,0,1] row_mask:0xf bank_mask:0xf
	v_mbcnt_lo_u32_b32 v70, -1, 0
	v_mbcnt_hi_u32_b32 v70, -1, v70
	v_add_f32_e32 v68, v68, v69
	v_lshlrev_b32_e32 v70, 2, v70
	v_xor_b32_e32 v70, 16, v70
	s_nop 1
	v_mov_b32_dpp v69, v68 row_shl:4 row_mask:0xf bank_mask:0x5
	v_mov_b32_dpp v69, v68 row_shr:4 row_mask:0xf bank_mask:0xa
	v_mbcnt_lo_u32_b32 v70, -1, 0
	v_mbcnt_hi_u32_b32 v70, -1, v70
	v_add_f32_e32 v68, v68, v69
	v_lshlrev_b32_e32 v70, 2, v70
	v_xor_b32_e32 v69, 32, v70
	s_nop 1
	v_mov_b32_dpp v69, v68 row_ror:8 row_mask:0xf bank_mask:0xf
	s_and_saveexec_b64 s[10:11], vcc
	s_cbranch_execz .LBB0_480
	s_waitcnt lgkmcnt(0)
	v_add_f32_e32 v68, v68, v69
	v_mul_f32_e32 v68, 0x3db504f3, v68
	ds_write_b32 v80, v68 offset:112
.LBB0_480:
	s_or_b64 exec, exec, s[10:11]
	v_lshl_add_u32 v68, v72, 2, 16
	s_waitcnt lgkmcnt(0)
	s_barrier
	ds_read2st64_b32 v[70:71], v68 offset1:1
	ds_read2st64_b32 v[72:73], v68 offset0:2 offset1:3
	v_mbcnt_lo_u32_b32 v74, -1, 0
	v_mbcnt_hi_u32_b32 v74, -1, v74
	v_mbcnt_lo_u32_b32 v75, -1, 0
	v_mbcnt_hi_u32_b32 v75, -1, v75
	v_readlane_b32 s10, v251, 58
	s_waitcnt lgkmcnt(1)
	v_max3_f32 v69, v70, s17, v71
	v_lshlrev_b32_e32 v74, 2, v74
	s_waitcnt lgkmcnt(0)
	v_max3_f32 v69, v69, v72, v73
	v_xor_b32_e32 v74, 0x80, v74
	ds_bpermute_b32 v74, v74, v69
	v_readlane_b32 s11, v251, 59
	s_and_b64 vcc, exec, s[10:11]
	s_waitcnt lgkmcnt(0)
	v_max_f32_e32 v74, v74, v74
	v_max_f32_e32 v69, v69, v74
	v_lshlrev_b32_e32 v74, 2, v75
	v_xor_b32_e32 v74, 64, v74
	ds_bpermute_b32 v74, v74, v69
	v_mbcnt_lo_u32_b32 v75, -1, 0
	v_mbcnt_hi_u32_b32 v75, -1, v75
	s_waitcnt lgkmcnt(0)
	v_max_f32_e32 v74, v74, v74
	v_lshlrev_b32_e32 v75, 2, v75
	v_max_f32_e32 v69, v69, v74
	v_xor_b32_e32 v74, 32, v75
	s_nop 1
	v_mov_b32_dpp v74, v69 row_ror:8 row_mask:0xf bank_mask:0xf
	v_mbcnt_lo_u32_b32 v75, -1, 0
	v_mbcnt_hi_u32_b32 v75, -1, v75
	v_max_f32_e32 v74, v74, v74
	v_lshlrev_b32_e32 v75, 2, v75
	v_xor_b32_e32 v75, 16, v75
	v_max_f32_e32 v69, v69, v74
	s_nop 1
	v_mov_b32_dpp v74, v69 row_shl:4 row_mask:0xf bank_mask:0x5
	v_mov_b32_dpp v74, v69 row_shr:4 row_mask:0xf bank_mask:0xa
	v_mbcnt_lo_u32_b32 v75, -1, 0
	v_mbcnt_hi_u32_b32 v75, -1, v75
	v_max_f32_e32 v74, v74, v74
	v_lshlrev_b32_e32 v75, 2, v75
	v_xor_b32_e32 v75, 8, v75
	v_max_f32_e32 v69, v69, v74
	s_nop 1
	v_mov_b32_dpp v74, v69 quad_perm:[2,3,0,1] row_mask:0xf bank_mask:0xf
	v_mbcnt_lo_u32_b32 v75, -1, 0
	v_mbcnt_hi_u32_b32 v75, -1, v75
	v_max_f32_e32 v74, v74, v74
	v_lshlrev_b32_e32 v75, 2, v75
	v_xor_b32_e32 v75, 4, v75
	v_max_f32_e32 v69, v69, v74
	s_nop 1
	v_mov_b32_dpp v74, v69 quad_perm:[1,0,3,2] row_mask:0xf bank_mask:0xf
	v_max_f32_e32 v74, v74, v74
	v_max_f32_e32 v69, v69, v74
	v_sub_f32_e32 v70, v70, v69
	v_sub_f32_e32 v71, v71, v69
	v_sub_f32_e32 v72, v72, v69
	v_sub_f32_e32 v69, v73, v69
	v_mul_f32_e32 v70, 0x3fb8aa3b, v70
	v_mul_f32_e32 v71, 0x3fb8aa3b, v71
	v_mul_f32_e32 v73, 0x3fb8aa3b, v69
	v_exp_f32_e32 v69, v70
	v_mul_f32_e32 v72, 0x3fb8aa3b, v72
	v_exp_f32_e32 v70, v71
	v_exp_f32_e32 v71, v72
	v_exp_f32_e32 v72, v73
	v_add_f32_e32 v73, 0, v69
	v_add_f32_e32 v73, v70, v73
	v_mbcnt_lo_u32_b32 v74, -1, 0
	v_mbcnt_hi_u32_b32 v74, -1, v74
	v_add_f32_e32 v73, v71, v73
	v_lshlrev_b32_e32 v74, 2, v74
	v_add_f32_e32 v73, v72, v73
	v_xor_b32_e32 v74, 0x80, v74
	ds_bpermute_b32 v74, v74, v73
	v_mbcnt_lo_u32_b32 v75, -1, 0
	v_mbcnt_hi_u32_b32 v75, -1, v75
	s_waitcnt lgkmcnt(0)
	v_add_f32_e32 v73, v73, v74
	v_lshlrev_b32_e32 v74, 2, v75
	v_xor_b32_e32 v74, 64, v74
	ds_bpermute_b32 v74, v74, v73
	v_mbcnt_lo_u32_b32 v75, -1, 0
	v_mbcnt_hi_u32_b32 v75, -1, v75
	s_waitcnt lgkmcnt(0)
	v_add_f32_e32 v73, v73, v74
	v_lshlrev_b32_e32 v75, 2, v75
	v_xor_b32_e32 v74, 32, v75
	s_nop 1
	v_mov_b32_dpp v74, v73 row_ror:8 row_mask:0xf bank_mask:0xf
	v_mbcnt_lo_u32_b32 v75, -1, 0
	v_mbcnt_hi_u32_b32 v75, -1, v75
	v_add_f32_e32 v73, v73, v74
	v_lshlrev_b32_e32 v75, 2, v75
	v_xor_b32_e32 v75, 16, v75
	s_nop 1
	v_mov_b32_dpp v74, v73 row_shl:4 row_mask:0xf bank_mask:0x5
	v_mov_b32_dpp v74, v73 row_shr:4 row_mask:0xf bank_mask:0xa
	v_mbcnt_lo_u32_b32 v75, -1, 0
	v_mbcnt_hi_u32_b32 v75, -1, v75
	v_add_f32_e32 v73, v73, v74
	v_lshlrev_b32_e32 v75, 2, v75
	v_xor_b32_e32 v75, 8, v75
	s_nop 1
	v_mov_b32_dpp v74, v73 quad_perm:[2,3,0,1] row_mask:0xf bank_mask:0xf
	v_mbcnt_lo_u32_b32 v75, -1, 0
	v_mbcnt_hi_u32_b32 v75, -1, v75
	v_lshlrev_b32_e32 v75, 2, v75
	s_barrier
	v_add_f32_e32 v73, v73, v74
	v_xor_b32_e32 v74, 4, v75
	s_nop 1
	v_mov_b32_dpp v74, v73 quad_perm:[1,0,3,2] row_mask:0xf bank_mask:0xf
	s_cbranch_vccnz .LBB0_482
	v_add_f32_e32 v73, v73, v74
	v_div_scale_f32 v74, s[10:11], v73, v73, 1.0
	v_rcp_f32_e32 v75, v74
	v_div_scale_f32 v76, vcc, 1.0, v73, 1.0
	v_fma_f32 v77, -v74, v75, 1.0
	v_fmac_f32_e32 v75, v77, v75
	v_mul_f32_e32 v77, v76, v75
	v_fma_f32 v78, -v74, v77, v76
	v_fmac_f32_e32 v77, v78, v75
	v_fma_f32 v74, -v74, v77, v76
	v_div_fmas_f32 v74, v74, v75, v77
	v_div_fixup_f32 v73, v74, v73, 1.0
	v_mul_f32_e32 v70, v70, v73
	v_mul_f32_e32 v69, v69, v73
	v_mul_f32_e32 v72, v72, v73
	v_mul_f32_e32 v71, v71, v73
	ds_write2st64_b32 v68, v69, v70 offset1:1
	ds_write2st64_b32 v68, v71, v72 offset0:2 offset1:3

; __device__ __forceinline__ float bflo(unsigned w) { return __uint_as_float(w << 16); }
; __device__ __forceinline__ float bfhi(unsigned w) { return __uint_as_float(w & 0xffff0000u); }
; __device__ __forceinline__ void attn_sample_item(const Params& p, int item, const int wv) {
;     ...
;   const int vdch = tid & 31, vmg = tid >> 5;
;   f32x4 vreg[16];
; #pragma unroll
;   for (int i = 0; i < 16; ++i) vreg[i] = *(const f32x4*)(Vc + (size_t)(vmg * 16 + i) * 512 + vdch * 4);
;   __syncthreads();
;   {
;     const int dch = lane & 15, ksub = lane >> 4;
;     u32x4 qw = *(const u32x4*)(Q + (size_t)tok * 512 + h * 128 + dch * 8);
;     float q[8] = {bflo(qw.x), bfhi(qw.x), bflo(qw.y), bfhi(qw.y), bflo(qw.z), bfhi(qw.z), bflo(qw.w), bfhi(qw.w)};
; #pragma unroll
;     for (int it = 0; it < 8; ++it) {
;       const int mm = wid * 32 + it * 4 + ksub;
;       f32x4 k0 = *(const f32x4*)(Kc + (size_t)mm * 512 + dch * 8), k1 = *(const f32x4*)(Kc + (size_t)mm * 512 + dch * 8 + 4);
.LBB0_490:
	s_lshr_b32 s0, s18, 2
	s_and_b32 s19, s14, 0x180
	v_readlane_b32 s64, v251, 6
	s_lshl_b32 s20, s19, 2
	s_lshl_b64 s[8:9], s[0:1], 19
	v_readlane_b32 s72, v251, 14
	v_readlane_b32 s73, v251, 15
	s_or_b32 s8, s8, s20
	s_mov_b64 s[44:45], s[72:73]
	v_mbcnt_lo_u32_b32 v72, -1, 0
	v_mbcnt_hi_u32_b32 v72, -1, v72
	v_readlane_b32 s70, v251, 12
	v_add_u32_e32 v66, s82, v72
	v_readlane_b32 s71, v251, 13
	s_add_u32 s20, s44, s8
	s_mov_b64 s[42:43], s[70:71]
	s_addc_u32 s21, s45, s9
	v_and_b32_e32 v0, 31, v72
	v_ashrrev_i32_e32 v67, 5, v66
	s_addk_i32 s0, 0x4000
	v_lshlrev_b32_e32 v56, 4, v67
	v_lshlrev_b32_e32 v64, 4, v0
	s_add_u32 s8, s42, s8
	v_lshl_add_u64 v[58:59], s[20:21], 0, v[64:65]
	v_ashrrev_i32_e32 v57, 31, v56
	s_addc_u32 s9, s43, s9
	s_lshl_b64 s[20:21], s[0:1], 10
	s_waitcnt lgkmcnt(0)
	v_lshlrev_b64 v[0:1], 11, v[56:57]
	v_or_b32_e32 v2, 1, v56
	v_or_b32_e32 v8, 2, v56
	v_or_b32_e32 v10, 3, v56
	v_or_b32_e32 v16, 4, v56
	v_or_b32_e32 v18, 5, v56
	v_or_b32_e32 v24, 6, v56
	v_or_b32_e32 v26, 7, v56
	v_or_b32_e32 v32, 8, v56
	v_or_b32_e32 v34, 9, v56
	v_or_b32_e32 v40, 10, v56
	v_or_b32_e32 v42, 11, v56
	v_or_b32_e32 v48, 12, v56
	v_or_b32_e32 v50, 13, v56
	v_or_b32_e32 v60, 14, v56
	v_or_b32_e32 v56, 15, v56
	s_add_u32 s20, s10, s20
	v_ashrrev_i32_e32 v3, 31, v2
	v_ashrrev_i32_e32 v9, 31, v8
	v_ashrrev_i32_e32 v11, 31, v10
	v_ashrrev_i32_e32 v17, 31, v16
	v_ashrrev_i32_e32 v19, 31, v18
	v_ashrrev_i32_e32 v25, 31, v24
	v_ashrrev_i32_e32 v27, 31, v26
	v_ashrrev_i32_e32 v33, 31, v32
	v_ashrrev_i32_e32 v35, 31, v34
	v_ashrrev_i32_e32 v41, 31, v40
	v_ashrrev_i32_e32 v43, 31, v42
	v_ashrrev_i32_e32 v49, 31, v48
	v_ashrrev_i32_e32 v51, 31, v50
	v_ashrrev_i32_e32 v61, 31, v60
	v_ashrrev_i32_e32 v57, 31, v56
	s_addc_u32 s21, s11, s21
	s_lshl_b32 s19, s19, 1
	v_lshlrev_b64 v[2:3], 11, v[2:3]
	v_lshlrev_b64 v[8:9], 11, v[8:9]
	v_lshlrev_b64 v[10:11], 11, v[10:11]
	v_lshlrev_b64 v[16:17], 11, v[16:17]
	v_lshlrev_b64 v[18:19], 11, v[18:19]
	v_lshlrev_b64 v[24:25], 11, v[24:25]
	v_lshlrev_b64 v[26:27], 11, v[26:27]
	v_lshlrev_b64 v[32:33], 11, v[32:33]
	v_lshlrev_b64 v[34:35], 11, v[34:35]
	v_lshlrev_b64 v[40:41], 11, v[40:41]
	v_lshlrev_b64 v[42:43], 11, v[42:43]
	v_lshlrev_b64 v[48:49], 11, v[48:49]
	v_lshlrev_b64 v[50:51], 11, v[50:51]
	v_lshlrev_b64 v[60:61], 11, v[60:61]
	v_lshlrev_b64 v[56:57], 11, v[56:57]
	v_and_b32_e32 v92, 15, v72
	v_ashrrev_i32_e32 v68, 4, v72
	s_add_u32 s20, s20, s19
	v_lshl_add_u64 v[0:1], v[58:59], 0, v[0:1]
	v_lshl_add_u64 v[2:3], v[58:59], 0, v[2:3]
	v_lshl_add_u64 v[8:9], v[58:59], 0, v[8:9]
	v_lshl_add_u64 v[10:11], v[58:59], 0, v[10:11]
	v_lshl_add_u64 v[16:17], v[58:59], 0, v[16:17]
	v_lshl_add_u64 v[18:19], v[58:59], 0, v[18:19]
	v_lshl_add_u64 v[24:25], v[58:59], 0, v[24:25]
	v_lshl_add_u64 v[26:27], v[58:59], 0, v[26:27]
	v_lshl_add_u64 v[32:33], v[58:59], 0, v[32:33]
	v_lshl_add_u64 v[34:35], v[58:59], 0, v[34:35]
	v_lshl_add_u64 v[40:41], v[58:59], 0, v[40:41]
	v_lshl_add_u64 v[42:43], v[58:59], 0, v[42:43]
	v_lshl_add_u64 v[48:49], v[58:59], 0, v[48:49]
	v_lshl_add_u64 v[50:51], v[58:59], 0, v[50:51]
	v_lshl_add_u64 v[60:61], v[58:59], 0, v[60:61]
	v_lshl_add_u64 v[56:57], v[58:59], 0, v[56:57]
	s_addc_u32 s21, s21, 0
	v_lshlrev_b32_e32 v69, 4, v92
	v_add_u32_e32 v70, s5, v68
	global_load_dwordx4 v[4:7], v[0:1], off
	s_nop 0
	global_load_dwordx4 v[0:3], v[2:3], off
	s_nop 0
	global_load_dwordx4 v[12:15], v[8:9], off
	s_nop 0
	global_load_dwordx4 v[8:11], v[10:11], off
	s_nop 0
	global_load_dwordx4 v[20:23], v[16:17], off
	s_nop 0
	global_load_dwordx4 v[16:19], v[18:19], off
	s_nop 0
	global_load_dwordx4 v[28:31], v[24:25], off
	s_nop 0
	global_load_dwordx4 v[24:27], v[26:27], off
	s_nop 0
	global_load_dwordx4 v[36:39], v[32:33], off
	s_nop 0
	global_load_dwordx4 v[32:35], v[34:35], off
	s_nop 0
	global_load_dwordx4 v[44:47], v[40:41], off
	s_nop 0
	global_load_dwordx4 v[40:43], v[42:43], off
	s_nop 0
	global_load_dwordx4 v[52:55], v[48:49], off
	s_nop 0
	global_load_dwordx4 v[48:51], v[50:51], off
	s_nop 0
	global_load_dwordx4 v[60:63], v[60:61], off
	s_nop 0
	global_load_dwordx4 v[56:59], v[56:57], off
	s_barrier
	global_load_dwordx4 v[80:83], v69, s[20:21]
	v_lshlrev_b32_e32 v68, 5, v92
	v_mov_b32_e32 v69, v65
	v_ashrrev_i32_e32 v71, 31, v70
	v_lshl_add_u64 v[68:69], s[8:9], 0, v[68:69]
	v_lshlrev_b64 v[74:75], 11, v[70:71]
	v_lshl_add_u64 v[74:75], v[68:69], 0, v[74:75]
	global_load_dwordx4 v[84:87], v[74:75], off
	global_load_dwordx4 v[88:91], v[74:75], off offset:16
	v_mov_b32_e32 v221, 0
	v_mov_b32_e32 v220, 0x2000
	v_lshl_add_u64 v[222:223], v[220:221], 0, v[74:75]
	global_load_dwordx4 v[164:167], v[222:223], off
	global_load_dwordx4 v[168:171], v[222:223], off offset:16
	v_mov_b32_e32 v220, 0x4000
	v_lshl_add_u64 v[222:223], v[220:221], 0, v[74:75]
	global_load_dwordx4 v[172:175], v[222:223], off
	global_load_dwordx4 v[176:179], v[222:223], off offset:16
	v_mov_b32_e32 v220, 0x6000
	v_lshl_add_u64 v[222:223], v[220:221], 0, v[74:75]
	global_load_dwordx4 v[180:183], v[222:223], off
	global_load_dwordx4 v[184:187], v[222:223], off offset:16
	v_mov_b32_e32 v220, 0x8000
	v_lshl_add_u64 v[222:223], v[220:221], 0, v[74:75]
	global_load_dwordx4 v[188:191], v[222:223], off
	global_load_dwordx4 v[192:195], v[222:223], off offset:16
	v_mov_b32_e32 v220, 0xa000
	v_lshl_add_u64 v[222:223], v[220:221], 0, v[74:75]
	global_load_dwordx4 v[196:199], v[222:223], off
	global_load_dwordx4 v[200:203], v[222:223], off offset:16
	v_mov_b32_e32 v220, 0xc000
	v_lshl_add_u64 v[222:223], v[220:221], 0, v[74:75]
	global_load_dwordx4 v[204:207], v[222:223], off
	global_load_dwordx4 v[208:211], v[222:223], off offset:16
	v_mov_b32_e32 v220, 0xe000
	v_lshl_add_u64 v[222:223], v[220:221], 0, v[74:75]
	global_load_dwordx4 v[212:215], v[222:223], off
	global_load_dwordx4 v[216:219], v[222:223], off offset:16
	v_cmp_eq_u32_e32 vcc, 0, v92
	v_readlane_b32 s65, v251, 7
	v_readlane_b32 s66, v251, 8
	v_readlane_b32 s67, v251, 9
	v_readlane_b32 s68, v251, 10
	v_readlane_b32 s69, v251, 11
	v_readlane_b32 s74, v251, 16
	v_readlane_b32 s75, v251, 17
	v_readlane_b32 s76, v251, 18
	v_readlane_b32 s77, v251, 19
	v_readlane_b32 s78, v251, 20
	v_readlane_b32 s79, v251, 21
	s_waitcnt vmcnt(16)
; __device__ __forceinline__ float shfl_xor_f(float v, int mask) { const int l = lane_fresh(); return __int_as_float(__builtin_amdgcn_ds_bpermute((l ^ mask) << 2, __float_as_int(v))); }
; __device__ __forceinline__ void attn_sample_item(const Params& p, int item, const int wv) {
;     ...
;     for (int it = 0; it < 8; ++it) {
;       const int mm = wid * 32 + it * 4 + ksub;
;       f32x4 k0 = *(const f32x4*)(Kc + (size_t)mm * 512 + dch * 8), k1 = *(const f32x4*)(Kc + (size_t)mm * 512 + dch * 8 + 4);
;       float d = q[0] * k0[0] + q[1] * k0[1] + q[2] * k0[2] + q[3] * k0[3] + q[4] * k1[0] + q[5] * k1[1] + q[6] * k1[2] + q[7] * k1[3];
;       d += shfl_xor_f(d, 1); d += shfl_xor_f(d, 2); d += shfl_xor_f(d, 4); d += shfl_xor_f(d, 8);
;       if (dch == 0) sc_l[mm] = d * 0.08838834764831845f;
;     }
	v_and_b32_e32 v79, 0xffff0000, v80
	v_lshlrev_b32_e32 v71, 16, v80
	v_lshlrev_b32_e32 v73, 16, v81
	v_and_b32_e32 v74, 0xffff0000, v81
	v_lshlrev_b32_e32 v75, 16, v82
	v_and_b32_e32 v76, 0xffff0000, v82
	s_waitcnt vmcnt(15)
	v_mul_f32_e32 v80, v85, v79
	v_fmac_f32_e32 v80, v84, v71
	v_fmac_f32_e32 v80, v86, v73
	v_fmac_f32_e32 v80, v87, v74
	s_waitcnt vmcnt(14)
	v_fmac_f32_e32 v80, v88, v75
	v_lshlrev_b32_e32 v77, 16, v83
	v_fmac_f32_e32 v80, v89, v76
	v_mbcnt_lo_u32_b32 v81, -1, 0
	v_mbcnt_hi_u32_b32 v81, -1, v81
	v_and_b32_e32 v78, 0xffff0000, v83
	v_fmac_f32_e32 v80, v90, v77
	v_lshlrev_b32_e32 v81, 2, v81
	v_fmac_f32_e32 v80, v91, v78
	v_xor_b32_e32 v81, 4, v81
	s_nop 1
	v_mov_b32_dpp v81, v80 quad_perm:[1,0,3,2] row_mask:0xf bank_mask:0xf
	v_add_f32_e32 v80, v80, v81
	v_mbcnt_lo_u32_b32 v81, -1, 0
	v_mbcnt_hi_u32_b32 v81, -1, v81
	s_nop 0
	v_lshlrev_b32_e32 v81, 2, v81
	v_xor_b32_e32 v81, 8, v81
	s_nop 1
	v_mov_b32_dpp v81, v80 quad_perm:[2,3,0,1] row_mask:0xf bank_mask:0xf
	v_add_f32_e32 v80, v80, v81
	v_mbcnt_lo_u32_b32 v81, -1, 0
	v_mbcnt_hi_u32_b32 v81, -1, v81
	s_nop 0
	v_lshlrev_b32_e32 v81, 2, v81
	v_xor_b32_e32 v81, 16, v81
	s_nop 1
	v_mov_b32_dpp v81, v80 row_shl:4 row_mask:0xf bank_mask:0x5
	v_mov_b32_dpp v81, v80 row_shr:4 row_mask:0xf bank_mask:0xa
	v_add_f32_e32 v81, v80, v81
	v_mbcnt_lo_u32_b32 v80, -1, 0
	v_mbcnt_hi_u32_b32 v80, -1, v80
	s_nop 0
	v_lshlrev_b32_e32 v80, 2, v80
	v_xor_b32_e32 v80, 32, v80
	s_nop 1
	v_mov_b32_dpp v82, v81 row_ror:8 row_mask:0xf bank_mask:0xf
	v_lshl_add_u32 v80, v70, 2, 16
	s_and_saveexec_b64 s[8:9], vcc
	s_cbranch_execz .LBB0_492
	s_waitcnt lgkmcnt(0)
	v_add_f32_e32 v81, v81, v82
	v_mul_f32_e32 v81, 0x3db504f3, v81
	ds_write_b32 v80, v81
.LBB0_492:
	s_or_b64 exec, exec, s[8:9]
	s_waitcnt lgkmcnt(0)
	v_add_u32_e32 v82, 4, v70
	v_ashrrev_i32_e32 v83, 31, v82
	v_lshlrev_b64 v[82:83], 11, v[82:83]
	v_lshl_add_u64 v[86:87], v[68:69], 0, v[82:83]
	s_nop 0
	v_mbcnt_lo_u32_b32 v81, -1, 0
	v_mbcnt_hi_u32_b32 v81, -1, v81
	s_waitcnt vmcnt(12)
	v_mul_f32_e32 v83, v165, v79
	v_fmac_f32_e32 v83, v164, v71
	v_fmac_f32_e32 v83, v166, v73
	v_fmac_f32_e32 v83, v167, v74
	v_fmac_f32_e32 v83, v168, v75
	v_fmac_f32_e32 v83, v169, v76
	v_lshlrev_b32_e32 v81, 2, v81
	v_fmac_f32_e32 v83, v170, v77
	v_xor_b32_e32 v81, 4, v81
	v_fmac_f32_e32 v83, v171, v78
	s_nop 1
	v_mov_b32_dpp v81, v83 quad_perm:[1,0,3,2] row_mask:0xf bank_mask:0xf
	v_mbcnt_lo_u32_b32 v82, -1, 0
	v_mbcnt_hi_u32_b32 v82, -1, v82
	v_add_f32_e32 v81, v83, v81
	v_lshlrev_b32_e32 v82, 2, v82
	v_xor_b32_e32 v82, 8, v82
	s_nop 1
	v_mov_b32_dpp v82, v81 quad_perm:[2,3,0,1] row_mask:0xf bank_mask:0xf
	v_mbcnt_lo_u32_b32 v83, -1, 0
	v_mbcnt_hi_u32_b32 v83, -1, v83
	v_add_f32_e32 v81, v81, v82
	v_lshlrev_b32_e32 v83, 2, v83
	v_xor_b32_e32 v83, 16, v83
	s_nop 1
	v_mov_b32_dpp v82, v81 row_shl:4 row_mask:0xf bank_mask:0x5
	v_mov_b32_dpp v82, v81 row_shr:4 row_mask:0xf bank_mask:0xa
	v_mbcnt_lo_u32_b32 v83, -1, 0
	v_mbcnt_hi_u32_b32 v83, -1, v83
	v_add_f32_e32 v81, v81, v82
	v_lshlrev_b32_e32 v83, 2, v83
	v_xor_b32_e32 v82, 32, v83
	s_nop 1
	v_mov_b32_dpp v82, v81 row_ror:8 row_mask:0xf bank_mask:0xf
	s_and_saveexec_b64 s[8:9], vcc
	s_cbranch_execz .LBB0_494
	s_waitcnt lgkmcnt(0)
	v_add_f32_e32 v81, v81, v82
	v_mul_f32_e32 v81, 0x3db504f3, v81
	ds_write_b32 v80, v81 offset:16
.LBB0_494:
	s_or_b64 exec, exec, s[8:9]
	s_waitcnt lgkmcnt(0)
	v_add_u32_e32 v82, 8, v70
	v_ashrrev_i32_e32 v83, 31, v82
	v_lshlrev_b64 v[82:83], 11, v[82:83]
	v_lshl_add_u64 v[86:87], v[68:69], 0, v[82:83]
	s_nop 0
	v_mbcnt_lo_u32_b32 v81, -1, 0
	v_mbcnt_hi_u32_b32 v81, -1, v81
	s_waitcnt vmcnt(10)
	v_mul_f32_e32 v83, v173, v79
	v_fmac_f32_e32 v83, v172, v71
	v_fmac_f32_e32 v83, v174, v73
	v_fmac_f32_e32 v83, v175, v74
	v_fmac_f32_e32 v83, v176, v75
	v_fmac_f32_e32 v83, v177, v76
	v_lshlrev_b32_e32 v81, 2, v81
	v_fmac_f32_e32 v83, v178, v77
	v_xor_b32_e32 v81, 4, v81
	v_fmac_f32_e32 v83, v179, v78
	s_nop 1
	v_mov_b32_dpp v81, v83 quad_perm:[1,0,3,2] row_mask:0xf bank_mask:0xf
	v_mbcnt_lo_u32_b32 v82, -1, 0
	v_mbcnt_hi_u32_b32 v82, -1, v82
	v_add_f32_e32 v81, v83, v81
	v_lshlrev_b32_e32 v82, 2, v82
	v_xor_b32_e32 v82, 8, v82
	s_nop 1
	v_mov_b32_dpp v82, v81 quad_perm:[2,3,0,1] row_mask:0xf bank_mask:0xf
	v_mbcnt_lo_u32_b32 v83, -1, 0
	v_mbcnt_hi_u32_b32 v83, -1, v83
	v_add_f32_e32 v81, v81, v82
	v_lshlrev_b32_e32 v83, 2, v83
	v_xor_b32_e32 v83, 16, v83
	s_nop 1
	v_mov_b32_dpp v82, v81 row_shl:4 row_mask:0xf bank_mask:0x5
	v_mov_b32_dpp v82, v81 row_shr:4 row_mask:0xf bank_mask:0xa
	v_mbcnt_lo_u32_b32 v83, -1, 0
	v_mbcnt_hi_u32_b32 v83, -1, v83
	v_add_f32_e32 v81, v81, v82
	v_lshlrev_b32_e32 v83, 2, v83
	v_xor_b32_e32 v82, 32, v83
	s_nop 1
	v_mov_b32_dpp v82, v81 row_ror:8 row_mask:0xf bank_mask:0xf
	s_and_saveexec_b64 s[8:9], vcc
	s_cbranch_execz .LBB0_496
	s_waitcnt lgkmcnt(0)
	v_add_f32_e32 v81, v81, v82
	v_mul_f32_e32 v81, 0x3db504f3, v81
	ds_write_b32 v80, v81 offset:32
; __device__ __forceinline__ float shfl_xor_f(float v, int mask) { const int l = lane_fresh(); return __int_as_float(__builtin_amdgcn_ds_bpermute((l ^ mask) << 2, __float_as_int(v))); }
; __device__ __forceinline__ void attn_sample_item(const Params& p, int item, const int wv) {
;     ...
;     for (int it = 0; it < 8; ++it) {
;       const int mm = wid * 32 + it * 4 + ksub;
;       f32x4 k0 = *(const f32x4*)(Kc + (size_t)mm * 512 + dch * 8), k1 = *(const f32x4*)(Kc + (size_t)mm * 512 + dch * 8 + 4);
;       float d = q[0] * k0[0] + q[1] * k0[1] + q[2] * k0[2] + q[3] * k0[3] + q[4] * k1[0] + q[5] * k1[1] + q[6] * k1[2] + q[7] * k1[3];
;       d += shfl_xor_f(d, 1); d += shfl_xor_f(d, 2); d += shfl_xor_f(d, 4); d += shfl_xor_f(d, 8);
;       if (dch == 0) sc_l[mm] = d * 0.08838834764831845f;
;     }
.LBB0_496:
	s_or_b64 exec, exec, s[8:9]
	s_waitcnt lgkmcnt(0)
	v_add_u32_e32 v82, 12, v70
	v_ashrrev_i32_e32 v83, 31, v82
	v_lshlrev_b64 v[82:83], 11, v[82:83]
	v_lshl_add_u64 v[86:87], v[68:69], 0, v[82:83]
	s_nop 0
	v_mbcnt_lo_u32_b32 v81, -1, 0
	v_mbcnt_hi_u32_b32 v81, -1, v81
	s_waitcnt vmcnt(8)
	v_mul_f32_e32 v83, v181, v79
	v_fmac_f32_e32 v83, v180, v71
	v_fmac_f32_e32 v83, v182, v73
	v_fmac_f32_e32 v83, v183, v74
	v_fmac_f32_e32 v83, v184, v75
	v_fmac_f32_e32 v83, v185, v76
	v_lshlrev_b32_e32 v81, 2, v81
	v_fmac_f32_e32 v83, v186, v77
	v_xor_b32_e32 v81, 4, v81
	v_fmac_f32_e32 v83, v187, v78
	s_nop 1
	v_mov_b32_dpp v81, v83 quad_perm:[1,0,3,2] row_mask:0xf bank_mask:0xf
	v_mbcnt_lo_u32_b32 v82, -1, 0
	v_mbcnt_hi_u32_b32 v82, -1, v82
	v_add_f32_e32 v81, v83, v81
	v_lshlrev_b32_e32 v82, 2, v82
	v_xor_b32_e32 v82, 8, v82
	s_nop 1
	v_mov_b32_dpp v82, v81 quad_perm:[2,3,0,1] row_mask:0xf bank_mask:0xf
	v_mbcnt_lo_u32_b32 v83, -1, 0
	v_mbcnt_hi_u32_b32 v83, -1, v83
	v_add_f32_e32 v81, v81, v82
	v_lshlrev_b32_e32 v83, 2, v83
	v_xor_b32_e32 v83, 16, v83
	s_nop 1
	v_mov_b32_dpp v82, v81 row_shl:4 row_mask:0xf bank_mask:0x5
	v_mov_b32_dpp v82, v81 row_shr:4 row_mask:0xf bank_mask:0xa
	v_mbcnt_lo_u32_b32 v83, -1, 0
	v_mbcnt_hi_u32_b32 v83, -1, v83
	v_add_f32_e32 v81, v81, v82
	v_lshlrev_b32_e32 v83, 2, v83
	v_xor_b32_e32 v82, 32, v83
	s_nop 1
	v_mov_b32_dpp v82, v81 row_ror:8 row_mask:0xf bank_mask:0xf
	s_and_saveexec_b64 s[8:9], vcc
	s_cbranch_execz .LBB0_498
	s_waitcnt lgkmcnt(0)
	v_add_f32_e32 v81, v81, v82
	v_mul_f32_e32 v81, 0x3db504f3, v81
	ds_write_b32 v80, v81 offset:48
.LBB0_498:
	s_or_b64 exec, exec, s[8:9]
	s_waitcnt lgkmcnt(0)
	v_add_u32_e32 v82, 16, v70
	v_ashrrev_i32_e32 v83, 31, v82
	v_lshlrev_b64 v[82:83], 11, v[82:83]
	v_lshl_add_u64 v[86:87], v[68:69], 0, v[82:83]
	s_nop 0
	v_mbcnt_lo_u32_b32 v81, -1, 0
	v_mbcnt_hi_u32_b32 v81, -1, v81
	s_waitcnt vmcnt(6)
	v_mul_f32_e32 v83, v189, v79
	v_fmac_f32_e32 v83, v188, v71
	v_fmac_f32_e32 v83, v190, v73
	v_fmac_f32_e32 v83, v191, v74
	v_fmac_f32_e32 v83, v192, v75
	v_fmac_f32_e32 v83, v193, v76
	v_lshlrev_b32_e32 v81, 2, v81
	v_fmac_f32_e32 v83, v194, v77
	v_xor_b32_e32 v81, 4, v81
	v_fmac_f32_e32 v83, v195, v78
	s_nop 1
	v_mov_b32_dpp v81, v83 quad_perm:[1,0,3,2] row_mask:0xf bank_mask:0xf
	v_mbcnt_lo_u32_b32 v82, -1, 0
	v_mbcnt_hi_u32_b32 v82, -1, v82
	v_add_f32_e32 v81, v83, v81
	v_lshlrev_b32_e32 v82, 2, v82
	v_xor_b32_e32 v82, 8, v82
	s_nop 1
	v_mov_b32_dpp v82, v81 quad_perm:[2,3,0,1] row_mask:0xf bank_mask:0xf
	v_mbcnt_lo_u32_b32 v83, -1, 0
	v_mbcnt_hi_u32_b32 v83, -1, v83
	v_add_f32_e32 v81, v81, v82
	v_lshlrev_b32_e32 v83, 2, v83
	v_xor_b32_e32 v83, 16, v83
	s_nop 1
	v_mov_b32_dpp v82, v81 row_shl:4 row_mask:0xf bank_mask:0x5
	v_mov_b32_dpp v82, v81 row_shr:4 row_mask:0xf bank_mask:0xa
	v_mbcnt_lo_u32_b32 v83, -1, 0
	v_mbcnt_hi_u32_b32 v83, -1, v83
	v_add_f32_e32 v81, v81, v82
	v_lshlrev_b32_e32 v83, 2, v83
	v_xor_b32_e32 v82, 32, v83
	s_nop 1
	v_mov_b32_dpp v82, v81 row_ror:8 row_mask:0xf bank_mask:0xf
	s_and_saveexec_b64 s[8:9], vcc
	s_cbranch_execz .LBB0_500
	s_waitcnt lgkmcnt(0)
	v_add_f32_e32 v81, v81, v82
	v_mul_f32_e32 v81, 0x3db504f3, v81
	ds_write_b32 v80, v81 offset:64
.LBB0_500:
	s_or_b64 exec, exec, s[8:9]
	s_waitcnt lgkmcnt(0)
	v_add_u32_e32 v82, 20, v70
	v_ashrrev_i32_e32 v83, 31, v82
	v_lshlrev_b64 v[82:83], 11, v[82:83]
	v_lshl_add_u64 v[86:87], v[68:69], 0, v[82:83]
	s_nop 0
	v_mbcnt_lo_u32_b32 v81, -1, 0
	v_mbcnt_hi_u32_b32 v81, -1, v81
	s_waitcnt vmcnt(4)
	v_mul_f32_e32 v83, v197, v79
	v_fmac_f32_e32 v83, v196, v71
	v_fmac_f32_e32 v83, v198, v73
	v_fmac_f32_e32 v83, v199, v74
	v_fmac_f32_e32 v83, v200, v75
	v_fmac_f32_e32 v83, v201, v76
	v_lshlrev_b32_e32 v81, 2, v81
	v_fmac_f32_e32 v83, v202, v77
	v_xor_b32_e32 v81, 4, v81
	v_fmac_f32_e32 v83, v203, v78
	s_nop 1
	v_mov_b32_dpp v81, v83 quad_perm:[1,0,3,2] row_mask:0xf bank_mask:0xf
	v_mbcnt_lo_u32_b32 v82, -1, 0
	v_mbcnt_hi_u32_b32 v82, -1, v82
	v_add_f32_e32 v81, v83, v81
	v_lshlrev_b32_e32 v82, 2, v82
	v_xor_b32_e32 v82, 8, v82
	s_nop 1
	v_mov_b32_dpp v82, v81 quad_perm:[2,3,0,1] row_mask:0xf bank_mask:0xf
	v_mbcnt_lo_u32_b32 v83, -1, 0
	v_mbcnt_hi_u32_b32 v83, -1, v83
	v_add_f32_e32 v81, v81, v82
	v_lshlrev_b32_e32 v83, 2, v83
	v_xor_b32_e32 v83, 16, v83
	s_nop 1
	v_mov_b32_dpp v82, v81 row_shl:4 row_mask:0xf bank_mask:0x5
	v_mov_b32_dpp v82, v81 row_shr:4 row_mask:0xf bank_mask:0xa
	v_mbcnt_lo_u32_b32 v83, -1, 0
	v_mbcnt_hi_u32_b32 v83, -1, v83
	v_add_f32_e32 v81, v81, v82
	v_lshlrev_b32_e32 v83, 2, v83
	v_xor_b32_e32 v82, 32, v83
	s_nop 1
	v_mov_b32_dpp v82, v81 row_ror:8 row_mask:0xf bank_mask:0xf
	s_and_saveexec_b64 s[8:9], vcc
	s_cbranch_execz .LBB0_502
	s_waitcnt lgkmcnt(0)
	v_add_f32_e32 v81, v81, v82
	v_mul_f32_e32 v81, 0x3db504f3, v81
	ds_write_b32 v80, v81 offset:80
.LBB0_502:
	s_or_b64 exec, exec, s[8:9]
	s_waitcnt lgkmcnt(0)
	v_add_u32_e32 v82, 24, v70
	v_ashrrev_i32_e32 v83, 31, v82
	v_lshlrev_b64 v[82:83], 11, v[82:83]
	v_lshl_add_u64 v[86:87], v[68:69], 0, v[82:83]
	s_nop 0
	v_mbcnt_lo_u32_b32 v81, -1, 0
	v_mbcnt_hi_u32_b32 v81, -1, v81
	s_waitcnt vmcnt(2)
	v_mul_f32_e32 v83, v205, v79
	v_fmac_f32_e32 v83, v204, v71
	v_fmac_f32_e32 v83, v206, v73
	v_fmac_f32_e32 v83, v207, v74
	v_fmac_f32_e32 v83, v208, v75
	v_fmac_f32_e32 v83, v209, v76
	v_lshlrev_b32_e32 v81, 2, v81
	v_fmac_f32_e32 v83, v210, v77
	v_xor_b32_e32 v81, 4, v81
	v_fmac_f32_e32 v83, v211, v78
	s_nop 1
	v_mov_b32_dpp v81, v83 quad_perm:[1,0,3,2] row_mask:0xf bank_mask:0xf
	v_mbcnt_lo_u32_b32 v82, -1, 0
	v_mbcnt_hi_u32_b32 v82, -1, v82
	v_add_f32_e32 v81, v83, v81
	v_lshlrev_b32_e32 v82, 2, v82
	v_xor_b32_e32 v82, 8, v82
	s_nop 1
	v_mov_b32_dpp v82, v81 quad_perm:[2,3,0,1] row_mask:0xf bank_mask:0xf
	v_mbcnt_lo_u32_b32 v83, -1, 0
	v_mbcnt_hi_u32_b32 v83, -1, v83
	v_add_f32_e32 v81, v81, v82
	v_lshlrev_b32_e32 v83, 2, v83
	v_xor_b32_e32 v83, 16, v83
	s_nop 1
	v_mov_b32_dpp v82, v81 row_shl:4 row_mask:0xf bank_mask:0x5
	v_mov_b32_dpp v82, v81 row_shr:4 row_mask:0xf bank_mask:0xa
	v_mbcnt_lo_u32_b32 v83, -1, 0
	v_mbcnt_hi_u32_b32 v83, -1, v83
	v_add_f32_e32 v81, v81, v82
	v_lshlrev_b32_e32 v83, 2, v83
	v_xor_b32_e32 v82, 32, v83
	s_nop 1
	v_mov_b32_dpp v82, v81 row_ror:8 row_mask:0xf bank_mask:0xf
	s_and_saveexec_b64 s[8:9], vcc
	s_cbranch_execz .LBB0_504
	s_waitcnt lgkmcnt(0)
	v_add_f32_e32 v81, v81, v82
	v_mul_f32_e32 v81, 0x3db504f3, v81
	ds_write_b32 v80, v81 offset:96
; __device__ __forceinline__ float shfl_xor_f(float v, int mask) { const int l = lane_fresh(); return __int_as_float(__builtin_amdgcn_ds_bpermute((l ^ mask) << 2, __float_as_int(v))); }
; __device__ __forceinline__ void attn_sample_item(const Params& p, int item, const int wv) {
;     ...
;     for (int it = 0; it < 8; ++it) {
;       const int mm = wid * 32 + it * 4 + ksub;
;       f32x4 k0 = *(const f32x4*)(Kc + (size_t)mm * 512 + dch * 8), k1 = *(const f32x4*)(Kc + (size_t)mm * 512 + dch * 8 + 4);
;       float d = q[0] * k0[0] + q[1] * k0[1] + q[2] * k0[2] + q[3] * k0[3] + q[4] * k1[0] + q[5] * k1[1] + q[6] * k1[2] + q[7] * k1[3];
;       d += shfl_xor_f(d, 1); d += shfl_xor_f(d, 2); d += shfl_xor_f(d, 4); d += shfl_xor_f(d, 8);
;       if (dch == 0) sc_l[mm] = d * 0.08838834764831845f;
;     }
;   }
;   __syncthreads();
;   float pv[4];
;   {
;     float mx = -1e30f;
; #pragma unroll
;     for (int i = 0; i < 4; ++i) { pv[i] = sc_l[lane + 64 * i]; mx = fmaxf(mx, pv[i]); }
;     mx = wave_max(mx);
;     float sum = 0.f;
; #pragma unroll
;     for (int i = 0; i < 4; ++i) { pv[i] = __expf(pv[i] - mx); sum += pv[i]; }
;     sum = wave_sum(sum);
;     const float inv = 1.f / sum;
; #pragma unroll
;     for (int i = 0; i < 4; ++i) pv[i] *= inv;
;   }
;   __syncthreads();
;   if (wid == 0) {
; #pragma unroll
;     for (int i = 0; i < 4; ++i) sc_l[lane + 64 * i] = pv[i];
;   }
.LBB0_504:
	s_or_b64 exec, exec, s[8:9]
	s_waitcnt lgkmcnt(0)
	v_add_u32_e32 v82, 28, v70
	v_ashrrev_i32_e32 v83, 31, v82
	v_lshlrev_b64 v[82:83], 11, v[82:83]
	v_lshl_add_u64 v[68:69], v[68:69], 0, v[82:83]
	v_mbcnt_lo_u32_b32 v68, -1, 0
	v_mbcnt_hi_u32_b32 v68, -1, v68
	v_mbcnt_lo_u32_b32 v70, -1, 0
	v_mbcnt_hi_u32_b32 v70, -1, v70
	s_waitcnt vmcnt(0)
	v_mul_f32_e32 v69, v213, v79
	v_fmac_f32_e32 v69, v212, v71
	v_fmac_f32_e32 v69, v214, v73
	v_fmac_f32_e32 v69, v215, v74
	v_fmac_f32_e32 v69, v216, v75
	v_fmac_f32_e32 v69, v217, v76
	v_lshlrev_b32_e32 v68, 2, v68
	v_fmac_f32_e32 v69, v218, v77
	v_xor_b32_e32 v68, 4, v68
	v_fmac_f32_e32 v69, v219, v78
	s_nop 1
	v_mov_b32_dpp v68, v69 quad_perm:[1,0,3,2] row_mask:0xf bank_mask:0xf
	v_lshlrev_b32_e32 v70, 2, v70
	v_xor_b32_e32 v70, 8, v70
	v_add_f32_e32 v68, v69, v68
	s_nop 1
	v_mov_b32_dpp v69, v68 quad_perm:[2,3,0,1] row_mask:0xf bank_mask:0xf
	v_mbcnt_lo_u32_b32 v70, -1, 0
	v_mbcnt_hi_u32_b32 v70, -1, v70
	v_add_f32_e32 v68, v68, v69
	v_lshlrev_b32_e32 v70, 2, v70
	v_xor_b32_e32 v70, 16, v70
	s_nop 1
	v_mov_b32_dpp v69, v68 row_shl:4 row_mask:0xf bank_mask:0x5
	v_mov_b32_dpp v69, v68 row_shr:4 row_mask:0xf bank_mask:0xa
	v_mbcnt_lo_u32_b32 v70, -1, 0
	v_mbcnt_hi_u32_b32 v70, -1, v70
	v_add_f32_e32 v68, v68, v69
	v_lshlrev_b32_e32 v70, 2, v70
	v_xor_b32_e32 v69, 32, v70
	s_nop 1
	v_mov_b32_dpp v69, v68 row_ror:8 row_mask:0xf bank_mask:0xf
	s_and_saveexec_b64 s[8:9], vcc
	s_cbranch_execz .LBB0_506
	s_waitcnt lgkmcnt(0)
	v_add_f32_e32 v68, v68, v69
	v_mul_f32_e32 v68, 0x3db504f3, v68
	ds_write_b32 v80, v68 offset:112
.LBB0_506:
	s_or_b64 exec, exec, s[8:9]
	v_lshl_add_u32 v68, v72, 2, 16
	s_waitcnt lgkmcnt(0)
	s_barrier
	ds_read2st64_b32 v[70:71], v68 offset1:1
	ds_read2st64_b32 v[72:73], v68 offset0:2 offset1:3
	v_mbcnt_lo_u32_b32 v74, -1, 0
	v_mbcnt_hi_u32_b32 v74, -1, v74
	v_mbcnt_lo_u32_b32 v75, -1, 0
	v_mbcnt_hi_u32_b32 v75, -1, v75
	v_readlane_b32 s8, v251, 58
	s_waitcnt lgkmcnt(1)
	v_max3_f32 v69, v70, s16, v71
	v_lshlrev_b32_e32 v74, 2, v74
	s_waitcnt lgkmcnt(0)
	v_max3_f32 v69, v69, v72, v73
	v_xor_b32_e32 v74, 0x80, v74
	ds_bpermute_b32 v74, v74, v69
	v_readlane_b32 s9, v251, 59
	s_and_b64 vcc, exec, s[8:9]
	s_waitcnt lgkmcnt(0)
	v_max_f32_e32 v74, v74, v74
	v_max_f32_e32 v69, v69, v74
	v_lshlrev_b32_e32 v74, 2, v75
	v_xor_b32_e32 v74, 64, v74
	ds_bpermute_b32 v74, v74, v69
	v_mbcnt_lo_u32_b32 v75, -1, 0
	v_mbcnt_hi_u32_b32 v75, -1, v75
	s_waitcnt lgkmcnt(0)
	v_max_f32_e32 v74, v74, v74
	v_lshlrev_b32_e32 v75, 2, v75
	v_max_f32_e32 v69, v69, v74
	v_xor_b32_e32 v74, 32, v75
	s_nop 1
	v_mov_b32_dpp v74, v69 row_ror:8 row_mask:0xf bank_mask:0xf
	v_mbcnt_lo_u32_b32 v75, -1, 0
	v_mbcnt_hi_u32_b32 v75, -1, v75
	v_max_f32_e32 v74, v74, v74
	v_lshlrev_b32_e32 v75, 2, v75
	v_xor_b32_e32 v75, 16, v75
	v_max_f32_e32 v69, v69, v74
	s_nop 1
	v_mov_b32_dpp v74, v69 row_shl:4 row_mask:0xf bank_mask:0x5
	v_mov_b32_dpp v74, v69 row_shr:4 row_mask:0xf bank_mask:0xa
	v_mbcnt_lo_u32_b32 v75, -1, 0
	v_mbcnt_hi_u32_b32 v75, -1, v75
	v_max_f32_e32 v74, v74, v74
	v_lshlrev_b32_e32 v75, 2, v75
	v_xor_b32_e32 v75, 8, v75
	v_max_f32_e32 v69, v69, v74
	s_nop 1
	v_mov_b32_dpp v74, v69 quad_perm:[2,3,0,1] row_mask:0xf bank_mask:0xf
	v_mbcnt_lo_u32_b32 v75, -1, 0
	v_mbcnt_hi_u32_b32 v75, -1, v75
	v_max_f32_e32 v74, v74, v74
	v_lshlrev_b32_e32 v75, 2, v75
	v_xor_b32_e32 v75, 4, v75
	v_max_f32_e32 v69, v69, v74
	s_nop 1
	v_mov_b32_dpp v74, v69 quad_perm:[1,0,3,2] row_mask:0xf bank_mask:0xf
	v_max_f32_e32 v74, v74, v74
	v_max_f32_e32 v69, v69, v74
	v_sub_f32_e32 v70, v70, v69
	v_sub_f32_e32 v71, v71, v69
	v_sub_f32_e32 v72, v72, v69
	v_sub_f32_e32 v69, v73, v69
	v_mul_f32_e32 v70, 0x3fb8aa3b, v70
	v_mul_f32_e32 v71, 0x3fb8aa3b, v71
	v_mul_f32_e32 v73, 0x3fb8aa3b, v69
	v_exp_f32_e32 v69, v70
	v_mul_f32_e32 v72, 0x3fb8aa3b, v72
	v_exp_f32_e32 v70, v71
	v_exp_f32_e32 v71, v72
	v_exp_f32_e32 v72, v73
	v_add_f32_e32 v73, 0, v69
	v_add_f32_e32 v73, v70, v73
	v_mbcnt_lo_u32_b32 v74, -1, 0
	v_mbcnt_hi_u32_b32 v74, -1, v74
	v_add_f32_e32 v73, v71, v73
	v_lshlrev_b32_e32 v74, 2, v74
	v_add_f32_e32 v73, v72, v73
	v_xor_b32_e32 v74, 0x80, v74
	ds_bpermute_b32 v74, v74, v73
	v_mbcnt_lo_u32_b32 v75, -1, 0
	v_mbcnt_hi_u32_b32 v75, -1, v75
	s_waitcnt lgkmcnt(0)
	v_add_f32_e32 v73, v73, v74
	v_lshlrev_b32_e32 v74, 2, v75
	v_xor_b32_e32 v74, 64, v74
	ds_bpermute_b32 v74, v74, v73
	v_mbcnt_lo_u32_b32 v75, -1, 0
	v_mbcnt_hi_u32_b32 v75, -1, v75
	s_waitcnt lgkmcnt(0)
	v_add_f32_e32 v73, v73, v74
	v_lshlrev_b32_e32 v75, 2, v75
	v_xor_b32_e32 v74, 32, v75
	s_nop 1
	v_mov_b32_dpp v74, v73 row_ror:8 row_mask:0xf bank_mask:0xf
	v_mbcnt_lo_u32_b32 v75, -1, 0
	v_mbcnt_hi_u32_b32 v75, -1, v75
	v_add_f32_e32 v73, v73, v74
	v_lshlrev_b32_e32 v75, 2, v75
	v_xor_b32_e32 v75, 16, v75
	s_nop 1
	v_mov_b32_dpp v74, v73 row_shl:4 row_mask:0xf bank_mask:0x5
	v_mov_b32_dpp v74, v73 row_shr:4 row_mask:0xf bank_mask:0xa
	v_mbcnt_lo_u32_b32 v75, -1, 0
	v_mbcnt_hi_u32_b32 v75, -1, v75
	v_add_f32_e32 v73, v73, v74
	v_lshlrev_b32_e32 v75, 2, v75
	v_xor_b32_e32 v75, 8, v75
	s_nop 1
	v_mov_b32_dpp v74, v73 quad_perm:[2,3,0,1] row_mask:0xf bank_mask:0xf
	v_mbcnt_lo_u32_b32 v75, -1, 0
	v_mbcnt_hi_u32_b32 v75, -1, v75
	v_lshlrev_b32_e32 v75, 2, v75
	s_barrier
	v_add_f32_e32 v73, v73, v74
	v_xor_b32_e32 v74, 4, v75
	s_nop 1
	v_mov_b32_dpp v74, v73 quad_perm:[1,0,3,2] row_mask:0xf bank_mask:0xf
	s_cbranch_vccnz .LBB0_508
	v_add_f32_e32 v73, v73, v74
	v_div_scale_f32 v74, s[8:9], v73, v73, 1.0
	v_rcp_f32_e32 v75, v74
	v_div_scale_f32 v76, vcc, 1.0, v73, 1.0
	v_fma_f32 v77, -v74, v75, 1.0
	v_fmac_f32_e32 v75, v77, v75
	v_mul_f32_e32 v77, v76, v75
	v_fma_f32 v78, -v74, v77, v76
	v_fmac_f32_e32 v77, v78, v75
	v_fma_f32 v74, -v74, v77, v76
	v_div_fmas_f32 v74, v74, v75, v77
	v_div_fixup_f32 v73, v74, v73, 1.0
	v_mul_f32_e32 v70, v70, v73
	v_mul_f32_e32 v69, v69, v73
	v_mul_f32_e32 v72, v72, v73
	v_mul_f32_e32 v71, v71, v73
	ds_write2st64_b32 v68, v69, v70 offset1:1
	ds_write2st64_b32 v68, v71, v72 offset0:2 offset1:3

; __device__ __forceinline__ float shfl_xor_f(float v, int mask) { const int l = lane_fresh(); return __int_as_float(__builtin_amdgcn_ds_bpermute((l ^ mask) << 2, __float_as_int(v))); }
; __device__ __forceinline__ void attn_sample_item(const Params& p, int item, const int wv) {
;     ...
;     for (int it = 0; it < 8; ++it) {
;       const int mm = wid * 32 + it * 4 + ksub;
;       f32x4 k0 = *(const f32x4*)(Kc + (size_t)mm * 512 + dch * 8), k1 = *(const f32x4*)(Kc + (size_t)mm * 512 + dch * 8 + 4);
;       float d = q[0] * k0[0] + q[1] * k0[1] + q[2] * k0[2] + q[3] * k0[3] + q[4] * k1[0] + q[5] * k1[1] + q[6] * k1[2] + q[7] * k1[3];
;       d += shfl_xor_f(d, 1); d += shfl_xor_f(d, 2); d += shfl_xor_f(d, 4); d += shfl_xor_f(d, 8);
;       if (dch == 0) sc_l[mm] = d * 0.08838834764831845f;
;     }
.LBB0_514:
	s_or_b64 exec, exec, s[8:9]
	v_add_u32_e32 v80, 4, v70
	s_waitcnt lgkmcnt(0)
	v_ashrrev_i32_e32 v81, 31, v80
	v_lshlrev_b64 v[80:81], 11, v[80:81]
	v_lshl_add_u64 v[84:85], v[68:69], 0, v[80:81]
	s_nop 0
	v_mbcnt_lo_u32_b32 v88, -1, 0
	v_mbcnt_hi_u32_b32 v88, -1, v88
	s_waitcnt vmcnt(12)
	v_mul_f32_e32 v81, v165, v78
	v_fmac_f32_e32 v81, v164, v67
	v_fmac_f32_e32 v81, v166, v71
	v_fmac_f32_e32 v81, v167, v73
	v_fmac_f32_e32 v81, v168, v74
	v_fmac_f32_e32 v81, v169, v75
	v_lshlrev_b32_e32 v88, 2, v88
	v_fmac_f32_e32 v81, v170, v76
	v_xor_b32_e32 v88, 4, v88
	v_fmac_f32_e32 v81, v171, v77
	s_nop 1
	v_mov_b32_dpp v80, v81 quad_perm:[1,0,3,2] row_mask:0xf bank_mask:0xf
	v_mbcnt_lo_u32_b32 v82, -1, 0
	v_mbcnt_hi_u32_b32 v82, -1, v82
	v_add_f32_e32 v80, v81, v80
	v_lshlrev_b32_e32 v82, 2, v82
	v_xor_b32_e32 v82, 8, v82
	s_nop 1
	v_mov_b32_dpp v81, v80 quad_perm:[2,3,0,1] row_mask:0xf bank_mask:0xf
	v_mbcnt_lo_u32_b32 v82, -1, 0
	v_mbcnt_hi_u32_b32 v82, -1, v82
	v_add_f32_e32 v80, v80, v81
	v_lshlrev_b32_e32 v82, 2, v82
	v_xor_b32_e32 v82, 16, v82
	s_nop 1
	v_mov_b32_dpp v81, v80 row_shl:4 row_mask:0xf bank_mask:0x5
	v_mov_b32_dpp v81, v80 row_shr:4 row_mask:0xf bank_mask:0xa
	v_mbcnt_lo_u32_b32 v82, -1, 0
	v_mbcnt_hi_u32_b32 v82, -1, v82
	v_add_f32_e32 v80, v80, v81
	v_lshlrev_b32_e32 v82, 2, v82
	v_xor_b32_e32 v81, 32, v82
	s_nop 1
	v_mov_b32_dpp v81, v80 row_ror:8 row_mask:0xf bank_mask:0xf
	s_and_saveexec_b64 s[8:9], vcc
	s_cbranch_execz .LBB0_516
	s_waitcnt lgkmcnt(0)
	v_add_f32_e32 v80, v80, v81
	v_mul_f32_e32 v80, 0x3db504f3, v80
	ds_write_b32 v79, v80 offset:16
.LBB0_516:
	s_or_b64 exec, exec, s[8:9]
	v_add_u32_e32 v80, 8, v70
	s_waitcnt lgkmcnt(0)
	v_ashrrev_i32_e32 v81, 31, v80
	v_lshlrev_b64 v[80:81], 11, v[80:81]
	v_lshl_add_u64 v[84:85], v[68:69], 0, v[80:81]
	s_nop 0
	v_mbcnt_lo_u32_b32 v88, -1, 0
	v_mbcnt_hi_u32_b32 v88, -1, v88
	s_waitcnt vmcnt(10)
	v_mul_f32_e32 v81, v173, v78
	v_fmac_f32_e32 v81, v172, v67
	v_fmac_f32_e32 v81, v174, v71
	v_fmac_f32_e32 v81, v175, v73
	v_fmac_f32_e32 v81, v176, v74
	v_fmac_f32_e32 v81, v177, v75
	v_lshlrev_b32_e32 v88, 2, v88
	v_fmac_f32_e32 v81, v178, v76
	v_xor_b32_e32 v88, 4, v88
	v_fmac_f32_e32 v81, v179, v77
	s_nop 1
	v_mov_b32_dpp v80, v81 quad_perm:[1,0,3,2] row_mask:0xf bank_mask:0xf
	v_mbcnt_lo_u32_b32 v82, -1, 0
	v_mbcnt_hi_u32_b32 v82, -1, v82
	v_add_f32_e32 v80, v81, v80
	v_lshlrev_b32_e32 v82, 2, v82
	v_xor_b32_e32 v82, 8, v82
	s_nop 1
	v_mov_b32_dpp v81, v80 quad_perm:[2,3,0,1] row_mask:0xf bank_mask:0xf
	v_mbcnt_lo_u32_b32 v82, -1, 0
	v_mbcnt_hi_u32_b32 v82, -1, v82
	v_add_f32_e32 v80, v80, v81
	v_lshlrev_b32_e32 v82, 2, v82
	v_xor_b32_e32 v82, 16, v82
	s_nop 1
	v_mov_b32_dpp v81, v80 row_shl:4 row_mask:0xf bank_mask:0x5
	v_mov_b32_dpp v81, v80 row_shr:4 row_mask:0xf bank_mask:0xa
	v_mbcnt_lo_u32_b32 v82, -1, 0
	v_mbcnt_hi_u32_b32 v82, -1, v82
	v_add_f32_e32 v80, v80, v81
	v_lshlrev_b32_e32 v82, 2, v82
	v_xor_b32_e32 v81, 32, v82
	s_nop 1
	v_mov_b32_dpp v81, v80 row_ror:8 row_mask:0xf bank_mask:0xf
	s_and_saveexec_b64 s[8:9], vcc
	s_cbranch_execz .LBB0_518
	s_waitcnt lgkmcnt(0)
	v_add_f32_e32 v80, v80, v81
	v_mul_f32_e32 v80, 0x3db504f3, v80
	ds_write_b32 v79, v80 offset:32
.LBB0_518:
	s_or_b64 exec, exec, s[8:9]
	v_add_u32_e32 v80, 12, v70
	s_waitcnt lgkmcnt(0)
	v_ashrrev_i32_e32 v81, 31, v80
	v_lshlrev_b64 v[80:81], 11, v[80:81]
	v_lshl_add_u64 v[84:85], v[68:69], 0, v[80:81]
	s_nop 0
	v_mbcnt_lo_u32_b32 v88, -1, 0
	v_mbcnt_hi_u32_b32 v88, -1, v88
	s_waitcnt vmcnt(8)
	v_mul_f32_e32 v81, v181, v78
	v_fmac_f32_e32 v81, v180, v67
	v_fmac_f32_e32 v81, v182, v71
	v_fmac_f32_e32 v81, v183, v73
	v_fmac_f32_e32 v81, v184, v74
	v_fmac_f32_e32 v81, v185, v75
	v_lshlrev_b32_e32 v88, 2, v88
	v_fmac_f32_e32 v81, v186, v76
	v_xor_b32_e32 v88, 4, v88
	v_fmac_f32_e32 v81, v187, v77
	s_nop 1
	v_mov_b32_dpp v80, v81 quad_perm:[1,0,3,2] row_mask:0xf bank_mask:0xf
	v_mbcnt_lo_u32_b32 v82, -1, 0
	v_mbcnt_hi_u32_b32 v82, -1, v82
	v_add_f32_e32 v80, v81, v80
	v_lshlrev_b32_e32 v82, 2, v82
	v_xor_b32_e32 v82, 8, v82
	s_nop 1
	v_mov_b32_dpp v81, v80 quad_perm:[2,3,0,1] row_mask:0xf bank_mask:0xf
	v_mbcnt_lo_u32_b32 v82, -1, 0
	v_mbcnt_hi_u32_b32 v82, -1, v82
	v_add_f32_e32 v80, v80, v81
	v_lshlrev_b32_e32 v82, 2, v82
	v_xor_b32_e32 v82, 16, v82
	s_nop 1
	v_mov_b32_dpp v81, v80 row_shl:4 row_mask:0xf bank_mask:0x5
	v_mov_b32_dpp v81, v80 row_shr:4 row_mask:0xf bank_mask:0xa
	v_mbcnt_lo_u32_b32 v82, -1, 0
	v_mbcnt_hi_u32_b32 v82, -1, v82
	v_add_f32_e32 v80, v80, v81
	v_lshlrev_b32_e32 v82, 2, v82
	v_xor_b32_e32 v81, 32, v82
	s_nop 1
	v_mov_b32_dpp v81, v80 row_ror:8 row_mask:0xf bank_mask:0xf
	s_and_saveexec_b64 s[8:9], vcc
	s_cbranch_execz .LBB0_520
	s_waitcnt lgkmcnt(0)
	v_add_f32_e32 v80, v80, v81
	v_mul_f32_e32 v80, 0x3db504f3, v80
	ds_write_b32 v79, v80 offset:48
.LBB0_520:
	s_or_b64 exec, exec, s[8:9]
	v_add_u32_e32 v80, 16, v70
	s_waitcnt lgkmcnt(0)
	v_ashrrev_i32_e32 v81, 31, v80
	v_lshlrev_b64 v[80:81], 11, v[80:81]
	v_lshl_add_u64 v[84:85], v[68:69], 0, v[80:81]
	s_nop 0
	v_mbcnt_lo_u32_b32 v88, -1, 0
	v_mbcnt_hi_u32_b32 v88, -1, v88
	s_waitcnt vmcnt(6)
	v_mul_f32_e32 v81, v189, v78
	v_fmac_f32_e32 v81, v188, v67
	v_fmac_f32_e32 v81, v190, v71
	v_fmac_f32_e32 v81, v191, v73
	v_fmac_f32_e32 v81, v192, v74
	v_fmac_f32_e32 v81, v193, v75
	v_lshlrev_b32_e32 v88, 2, v88
	v_fmac_f32_e32 v81, v194, v76
	v_xor_b32_e32 v88, 4, v88
	v_fmac_f32_e32 v81, v195, v77
	s_nop 1
	v_mov_b32_dpp v80, v81 quad_perm:[1,0,3,2] row_mask:0xf bank_mask:0xf
	v_mbcnt_lo_u32_b32 v82, -1, 0
	v_mbcnt_hi_u32_b32 v82, -1, v82
	v_add_f32_e32 v80, v81, v80
	v_lshlrev_b32_e32 v82, 2, v82
	v_xor_b32_e32 v82, 8, v82
	s_nop 1
	v_mov_b32_dpp v81, v80 quad_perm:[2,3,0,1] row_mask:0xf bank_mask:0xf
	v_mbcnt_lo_u32_b32 v82, -1, 0
	v_mbcnt_hi_u32_b32 v82, -1, v82
	v_add_f32_e32 v80, v80, v81
	v_lshlrev_b32_e32 v82, 2, v82
	v_xor_b32_e32 v82, 16, v82
	s_nop 1
	v_mov_b32_dpp v81, v80 row_shl:4 row_mask:0xf bank_mask:0x5
	v_mov_b32_dpp v81, v80 row_shr:4 row_mask:0xf bank_mask:0xa
	v_mbcnt_lo_u32_b32 v82, -1, 0
	v_mbcnt_hi_u32_b32 v82, -1, v82
	v_add_f32_e32 v80, v80, v81
	v_lshlrev_b32_e32 v82, 2, v82
	v_xor_b32_e32 v81, 32, v82
	s_nop 1
	v_mov_b32_dpp v81, v80 row_ror:8 row_mask:0xf bank_mask:0xf
	s_and_saveexec_b64 s[8:9], vcc
	s_cbranch_execz .LBB0_522
	s_waitcnt lgkmcnt(0)
	v_add_f32_e32 v80, v80, v81
	v_mul_f32_e32 v80, 0x3db504f3, v80
	ds_write_b32 v79, v80 offset:64
; __device__ __forceinline__ float shfl_xor_f(float v, int mask) { const int l = lane_fresh(); return __int_as_float(__builtin_amdgcn_ds_bpermute((l ^ mask) << 2, __float_as_int(v))); }
; __device__ __forceinline__ void attn_sample_item(const Params& p, int item, const int wv) {
;     ...
;     for (int it = 0; it < 8; ++it) {
;       const int mm = wid * 32 + it * 4 + ksub;
;       f32x4 k0 = *(const f32x4*)(Kc + (size_t)mm * 512 + dch * 8), k1 = *(const f32x4*)(Kc + (size_t)mm * 512 + dch * 8 + 4);
;       float d = q[0] * k0[0] + q[1] * k0[1] + q[2] * k0[2] + q[3] * k0[3] + q[4] * k1[0] + q[5] * k1[1] + q[6] * k1[2] + q[7] * k1[3];
;       d += shfl_xor_f(d, 1); d += shfl_xor_f(d, 2); d += shfl_xor_f(d, 4); d += shfl_xor_f(d, 8);
;       if (dch == 0) sc_l[mm] = d * 0.08838834764831845f;
;     }
.LBB0_522:
	s_or_b64 exec, exec, s[8:9]
	v_add_u32_e32 v80, 20, v70
	s_waitcnt lgkmcnt(0)
	v_ashrrev_i32_e32 v81, 31, v80
	v_lshlrev_b64 v[80:81], 11, v[80:81]
	v_lshl_add_u64 v[84:85], v[68:69], 0, v[80:81]
	s_nop 0
	v_mbcnt_lo_u32_b32 v88, -1, 0
	v_mbcnt_hi_u32_b32 v88, -1, v88
	s_waitcnt vmcnt(4)
	v_mul_f32_e32 v81, v197, v78
	v_fmac_f32_e32 v81, v196, v67
	v_fmac_f32_e32 v81, v198, v71
	v_fmac_f32_e32 v81, v199, v73
	v_fmac_f32_e32 v81, v200, v74
	v_fmac_f32_e32 v81, v201, v75
	v_lshlrev_b32_e32 v88, 2, v88
	v_fmac_f32_e32 v81, v202, v76
	v_xor_b32_e32 v88, 4, v88
	v_fmac_f32_e32 v81, v203, v77
	s_nop 1
	v_mov_b32_dpp v80, v81 quad_perm:[1,0,3,2] row_mask:0xf bank_mask:0xf
	v_mbcnt_lo_u32_b32 v82, -1, 0
	v_mbcnt_hi_u32_b32 v82, -1, v82
	v_add_f32_e32 v80, v81, v80
	v_lshlrev_b32_e32 v82, 2, v82
	v_xor_b32_e32 v82, 8, v82
	s_nop 1
	v_mov_b32_dpp v81, v80 quad_perm:[2,3,0,1] row_mask:0xf bank_mask:0xf
	v_mbcnt_lo_u32_b32 v82, -1, 0
	v_mbcnt_hi_u32_b32 v82, -1, v82
	v_add_f32_e32 v80, v80, v81
	v_lshlrev_b32_e32 v82, 2, v82
	v_xor_b32_e32 v82, 16, v82
	s_nop 1
	v_mov_b32_dpp v81, v80 row_shl:4 row_mask:0xf bank_mask:0x5
	v_mov_b32_dpp v81, v80 row_shr:4 row_mask:0xf bank_mask:0xa
	v_mbcnt_lo_u32_b32 v82, -1, 0
	v_mbcnt_hi_u32_b32 v82, -1, v82
	v_add_f32_e32 v80, v80, v81
	v_lshlrev_b32_e32 v82, 2, v82
	v_xor_b32_e32 v81, 32, v82
	s_nop 1
	v_mov_b32_dpp v81, v80 row_ror:8 row_mask:0xf bank_mask:0xf
	s_and_saveexec_b64 s[8:9], vcc
	s_cbranch_execz .LBB0_524
	s_waitcnt lgkmcnt(0)
	v_add_f32_e32 v80, v80, v81
	v_mul_f32_e32 v80, 0x3db504f3, v80
	ds_write_b32 v79, v80 offset:80
.LBB0_524:
	s_or_b64 exec, exec, s[8:9]
	v_add_u32_e32 v80, 24, v70
	s_waitcnt lgkmcnt(0)
	v_ashrrev_i32_e32 v81, 31, v80
	v_lshlrev_b64 v[80:81], 11, v[80:81]
	v_lshl_add_u64 v[84:85], v[68:69], 0, v[80:81]
	s_nop 0
	v_mbcnt_lo_u32_b32 v88, -1, 0
	v_mbcnt_hi_u32_b32 v88, -1, v88
	s_waitcnt vmcnt(2)
	v_mul_f32_e32 v81, v205, v78
	v_fmac_f32_e32 v81, v204, v67
	v_fmac_f32_e32 v81, v206, v71
	v_fmac_f32_e32 v81, v207, v73
	v_fmac_f32_e32 v81, v208, v74
	v_fmac_f32_e32 v81, v209, v75
	v_lshlrev_b32_e32 v88, 2, v88
	v_fmac_f32_e32 v81, v210, v76
	v_xor_b32_e32 v88, 4, v88
	v_fmac_f32_e32 v81, v211, v77
	s_nop 1
	v_mov_b32_dpp v80, v81 quad_perm:[1,0,3,2] row_mask:0xf bank_mask:0xf
	v_mbcnt_lo_u32_b32 v82, -1, 0
	v_mbcnt_hi_u32_b32 v82, -1, v82
	v_add_f32_e32 v80, v81, v80
	v_lshlrev_b32_e32 v82, 2, v82
	v_xor_b32_e32 v82, 8, v82
	s_nop 1
	v_mov_b32_dpp v81, v80 quad_perm:[2,3,0,1] row_mask:0xf bank_mask:0xf
	v_mbcnt_lo_u32_b32 v82, -1, 0
	v_mbcnt_hi_u32_b32 v82, -1, v82
	v_add_f32_e32 v80, v80, v81
	v_lshlrev_b32_e32 v82, 2, v82
	v_xor_b32_e32 v82, 16, v82
	s_nop 1
	v_mov_b32_dpp v81, v80 row_shl:4 row_mask:0xf bank_mask:0x5
	v_mov_b32_dpp v81, v80 row_shr:4 row_mask:0xf bank_mask:0xa
	v_mbcnt_lo_u32_b32 v82, -1, 0
	v_mbcnt_hi_u32_b32 v82, -1, v82
	v_add_f32_e32 v80, v80, v81
	v_lshlrev_b32_e32 v82, 2, v82
	v_xor_b32_e32 v81, 32, v82
	s_nop 1
	v_mov_b32_dpp v81, v80 row_ror:8 row_mask:0xf bank_mask:0xf
	s_and_saveexec_b64 s[8:9], vcc
	s_cbranch_execz .LBB0_526
	s_waitcnt lgkmcnt(0)
	v_add_f32_e32 v80, v80, v81
	v_mul_f32_e32 v80, 0x3db504f3, v80
	ds_write_b32 v79, v80 offset:96
.LBB0_526:
	s_or_b64 exec, exec, s[8:9]
	v_add_u32_e32 v80, 28, v70
	s_waitcnt lgkmcnt(0)
	v_ashrrev_i32_e32 v81, 31, v80
	v_lshlrev_b64 v[80:81], 11, v[80:81]
	v_lshl_add_u64 v[68:69], v[68:69], 0, v[80:81]
	v_mbcnt_lo_u32_b32 v68, -1, 0
	v_mbcnt_hi_u32_b32 v68, -1, v68
	s_waitcnt vmcnt(0)
	v_mul_f32_e32 v69, v213, v78
	v_fmac_f32_e32 v69, v212, v67
	v_fmac_f32_e32 v69, v214, v71
	v_fmac_f32_e32 v69, v215, v73
	v_fmac_f32_e32 v69, v216, v74
	v_fmac_f32_e32 v69, v217, v75
	v_lshlrev_b32_e32 v68, 2, v68
	v_fmac_f32_e32 v69, v218, v76
	v_xor_b32_e32 v68, 4, v68
	v_fmac_f32_e32 v69, v219, v77
	s_nop 1
	v_mov_b32_dpp v67, v69 quad_perm:[1,0,3,2] row_mask:0xf bank_mask:0xf
	v_mbcnt_lo_u32_b32 v68, -1, 0
	v_mbcnt_hi_u32_b32 v68, -1, v68
	v_add_f32_e32 v67, v69, v67
	v_lshlrev_b32_e32 v68, 2, v68
	v_xor_b32_e32 v68, 8, v68
	s_nop 1
	v_mov_b32_dpp v68, v67 quad_perm:[2,3,0,1] row_mask:0xf bank_mask:0xf
	v_mbcnt_lo_u32_b32 v69, -1, 0
	v_mbcnt_hi_u32_b32 v69, -1, v69
	v_add_f32_e32 v67, v67, v68
	v_lshlrev_b32_e32 v69, 2, v69
	v_xor_b32_e32 v69, 16, v69
	s_nop 1
	v_mov_b32_dpp v68, v67 row_shl:4 row_mask:0xf bank_mask:0x5
	v_mov_b32_dpp v68, v67 row_shr:4 row_mask:0xf bank_mask:0xa
	v_mbcnt_lo_u32_b32 v69, -1, 0
	v_mbcnt_hi_u32_b32 v69, -1, v69
	v_add_f32_e32 v67, v67, v68
	v_lshlrev_b32_e32 v69, 2, v69
	v_xor_b32_e32 v68, 32, v69
	s_nop 1
	v_mov_b32_dpp v68, v67 row_ror:8 row_mask:0xf bank_mask:0xf
	s_and_saveexec_b64 s[8:9], vcc
	s_cbranch_execz .LBB0_528
	s_waitcnt lgkmcnt(0)
	v_add_f32_e32 v67, v67, v68
	v_mul_f32_e32 v67, 0x3db504f3, v67
	ds_write_b32 v79, v67 offset:112
; __device__ __forceinline__ void attn_sample_item(const Params& p, int item, const int wv) {
;     ...
;   float pv[4];
;   {
;     float mx = -1e30f;
; #pragma unroll
;     for (int i = 0; i < 4; ++i) { pv[i] = sc_l[lane + 64 * i]; mx = fmaxf(mx, pv[i]); }
;     mx = wave_max(mx);
;     float sum = 0.f;
; #pragma unroll
;     for (int i = 0; i < 4; ++i) { pv[i] = __expf(pv[i] - mx); sum += pv[i]; }
;     sum = wave_sum(sum);
;     const float inv = 1.f / sum;
; #pragma unroll
;     for (int i = 0; i < 4; ++i) pv[i] *= inv;
;   }
;   __syncthreads();
;   if (wid == 0) {
; #pragma unroll
;     for (int i = 0; i < 4; ++i) sc_l[lane + 64 * i] = pv[i];
;   }
.LBB0_528:
	s_or_b64 exec, exec, s[8:9]
	v_lshl_add_u32 v67, v72, 2, 16
	s_waitcnt lgkmcnt(0)
	s_barrier
	ds_read2st64_b32 v[68:69], v67 offset1:1
	ds_read2st64_b32 v[70:71], v67 offset0:2 offset1:3
	s_mov_b32 s7, 0xf149f2ca
	v_mbcnt_lo_u32_b32 v73, -1, 0
	v_mbcnt_hi_u32_b32 v73, -1, v73
	v_readlane_b32 s8, v251, 58
	s_waitcnt lgkmcnt(1)
	v_max3_f32 v72, v68, s7, v69
	v_lshlrev_b32_e32 v73, 2, v73
	s_waitcnt lgkmcnt(0)
	v_max3_f32 v72, v72, v70, v71
	v_xor_b32_e32 v73, 0x80, v73
	ds_bpermute_b32 v73, v73, v72
	v_readlane_b32 s9, v251, 59
	s_movk_i32 s7, 0x80
	s_and_b64 vcc, exec, s[8:9]
	s_waitcnt lgkmcnt(0)
	v_max_f32_e32 v73, v73, v73
	v_max_f32_e32 v72, v72, v73
	v_mbcnt_lo_u32_b32 v73, -1, 0
	v_mbcnt_hi_u32_b32 v73, -1, v73
	v_mbcnt_lo_u32_b32 v74, -1, 0
	v_mbcnt_hi_u32_b32 v74, -1, v74
	s_nop 0
	v_lshlrev_b32_e32 v73, 2, v73
	v_xor_b32_e32 v73, 64, v73
	ds_bpermute_b32 v73, v73, v72
	s_waitcnt lgkmcnt(0)
	v_max_f32_e32 v73, v73, v73
	v_max_f32_e32 v72, v72, v73
	v_lshlrev_b32_e32 v73, 2, v74
	v_xor_b32_e32 v73, 32, v73
	s_nop 1
	v_mov_b32_dpp v73, v72 row_ror:8 row_mask:0xf bank_mask:0xf
	v_mbcnt_lo_u32_b32 v74, -1, 0
	v_mbcnt_hi_u32_b32 v74, -1, v74
	v_max_f32_e32 v73, v73, v73
	v_lshlrev_b32_e32 v74, 2, v74
	v_max_f32_e32 v72, v72, v73
	v_xor_b32_e32 v73, 16, v74
	s_nop 1
	v_mov_b32_dpp v73, v72 row_shl:4 row_mask:0xf bank_mask:0x5
	v_mov_b32_dpp v73, v72 row_shr:4 row_mask:0xf bank_mask:0xa
	v_mbcnt_lo_u32_b32 v74, -1, 0
	v_mbcnt_hi_u32_b32 v74, -1, v74
	v_max_f32_e32 v73, v73, v73
	v_lshlrev_b32_e32 v74, 2, v74
	v_xor_b32_e32 v74, 8, v74
	v_max_f32_e32 v72, v72, v73
	s_nop 1
	v_mov_b32_dpp v73, v72 quad_perm:[2,3,0,1] row_mask:0xf bank_mask:0xf
	v_mbcnt_lo_u32_b32 v74, -1, 0
	v_mbcnt_hi_u32_b32 v74, -1, v74
	v_max_f32_e32 v73, v73, v73
	v_lshlrev_b32_e32 v74, 2, v74
	v_xor_b32_e32 v74, 4, v74
	v_max_f32_e32 v72, v72, v73
	s_nop 1
	v_mov_b32_dpp v73, v72 quad_perm:[1,0,3,2] row_mask:0xf bank_mask:0xf
	v_max_f32_e32 v73, v73, v73
	v_max_f32_e32 v72, v72, v73
	v_sub_f32_e32 v68, v68, v72
	v_sub_f32_e32 v69, v69, v72
	v_mul_f32_e32 v68, 0x3fb8aa3b, v68
	v_sub_f32_e32 v70, v70, v72
	v_mul_f32_e32 v69, 0x3fb8aa3b, v69
	v_exp_f32_e32 v68, v68
	v_mul_f32_e32 v70, 0x3fb8aa3b, v70
	v_exp_f32_e32 v69, v69
	v_sub_f32_e32 v71, v71, v72
	v_exp_f32_e32 v70, v70
	v_mul_f32_e32 v71, 0x3fb8aa3b, v71
	v_exp_f32_e32 v71, v71
	v_add_f32_e32 v72, 0, v68
	v_add_f32_e32 v72, v69, v72
	v_mbcnt_lo_u32_b32 v73, -1, 0
	v_mbcnt_hi_u32_b32 v73, -1, v73
	v_add_f32_e32 v72, v70, v72
	v_lshlrev_b32_e32 v73, 2, v73
	v_add_f32_e32 v72, v71, v72
	v_xor_b32_e32 v73, 0x80, v73
	ds_bpermute_b32 v73, v73, v72
	s_waitcnt lgkmcnt(0)
	v_add_f32_e32 v72, v72, v73
	v_mbcnt_lo_u32_b32 v73, -1, 0
	v_mbcnt_hi_u32_b32 v73, -1, v73
	v_mbcnt_lo_u32_b32 v74, -1, 0
	v_mbcnt_hi_u32_b32 v74, -1, v74
	s_nop 0
	v_lshlrev_b32_e32 v73, 2, v73
	v_xor_b32_e32 v73, 64, v73
	ds_bpermute_b32 v73, v73, v72
	s_waitcnt lgkmcnt(0)
	v_add_f32_e32 v72, v72, v73
	v_lshlrev_b32_e32 v73, 2, v74
	v_xor_b32_e32 v73, 32, v73
	s_nop 1
	v_mov_b32_dpp v73, v72 row_ror:8 row_mask:0xf bank_mask:0xf
	v_mbcnt_lo_u32_b32 v74, -1, 0
	v_mbcnt_hi_u32_b32 v74, -1, v74
	v_add_f32_e32 v72, v72, v73
	v_lshlrev_b32_e32 v74, 2, v74
	v_xor_b32_e32 v73, 16, v74
	s_nop 1
	v_mov_b32_dpp v73, v72 row_shl:4 row_mask:0xf bank_mask:0x5
	v_mov_b32_dpp v73, v72 row_shr:4 row_mask:0xf bank_mask:0xa
	v_mbcnt_lo_u32_b32 v74, -1, 0
	v_mbcnt_hi_u32_b32 v74, -1, v74
	v_add_f32_e32 v72, v72, v73
	v_lshlrev_b32_e32 v74, 2, v74
	v_xor_b32_e32 v74, 8, v74
	s_nop 1
	v_mov_b32_dpp v73, v72 quad_perm:[2,3,0,1] row_mask:0xf bank_mask:0xf
	v_mbcnt_lo_u32_b32 v74, -1, 0
	v_mbcnt_hi_u32_b32 v74, -1, v74
	v_lshlrev_b32_e32 v74, 2, v74
	s_barrier
	v_add_f32_e32 v72, v72, v73
	v_xor_b32_e32 v73, 4, v74
	s_nop 1
	v_mov_b32_dpp v73, v72 quad_perm:[1,0,3,2] row_mask:0xf bank_mask:0xf
	s_cbranch_vccnz .LBB0_530
	v_add_f32_e32 v72, v72, v73
	v_div_scale_f32 v73, s[8:9], v72, v72, 1.0
	v_rcp_f32_e32 v74, v73
	v_div_scale_f32 v75, vcc, 1.0, v72, 1.0
	v_fma_f32 v76, -v73, v74, 1.0
	v_fmac_f32_e32 v74, v76, v74
	v_mul_f32_e32 v76, v75, v74
	v_fma_f32 v77, -v73, v76, v75
	v_fmac_f32_e32 v76, v77, v74
	v_fma_f32 v73, -v73, v76, v75
	v_div_fmas_f32 v73, v73, v74, v76
	v_div_fixup_f32 v72, v73, v72, 1.0
	v_mul_f32_e32 v69, v69, v72
	v_mul_f32_e32 v68, v68, v72
	v_mul_f32_e32 v71, v71, v72
	v_mul_f32_e32 v70, v70, v72
	ds_write2st64_b32 v67, v68, v69 offset1:1
	ds_write2st64_b32 v67, v70, v71 offset0:2 offset1:3

; __device__ __forceinline__ float bflo(unsigned w) { return __uint_as_float(w << 16); }
; __device__ __forceinline__ float bfhi(unsigned w) { return __uint_as_float(w & 0xffff0000u); }
; __device__ __forceinline__ void gmlp_prompt_item(const Params& p, int item, const int wv) {
;     ...
;   __syncthreads();
;   {
;     const int row = tid >> 2, qq = tid & 3;
;     const u16* vrow = UV + (size_t)(t0 + row) * 1024 + 512;
;     float sm = 0.f, sq = 0.f;
; #pragma unroll
;     for (int i = 0; i < 16; ++i) {
;       u32x4 w = *(const u32x4*)(vrow + qq * 128 + i * 8);
;       float f[8] = {bflo(w.x), bfhi(w.x), bflo(w.y), bfhi(w.y), bflo(w.z), bfhi(w.z), bflo(w.w), bfhi(w.w)};
; #pragma unroll
;       for (int e = 0; e < 8; ++e) { sm += f[e]; sq += f[e] * f[e]; }
;     }
.LBB0_552:
	v_mbcnt_lo_u32_b32 v72, -1, 0
	v_mbcnt_hi_u32_b32 v72, -1, v72
	s_lshl_b32 s16, s57, 6
	v_add_u32_e32 v0, s82, v72
	s_and_b32 s16, s16, 0x3f80
	v_ashrrev_i32_e32 v13, 2, v0
	v_add_u32_e32 v0, s16, v13
	s_waitcnt lgkmcnt(0)
	v_ashrrev_i32_e32 v1, 31, v0
	v_and_b32_e32 v12, 3, v72
	v_lshlrev_b64 v[0:1], 11, v[0:1]
	v_lshl_add_u64 v[8:9], s[12:13], 0, v[0:1]
	v_lshlrev_b32_e32 v64, 8, v12
	v_lshl_add_u64 v[10:11], v[8:9], 0, v[64:65]
	s_barrier
	global_load_dwordx4 v[14:17], v[10:11], off offset:1024
	global_load_dwordx4 v[18:21], v[10:11], off offset:1040
	global_load_dwordx4 v[22:25], v[10:11], off offset:1056
	global_load_dwordx4 v[26:29], v[10:11], off offset:1072
	global_load_dwordx4 v[30:33], v[10:11], off offset:1088
	global_load_dwordx4 v[34:37], v[10:11], off offset:1104
	global_load_dwordx4 v[0:3], v[10:11], off offset:1136
	global_load_dwordx4 v[4:7], v[10:11], off offset:1120
	s_lshl_b32 s22, s57, 8
	s_and_b32 s22, s22, 0x100
	v_ashrrev_i32_e32 v70, 4, v72
	v_and_b32_e32 v71, 15, v72
	s_add_i32 s23, s22, s7
	s_waitcnt vmcnt(7)
	v_lshlrev_b32_e32 v38, 16, v14
	v_and_b32_e32 v39, 0xffff0000, v14
	v_add_f32_e32 v56, 0, v38
	v_lshlrev_b32_e32 v40, 16, v15
	v_mul_f32_e32 v14, v39, v39
	v_add_f32_e32 v39, v56, v39
	v_and_b32_e32 v15, 0xffff0000, v15
	v_fmac_f32_e32 v14, v38, v38
	v_add_f32_e32 v38, v39, v40
	v_lshlrev_b32_e32 v41, 16, v16
	v_fmac_f32_e32 v14, v40, v40
	v_add_f32_e32 v38, v38, v15
	v_and_b32_e32 v16, 0xffff0000, v16
	v_fmac_f32_e32 v14, v15, v15
	v_add_f32_e32 v15, v38, v41
	v_lshlrev_b32_e32 v42, 16, v17
	v_fmac_f32_e32 v14, v41, v41
	v_add_f32_e32 v15, v15, v16
	v_and_b32_e32 v17, 0xffff0000, v17
	v_fmac_f32_e32 v14, v16, v16
	v_add_f32_e32 v15, v15, v42
	s_waitcnt vmcnt(6)
	v_lshlrev_b32_e32 v43, 16, v18
	v_fmac_f32_e32 v14, v42, v42
	v_add_f32_e32 v15, v15, v17
	v_and_b32_e32 v18, 0xffff0000, v18
	v_fmac_f32_e32 v14, v17, v17
	v_add_f32_e32 v15, v15, v43
	v_lshlrev_b32_e32 v44, 16, v19
	v_fmac_f32_e32 v14, v43, v43
	v_add_f32_e32 v15, v15, v18
	v_and_b32_e32 v19, 0xffff0000, v19
	v_fmac_f32_e32 v14, v18, v18
	v_add_f32_e32 v15, v15, v44
	v_lshlrev_b32_e32 v45, 16, v20
	v_fmac_f32_e32 v14, v44, v44
	v_add_f32_e32 v15, v15, v19
	v_and_b32_e32 v20, 0xffff0000, v20
	v_fmac_f32_e32 v14, v19, v19
	v_add_f32_e32 v15, v15, v45
	v_lshlrev_b32_e32 v46, 16, v21
	v_fmac_f32_e32 v14, v45, v45
	v_add_f32_e32 v15, v15, v20
	v_and_b32_e32 v21, 0xffff0000, v21
	v_fmac_f32_e32 v14, v20, v20
	v_add_f32_e32 v15, v15, v46
	s_waitcnt vmcnt(5)
	v_lshlrev_b32_e32 v47, 16, v22
	v_fmac_f32_e32 v14, v46, v46
	v_add_f32_e32 v15, v15, v21
	v_and_b32_e32 v22, 0xffff0000, v22
	v_fmac_f32_e32 v14, v21, v21
	v_add_f32_e32 v15, v15, v47
	v_lshlrev_b32_e32 v48, 16, v23
	v_fmac_f32_e32 v14, v47, v47
	v_add_f32_e32 v15, v15, v22
	v_and_b32_e32 v23, 0xffff0000, v23
	v_fmac_f32_e32 v14, v22, v22
	v_add_f32_e32 v15, v15, v48
	v_lshlrev_b32_e32 v49, 16, v24
	v_fmac_f32_e32 v14, v48, v48
	v_add_f32_e32 v15, v15, v23
	v_and_b32_e32 v24, 0xffff0000, v24
	v_fmac_f32_e32 v14, v23, v23
	v_add_f32_e32 v15, v15, v49
	v_lshlrev_b32_e32 v50, 16, v25
	v_fmac_f32_e32 v14, v49, v49
	v_add_f32_e32 v15, v15, v24
	v_and_b32_e32 v25, 0xffff0000, v25
	v_fmac_f32_e32 v14, v24, v24
	v_add_f32_e32 v15, v15, v50
	s_waitcnt vmcnt(4)
	v_lshlrev_b32_e32 v51, 16, v26
	v_fmac_f32_e32 v14, v50, v50
	v_add_f32_e32 v15, v15, v25
	v_and_b32_e32 v26, 0xffff0000, v26
	v_fmac_f32_e32 v14, v25, v25
	v_add_f32_e32 v15, v15, v51
	v_lshlrev_b32_e32 v52, 16, v27
	v_fmac_f32_e32 v14, v51, v51
	v_add_f32_e32 v15, v15, v26
	v_and_b32_e32 v27, 0xffff0000, v27
	v_fmac_f32_e32 v14, v26, v26
	v_add_f32_e32 v15, v15, v52
	v_lshlrev_b32_e32 v53, 16, v28
	v_fmac_f32_e32 v14, v52, v52
	v_add_f32_e32 v15, v15, v27
	v_and_b32_e32 v28, 0xffff0000, v28
	v_fmac_f32_e32 v14, v27, v27
	v_add_f32_e32 v15, v15, v53
	v_lshlrev_b32_e32 v54, 16, v29
	v_fmac_f32_e32 v14, v53, v53
	v_add_f32_e32 v15, v15, v28
	v_and_b32_e32 v29, 0xffff0000, v29
	v_fmac_f32_e32 v14, v28, v28
	v_add_f32_e32 v15, v15, v54
	s_waitcnt vmcnt(3)
	v_lshlrev_b32_e32 v55, 16, v30
	v_fmac_f32_e32 v14, v54, v54
	v_add_f32_e32 v15, v15, v29
	v_and_b32_e32 v30, 0xffff0000, v30
	v_fmac_f32_e32 v14, v29, v29
	v_add_f32_e32 v15, v15, v55
	v_lshlrev_b32_e32 v16, 16, v31
	v_fmac_f32_e32 v14, v55, v55
	v_add_f32_e32 v15, v15, v30
	v_and_b32_e32 v17, 0xffff0000, v31
	v_fmac_f32_e32 v14, v30, v30
	v_add_f32_e32 v15, v15, v16
	v_lshlrev_b32_e32 v18, 16, v32
	v_fmac_f32_e32 v14, v16, v16
	v_add_f32_e32 v15, v15, v17
	v_and_b32_e32 v24, 0xffff0000, v32
	v_fmac_f32_e32 v14, v17, v17
	v_add_f32_e32 v15, v15, v18
	v_lshlrev_b32_e32 v25, 16, v33
	v_fmac_f32_e32 v14, v18, v18
	v_add_f32_e32 v15, v15, v24
	global_load_dwordx4 v[16:19], v[10:11], off offset:1168
	global_load_dwordx4 v[20:23], v[10:11], off offset:1152
	v_and_b32_e32 v26, 0xffff0000, v33
	v_fmac_f32_e32 v14, v24, v24
	v_add_f32_e32 v15, v15, v25
	v_fmac_f32_e32 v14, v25, v25
	v_add_f32_e32 v15, v15, v26
	s_waitcnt vmcnt(4)
	v_lshlrev_b32_e32 v24, 16, v34
	v_fmac_f32_e32 v14, v26, v26
	v_and_b32_e32 v25, 0xffff0000, v34
	v_add_f32_e32 v15, v15, v24
	v_lshlrev_b32_e32 v26, 16, v35
	v_fmac_f32_e32 v14, v24, v24
	v_add_f32_e32 v15, v15, v25
	v_and_b32_e32 v27, 0xffff0000, v35
	v_fmac_f32_e32 v14, v25, v25
	v_add_f32_e32 v15, v15, v26
	v_lshlrev_b32_e32 v28, 16, v36
	v_fmac_f32_e32 v14, v26, v26
	v_add_f32_e32 v15, v15, v27
	v_and_b32_e32 v29, 0xffff0000, v36
	v_fmac_f32_e32 v14, v27, v27
	v_add_f32_e32 v15, v15, v28
	v_lshlrev_b32_e32 v30, 16, v37
	v_fmac_f32_e32 v14, v28, v28
	v_add_f32_e32 v15, v15, v29
	v_and_b32_e32 v31, 0xffff0000, v37
	v_fmac_f32_e32 v14, v29, v29
	v_add_f32_e32 v15, v15, v30
	v_fmac_f32_e32 v14, v30, v30
	v_add_f32_e32 v15, v15, v31
	s_waitcnt vmcnt(2)
; __device__ __forceinline__ float bflo(unsigned w) { return __uint_as_float(w << 16); }
; __device__ __forceinline__ float bfhi(unsigned w) { return __uint_as_float(w & 0xffff0000u); }
; __device__ __forceinline__ void gmlp_prompt_item(const Params& p, int item, const int wv) {
;     ...
; #pragma unroll
;     for (int i = 0; i < 16; ++i) {
;       u32x4 w = *(const u32x4*)(vrow + qq * 128 + i * 8);
;       float f[8] = {bflo(w.x), bfhi(w.x), bflo(w.y), bfhi(w.y), bflo(w.z), bfhi(w.z), bflo(w.w), bfhi(w.w)};
; #pragma unroll
;       for (int e = 0; e < 8; ++e) { sm += f[e]; sq += f[e] * f[e]; }
;     }
	v_lshlrev_b32_e32 v24, 16, v4
	v_fmac_f32_e32 v14, v31, v31
	v_and_b32_e32 v4, 0xffff0000, v4
	v_lshlrev_b32_e32 v26, 16, v6
	v_and_b32_e32 v28, 0xffff0000, v6
	v_add_f32_e32 v6, v15, v24
	v_lshlrev_b32_e32 v25, 16, v5
	v_fmac_f32_e32 v14, v24, v24
	v_add_f32_e32 v6, v6, v4
	v_and_b32_e32 v5, 0xffff0000, v5
	v_fmac_f32_e32 v14, v4, v4
	v_add_f32_e32 v4, v6, v25
	v_fmac_f32_e32 v14, v25, v25
	v_add_f32_e32 v4, v4, v5
	v_fmac_f32_e32 v14, v5, v5
	v_add_f32_e32 v4, v4, v26
	v_lshlrev_b32_e32 v29, 16, v7
	v_and_b32_e32 v30, 0xffff0000, v7
	v_fmac_f32_e32 v14, v26, v26
	v_add_f32_e32 v15, v4, v28
	global_load_dwordx4 v[4:7], v[10:11], off offset:1200
	global_load_dwordx4 v[24:27], v[10:11], off offset:1184
	v_fmac_f32_e32 v14, v28, v28
	v_add_f32_e32 v15, v15, v29
	v_fmac_f32_e32 v14, v29, v29
	v_add_f32_e32 v15, v15, v30
	v_fmac_f32_e32 v14, v30, v30
	v_lshlrev_b32_e32 v28, 16, v0
	v_and_b32_e32 v0, 0xffff0000, v0
	v_add_f32_e32 v15, v15, v28
	v_fmac_f32_e32 v14, v28, v28
	v_lshlrev_b32_e32 v29, 16, v1
	v_add_f32_e32 v15, v15, v0
	v_fmac_f32_e32 v14, v0, v0
	v_and_b32_e32 v1, 0xffff0000, v1
	v_add_f32_e32 v0, v15, v29
	v_fmac_f32_e32 v14, v29, v29
	v_lshlrev_b32_e32 v30, 16, v2
	v_add_f32_e32 v0, v0, v1
	v_fmac_f32_e32 v14, v1, v1
	v_and_b32_e32 v2, 0xffff0000, v2
	v_add_f32_e32 v0, v0, v30
	v_fmac_f32_e32 v14, v30, v30
	v_lshlrev_b32_e32 v31, 16, v3
	v_add_f32_e32 v0, v0, v2
	v_fmac_f32_e32 v14, v2, v2
	v_and_b32_e32 v3, 0xffff0000, v3
	v_add_f32_e32 v0, v0, v31
	v_fmac_f32_e32 v14, v31, v31
	v_add_f32_e32 v0, v0, v3
	v_fmac_f32_e32 v14, v3, v3
	s_waitcnt vmcnt(2)
	v_lshlrev_b32_e32 v1, 16, v20
	v_and_b32_e32 v2, 0xffff0000, v20
	v_add_f32_e32 v0, v0, v1
	v_fmac_f32_e32 v14, v1, v1
	v_lshlrev_b32_e32 v3, 16, v21
	v_add_f32_e32 v0, v0, v2
	v_fmac_f32_e32 v14, v2, v2
	v_and_b32_e32 v15, 0xffff0000, v21
	v_add_f32_e32 v0, v0, v3
	v_fmac_f32_e32 v14, v3, v3
	v_lshlrev_b32_e32 v20, 16, v22
	v_add_f32_e32 v0, v0, v15
	v_fmac_f32_e32 v14, v15, v15
	v_and_b32_e32 v32, 0xffff0000, v22
	v_lshlrev_b32_e32 v33, 16, v23
	v_and_b32_e32 v34, 0xffff0000, v23
	v_add_f32_e32 v0, v0, v20
	v_fmac_f32_e32 v14, v20, v20
	global_load_dwordx4 v[20:23], v[10:11], off offset:1232
	global_load_dwordx4 v[28:31], v[10:11], off offset:1216
	v_add_f32_e32 v0, v0, v32
	v_fmac_f32_e32 v14, v32, v32
	v_add_f32_e32 v0, v0, v33
	v_fmac_f32_e32 v14, v33, v33
	v_add_f32_e32 v0, v0, v34
	v_lshlrev_b32_e32 v1, 16, v16
	v_fmac_f32_e32 v14, v34, v34
	v_and_b32_e32 v2, 0xffff0000, v16
	v_add_f32_e32 v0, v0, v1
	v_lshlrev_b32_e32 v3, 16, v17
	v_fmac_f32_e32 v14, v1, v1
	v_add_f32_e32 v0, v0, v2
	v_and_b32_e32 v15, 0xffff0000, v17
	v_fmac_f32_e32 v14, v2, v2
	v_add_f32_e32 v0, v0, v3
	v_lshlrev_b32_e32 v16, 16, v18
	v_fmac_f32_e32 v14, v3, v3
	v_add_f32_e32 v0, v0, v15
	v_and_b32_e32 v17, 0xffff0000, v18
	v_fmac_f32_e32 v14, v15, v15
	v_add_f32_e32 v0, v0, v16
	v_lshlrev_b32_e32 v18, 16, v19
	v_fmac_f32_e32 v14, v16, v16
	v_add_f32_e32 v0, v0, v17
	v_and_b32_e32 v19, 0xffff0000, v19
	v_fmac_f32_e32 v14, v17, v17
	v_add_f32_e32 v0, v0, v18
	v_fmac_f32_e32 v14, v18, v18
	v_add_f32_e32 v0, v0, v19
	v_fmac_f32_e32 v14, v19, v19
	s_waitcnt vmcnt(2)
	v_lshlrev_b32_e32 v1, 16, v24
	v_and_b32_e32 v2, 0xffff0000, v24
	v_add_f32_e32 v0, v0, v1
	v_lshlrev_b32_e32 v3, 16, v25
	v_fmac_f32_e32 v14, v1, v1
	v_add_f32_e32 v0, v0, v2
	v_and_b32_e32 v15, 0xffff0000, v25
	v_fmac_f32_e32 v14, v2, v2
	v_add_f32_e32 v0, v0, v3
	v_lshlrev_b32_e32 v24, 16, v26
	v_fmac_f32_e32 v14, v3, v3
	v_add_f32_e32 v0, v0, v15
	v_fmac_f32_e32 v14, v15, v15
	v_add_f32_e32 v15, v0, v24
	global_load_dwordx4 v[0:3], v[10:11], off offset:1264
	global_load_dwordx4 v[16:19], v[10:11], off offset:1248
	v_and_b32_e32 v25, 0xffff0000, v26
	v_lshlrev_b32_e32 v26, 16, v27
	v_fmac_f32_e32 v14, v24, v24
	v_add_f32_e32 v10, v15, v25
	v_and_b32_e32 v27, 0xffff0000, v27
	v_fmac_f32_e32 v14, v25, v25
	v_add_f32_e32 v10, v10, v26
	v_fmac_f32_e32 v14, v26, v26
	v_add_f32_e32 v10, v10, v27
	v_lshlrev_b32_e32 v11, 16, v4
	v_fmac_f32_e32 v14, v27, v27
	v_and_b32_e32 v4, 0xffff0000, v4
	v_add_f32_e32 v10, v10, v11
	v_lshlrev_b32_e32 v15, 16, v5
	v_fmac_f32_e32 v14, v11, v11
	v_add_f32_e32 v10, v10, v4
	v_and_b32_e32 v5, 0xffff0000, v5
	v_fmac_f32_e32 v14, v4, v4
	v_add_f32_e32 v4, v10, v15
	v_lshlrev_b32_e32 v24, 16, v6
	v_fmac_f32_e32 v14, v15, v15
	v_add_f32_e32 v4, v4, v5
	v_and_b32_e32 v6, 0xffff0000, v6
	v_fmac_f32_e32 v14, v5, v5
	v_add_f32_e32 v4, v4, v24
	v_lshlrev_b32_e32 v25, 16, v7
	v_fmac_f32_e32 v14, v24, v24
	v_add_f32_e32 v4, v4, v6
	v_and_b32_e32 v7, 0xffff0000, v7
	v_fmac_f32_e32 v14, v6, v6
	v_add_f32_e32 v4, v4, v25
	v_fmac_f32_e32 v14, v25, v25
	v_add_f32_e32 v4, v4, v7
	s_waitcnt vmcnt(2)
	v_lshlrev_b32_e32 v5, 16, v28
	v_fmac_f32_e32 v14, v7, v7
	v_and_b32_e32 v6, 0xffff0000, v28
	v_add_f32_e32 v4, v4, v5
	v_lshlrev_b32_e32 v7, 16, v29
	v_fmac_f32_e32 v14, v5, v5
	v_add_f32_e32 v4, v4, v6
	v_and_b32_e32 v10, 0xffff0000, v29
	v_fmac_f32_e32 v14, v6, v6
	v_add_f32_e32 v4, v4, v7
	v_lshlrev_b32_e32 v11, 16, v30
	v_fmac_f32_e32 v14, v7, v7
	v_add_f32_e32 v4, v4, v10
	v_and_b32_e32 v15, 0xffff0000, v30
	v_fmac_f32_e32 v14, v10, v10
	v_add_f32_e32 v4, v4, v11
	v_lshlrev_b32_e32 v24, 16, v31
	v_fmac_f32_e32 v14, v11, v11
	v_add_f32_e32 v4, v4, v15
	v_and_b32_e32 v25, 0xffff0000, v31
	v_fmac_f32_e32 v14, v15, v15
	v_add_f32_e32 v4, v4, v24
	v_fmac_f32_e32 v14, v24, v24
	v_add_f32_e32 v4, v4, v25
	v_lshlrev_b32_e32 v5, 16, v20
	v_fmac_f32_e32 v14, v25, v25
	v_and_b32_e32 v6, 0xffff0000, v20
	v_add_f32_e32 v4, v4, v5
	v_lshlrev_b32_e32 v7, 16, v21
	v_fmac_f32_e32 v14, v5, v5
	v_add_f32_e32 v4, v4, v6
	v_and_b32_e32 v10, 0xffff0000, v21
	v_fmac_f32_e32 v14, v6, v6
	v_add_f32_e32 v4, v4, v7
	v_lshlrev_b32_e32 v11, 16, v22
	v_fmac_f32_e32 v14, v7, v7
	v_add_f32_e32 v4, v4, v10
	v_and_b32_e32 v15, 0xffff0000, v22
	v_fmac_f32_e32 v14, v10, v10
	v_add_f32_e32 v4, v4, v11
	v_lshlrev_b32_e32 v20, 16, v23
	v_fmac_f32_e32 v14, v11, v11
	v_add_f32_e32 v4, v4, v15
	v_and_b32_e32 v21, 0xffff0000, v23
	v_fmac_f32_e32 v14, v15, v15
	v_add_f32_e32 v4, v4, v20
	v_fmac_f32_e32 v14, v20, v20
	v_add_f32_e32 v4, v4, v21
	s_waitcnt vmcnt(0)
; __device__ __forceinline__ u16 f2bf(float f) { return (u16)(cvt_pk(f, 0.f) & 0xffffu); }
; __device__ __forceinline__ float bflo(unsigned w) { return __uint_as_float(w << 16); }
; __device__ __forceinline__ float bfhi(unsigned w) { return __uint_as_float(w & 0xffff0000u); }
; __device__ __forceinline__ float shfl_xor_f(float v, int mask) { const int l = lane_fresh(); return __int_as_float(__builtin_amdgcn_ds_bpermute((l ^ mask) << 2, __float_as_int(v))); }
; __device__ __forceinline__ void gmlp_prompt_item(const Params& p, int item, const int wv) {
;     ...
;     sm += shfl_xor_f(sm, 1); sm += shfl_xor_f(sm, 2); sq += shfl_xor_f(sq, 1); sq += shfl_xor_f(sq, 2);
;     const float mean = sm * (1.f / 512.f), var = fmaxf(sq * (1.f / 512.f) - mean * mean, 0.f), rstd = rsqrtf(var + EPS);
; #pragma unroll
;     for (int i = 0; i < 8; ++i) {
;       const int cl = qq * 64 + i * 8, col = gp * 256 + cl;
;       u32x4 w = *(const u32x4*)(vrow + col);
;       float f[8] = {bflo(w.x), bfhi(w.x), bflo(w.y), bfhi(w.y), bflo(w.z), bfhi(w.z), bflo(w.w), bfhi(w.w)};
; #pragma unroll
;       for (int e = 0; e < 8; ++e) {
;         float vn = (f[e] - mean) * rstd * p.in[9][col + e] + p.in[10][col + e];
;         VnT[(cl + e) * 136 + row] = f2bf(vn);
;       }
	v_lshlrev_b32_e32 v5, 16, v16
	v_fmac_f32_e32 v14, v21, v21
	v_and_b32_e32 v6, 0xffff0000, v16
	v_add_f32_e32 v4, v4, v5
	v_lshlrev_b32_e32 v7, 16, v17
	v_fmac_f32_e32 v14, v5, v5
	v_add_f32_e32 v4, v4, v6
	v_fmac_f32_e32 v14, v6, v6
	v_add_f32_e32 v6, v4, v7
	v_and_b32_e32 v4, 0xffff0000, v17
	v_lshlrev_b32_e32 v5, 16, v18
	v_add_f32_e32 v10, v6, v4
	v_add_f32_e32 v11, v10, v5
	v_lshlrev_b32_e32 v10, 6, v12
	v_fmac_f32_e32 v14, v7, v7
	v_pk_mul_f32 v[6:7], v[4:5], v[4:5]
	v_or_b32_e32 v25, s22, v10
	v_add_f32_e32 v4, v6, v14
	v_lshlrev_b32_e32 v64, 1, v25
	v_add_f32_e32 v24, v7, v4
	v_lshl_add_u64 v[6:7], v[8:9], 0, v[64:65]
	v_mbcnt_lo_u32_b32 v40, -1, 0
	v_mbcnt_hi_u32_b32 v40, -1, v40
	v_mbcnt_lo_u32_b32 v41, -1, 0
	v_mbcnt_hi_u32_b32 v41, -1, v41
	v_mbcnt_lo_u32_b32 v42, -1, 0
	v_mbcnt_hi_u32_b32 v42, -1, v42
	v_mbcnt_lo_u32_b32 v43, -1, 0
	v_mbcnt_hi_u32_b32 v43, -1, v43
	global_load_dwordx4 v[14:17], v[6:7], off offset:1040
	global_load_dwordx4 v[20:23], v[6:7], off offset:1024
	v_lshlrev_b32_e32 v5, 16, v19
	v_and_b32_e32 v4, 0xffff0000, v18
	v_pk_mul_f32 v[8:9], v[4:5], v[4:5]
	v_add_f32_e32 v11, v11, v4
	v_add_f32_e32 v4, v8, v24
	v_add_f32_e32 v4, v9, v4
	v_lshlrev_b32_e32 v9, 2, v25
	global_load_dwordx4 v[24:27], v9, s[62:63]
	global_load_dwordx4 v[28:31], v9, s[64:65]
	v_add_f32_e32 v8, v11, v5
	v_lshlrev_b32_e32 v18, 16, v0
	v_and_b32_e32 v19, 0xffff0000, v19
	v_add_f32_e32 v8, v8, v19
	v_pk_mul_f32 v[32:33], v[18:19], v[18:19]
	v_add_f32_e32 v8, v8, v18
	v_add_f32_e32 v4, v33, v4
	v_lshlrev_b32_e32 v19, 16, v1
	v_and_b32_e32 v18, 0xffff0000, v0
	v_add_f32_e32 v4, v32, v4
	v_pk_mul_f32 v[32:33], v[18:19], v[18:19]
	v_add_f32_e32 v0, v8, v18
	v_add_f32_e32 v4, v32, v4
	v_add_f32_e32 v0, v0, v19
	v_add_f32_e32 v4, v33, v4
	v_lshlrev_b32_e32 v19, 16, v2
	v_and_b32_e32 v18, 0xffff0000, v1
	global_load_dwordx4 v[32:35], v9, s[62:63] offset:16
	global_load_dwordx4 v[36:39], v9, s[64:65] offset:16
	v_add_f32_e32 v8, v0, v18
	v_pk_mul_f32 v[0:1], v[18:19], v[18:19]
	v_and_b32_e32 v5, 0xffff0000, v3
	v_add_f32_e32 v0, v0, v4
	v_add_f32_e32 v4, v8, v19
	v_add_f32_e32 v8, v1, v0
	v_lshlrev_b32_e32 v1, 16, v3
	v_and_b32_e32 v0, 0xffff0000, v2
	v_pk_mul_f32 v[2:3], v[0:1], v[0:1]
	v_add_f32_e32 v4, v4, v0
	v_add_f32_e32 v0, v2, v8
	v_add_f32_e32 v1, v4, v1
	v_add_f32_e32 v4, v3, v0
	v_mul_f32_e32 v0, v5, v5
	v_lshlrev_b32_e32 v2, 2, v40
	v_lshlrev_b32_e32 v3, 2, v42
	v_xor_b32_e32 v2, 4, v2
	v_xor_b32_e32 v8, 4, v3
	v_pk_add_f32 v[0:1], v[0:1], v[4:5]
	s_nop 1
	v_mov_b32_dpp v3, v1 quad_perm:[1,0,3,2] row_mask:0xf bank_mask:0xf
	s_nop 1
	v_mov_b32_dpp v2, v0 quad_perm:[1,0,3,2] row_mask:0xf bank_mask:0xf
	v_lshlrev_b32_e32 v4, 2, v41
	v_lshlrev_b32_e32 v5, 2, v43
	v_xor_b32_e32 v4, 8, v4
	v_xor_b32_e32 v5, 8, v5
	v_pk_add_f32 v[0:1], v[0:1], v[2:3]
	s_nop 1
	v_mov_b32_dpp v3, v1 quad_perm:[2,3,0,1] row_mask:0xf bank_mask:0xf
	s_nop 1
	v_mov_b32_dpp v2, v0 quad_perm:[2,3,0,1] row_mask:0xf bank_mask:0xf
	global_load_dwordx4 v[40:43], v9, s[62:63] offset:32
	global_load_dwordx4 v[44:47], v9, s[64:65] offset:32
	v_lshl_add_u32 v11, v13, 1, 16
	v_or_b32_e32 v64, s23, v71
	s_addk_i32 s23, 0x80
	v_pk_add_f32 v[0:1], v[0:1], v[2:3]
	s_waitcnt vmcnt(6)
	v_lshlrev_b32_e32 v8, 16, v20
	v_pk_mul_f32 v[4:5], v[0:1], s[18:19] op_sel_hi:[1,0]
	v_and_b32_e32 v13, 0xffff0000, v20
	v_fma_f32 v0, -v5, v5, v4
	v_max_f32_e32 v0, 0, v0
	v_add_f32_e32 v0, 0x358637bd, v0
	v_mul_f32_e32 v1, 0x4b800000, v0
	v_cmp_gt_f32_e32 vcc, s19, v0
	v_lshlrev_b32_e32 v56, 16, v21
	v_and_b32_e32 v57, 0xffff0000, v21
	v_cndmask_b32_e32 v0, v0, v1, vcc
	v_rsq_f32_e32 v0, v0
	v_sub_f32_e32 v8, v8, v5
	v_lshlrev_b32_e32 v59, 16, v23
	v_and_b32_e32 v60, 0xffff0000, v23
	v_mul_f32_e32 v1, 0x45800000, v0
	v_cndmask_b32_e32 v4, v0, v1, vcc
	global_load_dwordx4 v[0:3], v[6:7], off offset:1072
	global_load_dwordx4 v[48:51], v[6:7], off offset:1056
	global_load_dwordx4 v[18:21], v9, s[62:63] offset:48
	global_load_dwordx4 v[52:55], v9, s[64:65] offset:48
	v_mul_f32_e32 v8, v8, v4
	s_waitcnt vmcnt(8)
	v_fma_f32 v8, v24, v8, v28
	v_cvt_pk_bf16_f32 v23, v8, s0
	v_mad_u32_u24 v8, v12, s20, v11
	v_sub_f32_e32 v12, v13, v5
	v_mul_f32_e32 v12, v12, v4
	v_fma_f32 v12, v25, v12, v29
	v_cvt_pk_bf16_f32 v12, v12, s0
	ds_write_b16 v8, v12 offset:272
	v_sub_f32_e32 v12, v56, v5
	v_mul_f32_e32 v12, v12, v4
	v_fma_f32 v12, v26, v12, v30
	v_cvt_pk_bf16_f32 v12, v12, s0
	ds_write_b16 v8, v12 offset:544
	v_sub_f32_e32 v12, v57, v5
	v_mul_f32_e32 v12, v12, v4
	v_fmac_f32_e32 v31, v27, v12
	v_lshlrev_b32_e32 v58, 16, v22
	v_cvt_pk_bf16_f32 v12, v31, s0
	ds_write_b16 v8, v12 offset:816
	v_sub_f32_e32 v12, v58, v5
	v_mul_f32_e32 v12, v12, v4
	s_waitcnt vmcnt(6)
	v_fma_f32 v12, v32, v12, v36
	v_and_b32_e32 v22, 0xffff0000, v22
	v_cvt_pk_bf16_f32 v12, v12, s0
	ds_write_b16 v8, v23
	ds_write_b16 v8, v12 offset:1088
	v_sub_f32_e32 v12, v22, v5
	v_mul_f32_e32 v12, v12, v4
	global_load_dwordx4 v[22:25], v9, s[62:63] offset:64
	global_load_dwordx4 v[26:29], v9, s[64:65] offset:64
	v_fma_f32 v12, v33, v12, v37
	v_cvt_pk_bf16_f32 v12, v12, s0
	ds_write_b16 v8, v12 offset:1360
	v_sub_f32_e32 v12, v59, v5
	v_mul_f32_e32 v12, v12, v4
	v_fma_f32 v12, v34, v12, v38
	v_cvt_pk_bf16_f32 v12, v12, s0
	ds_write_b16 v8, v12 offset:1632
	v_sub_f32_e32 v12, v60, v5
	v_mul_f32_e32 v12, v12, v4
	v_fmac_f32_e32 v39, v35, v12
	v_lshlrev_b32_e32 v35, 16, v14
	v_lshlrev_b32_e32 v56, 16, v17
	v_and_b32_e32 v57, 0xffff0000, v17
	v_sub_f32_e32 v17, v35, v5
	v_cvt_pk_bf16_f32 v12, v39, s0
	v_mul_f32_e32 v17, v17, v4
	ds_write_b16 v8, v12 offset:1904
	v_or_b32_e32 v34, 8, v10
	s_waitcnt vmcnt(6)
; __device__ __forceinline__ u16 f2bf(float f) { return (u16)(cvt_pk(f, 0.f) & 0xffffu); }
; __device__ __forceinline__ float bflo(unsigned w) { return __uint_as_float(w << 16); }
; __device__ __forceinline__ float bfhi(unsigned w) { return __uint_as_float(w & 0xffff0000u); }
; __device__ __forceinline__ void gmlp_prompt_item(const Params& p, int item, const int wv) {
;     ...
; #pragma unroll
;     for (int i = 0; i < 8; ++i) {
;       const int cl = qq * 64 + i * 8, col = gp * 256 + cl;
;       u32x4 w = *(const u32x4*)(vrow + col);
;       float f[8] = {bflo(w.x), bfhi(w.x), bflo(w.y), bfhi(w.y), bflo(w.z), bfhi(w.z), bflo(w.w), bfhi(w.w)};
; #pragma unroll
;       for (int e = 0; e < 8; ++e) {
;         float vn = (f[e] - mean) * rstd * p.in[9][col + e] + p.in[10][col + e];
;         VnT[(cl + e) * 136 + row] = f2bf(vn);
;       }
	v_fma_f32 v17, v40, v17, v44
	v_and_b32_e32 v36, 0xffff0000, v14
	v_lshlrev_b32_e32 v37, 16, v15
	v_and_b32_e32 v38, 0xffff0000, v15
	global_load_dwordx4 v[12:15], v9, s[62:63] offset:80
	global_load_dwordx4 v[30:33], v9, s[64:65] offset:80
	v_cvt_pk_bf16_f32 v17, v17, s0
	v_mad_u32_u24 v34, v34, s21, v11
	ds_write_b16 v34, v17
	v_sub_f32_e32 v17, v36, v5
	v_mul_f32_e32 v17, v17, v4
	v_fma_f32 v17, v41, v17, v45
	v_cvt_pk_bf16_f32 v17, v17, s0
	ds_write_b16 v8, v17 offset:2448
	v_sub_f32_e32 v17, v37, v5
	v_mul_f32_e32 v17, v17, v4
	v_fma_f32 v17, v42, v17, v46
	v_cvt_pk_bf16_f32 v17, v17, s0
	ds_write_b16 v8, v17 offset:2720
	v_sub_f32_e32 v17, v38, v5
	v_mul_f32_e32 v17, v17, v4
	v_fmac_f32_e32 v47, v43, v17
	v_lshlrev_b32_e32 v39, 16, v16
	v_and_b32_e32 v16, 0xffff0000, v16
	v_cvt_pk_bf16_f32 v17, v47, s0
	ds_write_b16 v8, v17 offset:2992
	v_sub_f32_e32 v17, v39, v5
	v_sub_f32_e32 v16, v16, v5
	v_mul_f32_e32 v17, v17, v4
	v_mul_f32_e32 v16, v16, v4
	v_sub_f32_e32 v38, v56, v5
	s_waitcnt vmcnt(4)
	v_fma_f32 v17, v18, v17, v52
	v_fma_f32 v16, v19, v16, v53
	v_cvt_pk_bf16_f32 v17, v17, s0
	v_cvt_pk_bf16_f32 v16, v16, s0
	ds_write_b16 v8, v17 offset:3264
	ds_write_b16 v8, v16 offset:3536
	global_load_dwordx4 v[16:19], v9, s[62:63] offset:96
	global_load_dwordx4 v[34:37], v9, s[64:65] offset:96
	v_mul_f32_e32 v38, v38, v4
	v_fma_f32 v20, v20, v38, v54
	v_cvt_pk_bf16_f32 v20, v20, s0
	ds_write_b16 v8, v20 offset:3808
	v_sub_f32_e32 v20, v57, v5
	v_mul_f32_e32 v20, v20, v4
	v_fmac_f32_e32 v55, v21, v20
	v_cvt_pk_bf16_f32 v20, v55, s0
	ds_write_b16 v8, v20 offset:4080
	global_load_dwordx4 v[38:41], v9, s[62:63] offset:112
	global_load_dwordx4 v[42:45], v9, s[64:65] offset:112
	v_lshlrev_b32_e32 v21, 16, v48
	v_sub_f32_e32 v21, v21, v5
	v_mul_f32_e32 v21, v21, v4
	v_or_b32_e32 v20, 16, v10
	v_and_b32_e32 v46, 0xffff0000, v48
	v_mad_u32_u24 v20, v20, s21, v11
	v_lshlrev_b32_e32 v47, 16, v49
	v_and_b32_e32 v48, 0xffff0000, v49
	v_lshlrev_b32_e32 v49, 16, v50
	v_and_b32_e32 v50, 0xffff0000, v50
	v_lshlrev_b32_e32 v52, 16, v51
	v_and_b32_e32 v51, 0xffff0000, v51
	v_lshlrev_b32_e32 v54, 16, v1
	s_waitcnt vmcnt(6)
	v_fma_f32 v21, v22, v21, v26
	v_cvt_pk_bf16_f32 v21, v21, s0
	ds_write_b16 v20, v21
	v_sub_f32_e32 v20, v46, v5
	v_mul_f32_e32 v20, v20, v4
	v_fma_f32 v20, v23, v20, v27
	v_cvt_pk_bf16_f32 v20, v20, s0
	ds_write_b16 v8, v20 offset:4624
	v_sub_f32_e32 v20, v47, v5
	v_mul_f32_e32 v20, v20, v4
	v_fma_f32 v20, v24, v20, v28
	v_cvt_pk_bf16_f32 v20, v20, s0
	ds_write_b16 v8, v20 offset:4896
	v_sub_f32_e32 v20, v48, v5
	v_mul_f32_e32 v20, v20, v4
	v_sub_f32_e32 v28, v49, v5
	v_fmac_f32_e32 v29, v25, v20
	v_mul_f32_e32 v28, v28, v4
	v_cvt_pk_bf16_f32 v20, v29, s0
	ds_write_b16 v8, v20 offset:5168
	global_load_dwordx4 v[20:23], v[6:7], off offset:1104
	global_load_dwordx4 v[24:27], v[6:7], off offset:1088
	v_and_b32_e32 v1, 0xffff0000, v1
	v_lshlrev_b32_e32 v55, 16, v2
	v_and_b32_e32 v2, 0xffff0000, v2
	s_waitcnt vmcnt(6)
	v_fma_f32 v12, v12, v28, v30
	v_cvt_pk_bf16_f32 v12, v12, s0
	ds_write_b16 v8, v12 offset:5440
	v_sub_f32_e32 v12, v50, v5
	v_mul_f32_e32 v12, v12, v4
	v_fma_f32 v12, v13, v12, v31
	v_cvt_pk_bf16_f32 v12, v12, s0
	ds_write_b16 v8, v12 offset:5712
	global_load_dwordx4 v[28:31], v9, s[62:63] offset:128
	global_load_dwordx4 v[46:49], v9, s[64:65] offset:128
	v_sub_f32_e32 v12, v52, v5
	v_mul_f32_e32 v12, v12, v4
	v_fma_f32 v12, v14, v12, v32
	v_cvt_pk_bf16_f32 v12, v12, s0
	ds_write_b16 v8, v12 offset:5984
	v_sub_f32_e32 v12, v51, v5
	v_mul_f32_e32 v12, v12, v4
	v_fmac_f32_e32 v33, v15, v12
	v_cvt_pk_bf16_f32 v12, v33, s0
	v_lshlrev_b32_e32 v33, 16, v0
	v_and_b32_e32 v0, 0xffff0000, v0
	v_sub_f32_e32 v33, v33, v5
	v_sub_f32_e32 v0, v0, v5
	v_mul_f32_e32 v33, v33, v4
	v_mul_f32_e32 v0, v0, v4
	v_or_b32_e32 v32, 24, v10
	ds_write_b16 v8, v12 offset:6256
	v_mad_u32_u24 v32, v32, s21, v11
	global_load_dwordx4 v[12:15], v9, s[62:63] offset:144
	global_load_dwordx4 v[50:53], v9, s[64:65] offset:144
	v_lshlrev_b32_e32 v56, 16, v3
	v_and_b32_e32 v3, 0xffff0000, v3
	s_and_b64 vcc, exec, s[0:1]
	s_waitcnt vmcnt(8)
	v_fma_f32 v16, v16, v33, v34
	v_fma_f32 v0, v17, v0, v35
	v_cvt_pk_bf16_f32 v16, v16, s0
	v_cvt_pk_bf16_f32 v0, v0, s0
	ds_write_b16 v32, v16
	ds_write_b16 v8, v0 offset:6800
	v_sub_f32_e32 v0, v54, v5
	v_mul_f32_e32 v0, v0, v4
	v_fma_f32 v0, v18, v0, v36
	v_cvt_pk_bf16_f32 v0, v0, s0
	ds_write_b16 v8, v0 offset:7072
	v_sub_f32_e32 v0, v1, v5
	v_mul_f32_e32 v0, v0, v4
	v_fmac_f32_e32 v37, v19, v0
	v_cvt_pk_bf16_f32 v0, v37, s0
	ds_write_b16 v8, v0 offset:7344
	v_sub_f32_e32 v0, v55, v5
	v_mul_f32_e32 v0, v0, v4
	s_waitcnt vmcnt(6)
	v_fma_f32 v0, v38, v0, v42
	v_cvt_pk_bf16_f32 v0, v0, s0
	ds_write_b16 v8, v0 offset:7616
	v_sub_f32_e32 v0, v2, v5
	v_mul_f32_e32 v0, v0, v4
	v_fma_f32 v0, v39, v0, v43
	v_cvt_pk_bf16_f32 v0, v0, s0
	ds_write_b16 v8, v0 offset:7888
	global_load_dwordx4 v[16:19], v9, s[62:63] offset:160
	global_load_dwordx4 v[32:35], v9, s[64:65] offset:160
	v_sub_f32_e32 v0, v56, v5
	v_mul_f32_e32 v0, v0, v4
	v_fma_f32 v0, v40, v0, v44
	v_cvt_pk_bf16_f32 v0, v0, s0
	ds_write_b16 v8, v0 offset:8160
	v_sub_f32_e32 v0, v3, v5
	v_mul_f32_e32 v0, v0, v4
	v_fmac_f32_e32 v45, v41, v0
	v_cvt_pk_bf16_f32 v0, v45, s0
	ds_write_b16 v8, v0 offset:8432
	global_load_dwordx4 v[0:3], v[6:7], off offset:1136
	global_load_dwordx4 v[36:39], v[6:7], off offset:1120
	global_load_dwordx4 v[40:43], v9, s[62:63] offset:176
	global_load_dwordx4 v[54:57], v9, s[64:65] offset:176
	v_or_b32_e32 v44, 32, v10
	s_waitcnt vmcnt(10)
; __device__ __forceinline__ u16 f2bf(float f) { return (u16)(cvt_pk(f, 0.f) & 0xffffu); }
; __device__ __forceinline__ float bflo(unsigned w) { return __uint_as_float(w << 16); }
; __device__ __forceinline__ float bfhi(unsigned w) { return __uint_as_float(w & 0xffff0000u); }
; __device__ __forceinline__ void gmlp_prompt_item(const Params& p, int item, const int wv) {
;     ...
; #pragma unroll
;     for (int i = 0; i < 8; ++i) {
;       const int cl = qq * 64 + i * 8, col = gp * 256 + cl;
;       u32x4 w = *(const u32x4*)(vrow + col);
;       float f[8] = {bflo(w.x), bfhi(w.x), bflo(w.y), bfhi(w.y), bflo(w.z), bfhi(w.z), bflo(w.w), bfhi(w.w)};
; #pragma unroll
;       for (int e = 0; e < 8; ++e) {
;         float vn = (f[e] - mean) * rstd * p.in[9][col + e] + p.in[10][col + e];
;         VnT[(cl + e) * 136 + row] = f2bf(vn);
;       }
;     }
;   }
;   __syncthreads();
	v_lshlrev_b32_e32 v6, 16, v24
	v_sub_f32_e32 v6, v6, v5
	v_mul_f32_e32 v6, v6, v4
	v_and_b32_e32 v7, 0xffff0000, v24
	v_lshlrev_b32_e32 v58, 16, v27
	v_and_b32_e32 v59, 0xffff0000, v27
	v_mad_u32_u24 v27, v44, s21, v11
	v_lshlrev_b32_e32 v24, 16, v25
	v_and_b32_e32 v25, 0xffff0000, v25
	v_lshlrev_b32_e32 v45, 16, v26
	v_and_b32_e32 v26, 0xffff0000, v26
	s_waitcnt vmcnt(8)
	v_fma_f32 v6, v28, v6, v46
	v_cvt_pk_bf16_f32 v6, v6, s0
	ds_write_b16 v27, v6
	v_sub_f32_e32 v6, v7, v5
	v_mul_f32_e32 v6, v6, v4
	v_fma_f32 v6, v29, v6, v47
	v_cvt_pk_bf16_f32 v6, v6, s0
	ds_write_b16 v8, v6 offset:8976
	v_sub_f32_e32 v6, v24, v5
	v_mul_f32_e32 v6, v6, v4
	v_fma_f32 v6, v30, v6, v48
	v_cvt_pk_bf16_f32 v6, v6, s0
	ds_write_b16 v8, v6 offset:9248
	v_sub_f32_e32 v6, v25, v5
	v_mul_f32_e32 v6, v6, v4
	v_fmac_f32_e32 v49, v31, v6
	v_cvt_pk_bf16_f32 v6, v49, s0
	ds_write_b16 v8, v6 offset:9520
	v_sub_f32_e32 v6, v45, v5
	v_mul_f32_e32 v6, v6, v4
	s_waitcnt vmcnt(6)
	v_fma_f32 v6, v12, v6, v50
	v_cvt_pk_bf16_f32 v6, v6, s0
	ds_write_b16 v8, v6 offset:9792
	v_sub_f32_e32 v6, v26, v5
	v_mul_f32_e32 v6, v6, v4
	global_load_dwordx4 v[24:27], v9, s[62:63] offset:192
	global_load_dwordx4 v[28:31], v9, s[64:65] offset:192
	v_fma_f32 v6, v13, v6, v51
	v_cvt_pk_bf16_f32 v6, v6, s0
	ds_write_b16 v8, v6 offset:10064
	v_sub_f32_e32 v6, v58, v5
	v_mul_f32_e32 v6, v6, v4
	v_fma_f32 v6, v14, v6, v52
	v_cvt_pk_bf16_f32 v6, v6, s0
	ds_write_b16 v8, v6 offset:10336
	v_sub_f32_e32 v6, v59, v5
	v_mul_f32_e32 v6, v6, v4
	v_lshlrev_b32_e32 v7, 16, v20
	v_fmac_f32_e32 v53, v6, v15
	v_sub_f32_e32 v7, v7, v5
	v_cvt_pk_bf16_f32 v6, v53, s0
	v_mul_f32_e32 v7, v4, v7
	ds_write_b16 v8, v6 offset:10608
	v_or_b32_e32 v6, 40, v10
	v_and_b32_e32 v20, 0xffff0000, v20
	v_mad_u32_u24 v6, v6, s21, v11
	global_load_dwordx4 v[12:15], v9, s[62:63] offset:208
	global_load_dwordx4 v[44:47], v9, s[64:65] offset:208
	v_lshlrev_b32_e32 v48, 16, v21
	v_and_b32_e32 v21, 0xffff0000, v21
	v_lshlrev_b32_e32 v49, 16, v22
	v_and_b32_e32 v50, 0xffff0000, v22
	s_waitcnt vmcnt(8)
	v_fma_f32 v7, v16, v7, v32
	v_cvt_pk_bf16_f32 v7, v7, s0
	ds_write_b16 v6, v7
	v_sub_f32_e32 v6, v20, v5
	v_mul_f32_e32 v6, v4, v6
	v_fma_f32 v6, v17, v6, v33
	v_cvt_pk_bf16_f32 v6, v6, s0
	ds_write_b16 v8, v6 offset:11152
	v_sub_f32_e32 v6, v48, v5
	v_mul_f32_e32 v6, v4, v6
	v_fma_f32 v6, v6, v18, v34
	v_cvt_pk_bf16_f32 v6, v6, s0
	ds_write_b16 v8, v6 offset:11424
	v_sub_f32_e32 v6, v21, v5
	v_mul_f32_e32 v6, v4, v6
	v_fmac_f32_e32 v35, v6, v19
	v_cvt_pk_bf16_f32 v6, v35, s0
	ds_write_b16 v8, v6 offset:11696
	v_sub_f32_e32 v6, v49, v5
	v_mul_f32_e32 v6, v4, v6
	s_waitcnt vmcnt(4)
	v_fma_f32 v6, v6, v40, v54
	v_cvt_pk_bf16_f32 v6, v6, s0
	v_lshlrev_b32_e32 v51, 16, v23
	v_and_b32_e32 v52, 0xffff0000, v23
	global_load_dwordx4 v[16:19], v9, s[62:63] offset:224
	global_load_dwordx4 v[20:23], v9, s[64:65] offset:224
	ds_write_b16 v8, v6 offset:11968
	v_sub_f32_e32 v6, v50, v5
	v_mul_f32_e32 v6, v4, v6
	v_fma_f32 v6, v6, v41, v55
	v_cvt_pk_bf16_f32 v6, v6, s0
	ds_write_b16 v8, v6 offset:12240
	v_sub_f32_e32 v6, v51, v5
	v_mul_f32_e32 v6, v4, v6
	v_fma_f32 v6, v6, v42, v56
	v_cvt_pk_bf16_f32 v6, v6, s0
	ds_write_b16 v8, v6 offset:12512
	v_sub_f32_e32 v6, v52, v5
	v_mul_f32_e32 v6, v4, v6
	v_fmac_f32_e32 v57, v6, v43
	v_cvt_pk_bf16_f32 v6, v57, s0
	ds_write_b16 v8, v6 offset:12784
	global_load_dwordx4 v[32:35], v9, s[62:63] offset:240
	global_load_dwordx4 v[40:43], v9, s[64:65] offset:240
	v_lshlrev_b32_e32 v7, 16, v36
	v_sub_f32_e32 v7, v7, v5
	v_mul_f32_e32 v7, v4, v7
	v_or_b32_e32 v6, 48, v10
	v_and_b32_e32 v36, 0xffff0000, v36
	v_mad_u32_u24 v6, v6, s21, v11
	v_lshlrev_b32_e32 v9, 16, v37
	v_and_b32_e32 v37, 0xffff0000, v37
	v_lshlrev_b32_e32 v48, 16, v38
	v_and_b32_e32 v38, 0xffff0000, v38
	v_lshlrev_b32_e32 v49, 16, v39
	v_and_b32_e32 v39, 0xffff0000, v39
	s_waitcnt vmcnt(6)
	v_fma_f32 v7, v24, v7, v28
	v_cvt_pk_bf16_f32 v7, v7, s0
	ds_write_b16 v6, v7
	v_sub_f32_e32 v6, v36, v5
	v_mul_f32_e32 v6, v4, v6
	v_fma_f32 v6, v25, v6, v29
	v_cvt_pk_bf16_f32 v6, v6, s0
	ds_write_b16 v8, v6 offset:13328
	v_sub_f32_e32 v6, v9, v5
	v_mul_f32_e32 v6, v4, v6
	v_fma_f32 v6, v6, v26, v30
	v_cvt_pk_bf16_f32 v6, v6, s0
	ds_write_b16 v8, v6 offset:13600
	v_sub_f32_e32 v6, v37, v5
	v_mul_f32_e32 v6, v4, v6
	v_fmac_f32_e32 v31, v6, v27
	v_cvt_pk_bf16_f32 v6, v31, s0
	ds_write_b16 v8, v6 offset:13872
	v_sub_f32_e32 v6, v48, v5
	v_mul_f32_e32 v6, v4, v6
	s_waitcnt vmcnt(4)
	v_fma_f32 v6, v6, v12, v44
	v_cvt_pk_bf16_f32 v6, v6, s0
	ds_write_b16 v8, v6 offset:14144
	v_sub_f32_e32 v6, v38, v5
	v_mul_f32_e32 v6, v4, v6
	v_fma_f32 v6, v6, v13, v45
	v_cvt_pk_bf16_f32 v6, v6, s0
	ds_write_b16 v8, v6 offset:14416
	v_sub_f32_e32 v6, v49, v5
	v_mul_f32_e32 v6, v4, v6
	v_fma_f32 v6, v6, v14, v46
	v_cvt_pk_bf16_f32 v6, v6, s0
	ds_write_b16 v8, v6 offset:14688
	v_sub_f32_e32 v6, v39, v5
	v_mul_f32_e32 v6, v4, v6
	v_lshlrev_b32_e32 v7, 16, v0
	v_and_b32_e32 v0, 0xffff0000, v0
	v_fmac_f32_e32 v47, v6, v15
	v_sub_f32_e32 v7, v7, v5
	v_sub_f32_e32 v0, v0, v5
	v_cvt_pk_bf16_f32 v6, v47, s0
	v_mul_f32_e32 v7, v4, v7
	v_mul_f32_e32 v0, v4, v0
	ds_write_b16 v8, v6 offset:14960
	v_or_b32_e32 v6, 56, v10
	v_lshlrev_b32_e32 v9, 16, v1
	v_mad_u32_u24 v6, v6, s21, v11
	v_and_b32_e32 v1, 0xffff0000, v1
	v_lshlrev_b32_e32 v10, 16, v2
	s_waitcnt vmcnt(2)
	v_fma_f32 v7, v16, v7, v20
	v_fma_f32 v0, v17, v0, v21
	v_cvt_pk_bf16_f32 v7, v7, s0
	v_cvt_pk_bf16_f32 v0, v0, s0
	ds_write_b16 v6, v7
	ds_write_b16 v8, v0 offset:15504
	v_sub_f32_e32 v0, v9, v5
	v_mul_f32_e32 v0, v4, v0
	v_fma_f32 v0, v0, v18, v22
	v_cvt_pk_bf16_f32 v0, v0, s0
	ds_write_b16 v8, v0 offset:15776
	v_sub_f32_e32 v0, v1, v5
	v_mul_f32_e32 v0, v4, v0
	v_fmac_f32_e32 v23, v0, v19
	v_cvt_pk_bf16_f32 v0, v23, s0
	ds_write_b16 v8, v0 offset:16048
	v_sub_f32_e32 v0, v10, v5
	v_mul_f32_e32 v0, v4, v0
	s_waitcnt vmcnt(0)
	v_fma_f32 v0, v0, v32, v40
	v_and_b32_e32 v2, 0xffff0000, v2
	v_cvt_pk_bf16_f32 v0, v0, s0
	ds_write_b16 v8, v0 offset:16320
	v_sub_f32_e32 v0, v2, v5
	v_mul_f32_e32 v0, v4, v0
	v_fma_f32 v0, v0, v33, v41
	v_lshlrev_b32_e32 v12, 16, v3
	v_cvt_pk_bf16_f32 v0, v0, s0
	ds_write_b16 v8, v0 offset:16592
	v_sub_f32_e32 v0, v12, v5
	v_mul_f32_e32 v0, v4, v0
	v_fma_f32 v0, v0, v34, v42
	v_and_b32_e32 v3, 0xffff0000, v3
	v_cvt_pk_bf16_f32 v0, v0, s0
	ds_write_b16 v8, v0 offset:16864
	v_sub_f32_e32 v0, v3, v5
	v_mul_f32_e32 v0, v4, v0
	v_fmac_f32_e32 v43, v0, v35
	v_cvt_pk_bf16_f32 v0, v43, s0
	v_lshlrev_b32_e32 v2, 3, v70
	ds_write_b16 v8, v0 offset:17136
	v_lshlrev_b64 v[0:1], 8, v[64:65]
	v_ashrrev_i32_e32 v3, 31, v2
	v_lshl_add_u64 v[0:1], s[2:3], 0, v[0:1]
	v_lshlrev_b64 v[4:5], 1, v[2:3]
	v_lshl_add_u64 v[66:67], v[0:1], 0, v[4:5]
	s_waitcnt lgkmcnt(0)
	s_barrier
; #define MFMA16(a, b, c) __builtin_amdgcn_mfma_f32_16x16x32_bf16((a), (b), (c), 0, 0, 0)
; __device__ __forceinline__ void gmlp_prompt_item(const Params& p, int item, const int wv) {
;     ...
; #pragma unroll
;   for (int ks = 0; ks < 4; ++ks) {
;     if (ks <= (wid >> 1)) {
;       bf16x8 w0 = *(const bf16x8*)(WSB + ((size_t)(gp * 2) * 128 + wid * 16 + fr) * 128 + ks * 32 + fq * 8);
;       bf16x8 w1 = *(const bf16x8*)(WSB + ((size_t)(gp * 2 + 1) * 128 + wid * 16 + fr) * 128 + ks * 32 + fq * 8);
; #pragma unroll
;       for (int db = 0; db < 16; ++db) {
;         bf16x8 vf = *(const bf16x8*)(VnT + (db * 16 + fr) * 136 + ks * 32 + fq * 8);
;         acc[db] = MFMA16(vf, db < 8 ? w0 : w1, acc[db]);
;       }
;     }
;   }
	global_load_dwordx4 v[0:3], v[66:67], off
	v_or_b32_e32 v64, s23, v71
	v_lshlrev_b64 v[6:7], 8, v[64:65]
	v_lshl_add_u64 v[6:7], s[2:3], 0, v[6:7]
	v_lshl_add_u64 v[68:69], v[6:7], 0, v[4:5]
	global_load_dwordx4 v[4:7], v[68:69], off
	v_and_b32_e32 v8, -16, v72
	v_mul_u32_u24_e32 v9, 0x110, v71
	v_add3_u32 v64, 16, v8, v9
	ds_read_b128 v[8:11], v64
	ds_read_b128 v[12:15], v64 offset:4352
	s_waitcnt vmcnt(1) lgkmcnt(1)
	v_mfma_f32_16x16x32_bf16 v[56:59], v[8:11], v[0:3], 0
	ds_read_b128 v[8:11], v64 offset:8704
	ds_read_b128 v[74:77], v64 offset:60928
	ds_read_b128 v[78:81], v64 offset:65280
	s_waitcnt lgkmcnt(3)
	v_mfma_f32_16x16x32_bf16 v[60:63], v[12:15], v[0:3], 0
	ds_read_b128 v[12:15], v64 offset:13056
	s_waitcnt lgkmcnt(3)
	v_mfma_f32_16x16x32_bf16 v[52:55], v[8:11], v[0:3], 0
	ds_read_b128 v[8:11], v64 offset:17408
	s_waitcnt lgkmcnt(1)
	v_mfma_f32_16x16x32_bf16 v[48:51], v[12:15], v[0:3], 0
	ds_read_b128 v[12:15], v64 offset:21760
	s_waitcnt lgkmcnt(1)
	v_mfma_f32_16x16x32_bf16 v[44:47], v[8:11], v[0:3], 0
	ds_read_b128 v[8:11], v64 offset:26112
	s_waitcnt lgkmcnt(1)
	v_mfma_f32_16x16x32_bf16 v[40:43], v[12:15], v[0:3], 0
	ds_read_b128 v[12:15], v64 offset:30464
	s_waitcnt lgkmcnt(1)
	v_mfma_f32_16x16x32_bf16 v[36:39], v[8:11], v[0:3], 0
	ds_read_b128 v[8:11], v64 offset:34816
	s_waitcnt lgkmcnt(1)
	v_mfma_f32_16x16x32_bf16 v[32:35], v[12:15], v[0:3], 0
	ds_read_b128 v[0:3], v64 offset:39168
	s_waitcnt vmcnt(0) lgkmcnt(1)
	v_mfma_f32_16x16x32_bf16 v[28:31], v[8:11], v[4:7], 0
	ds_read_b128 v[8:11], v64 offset:43520
	s_waitcnt lgkmcnt(1)
	v_mfma_f32_16x16x32_bf16 v[24:27], v[0:3], v[4:7], 0
	ds_read_b128 v[0:3], v64 offset:47872
	s_waitcnt lgkmcnt(1)
	v_mfma_f32_16x16x32_bf16 v[20:23], v[8:11], v[4:7], 0
	ds_read_b128 v[8:11], v64 offset:52224
	s_waitcnt lgkmcnt(1)
	v_mfma_f32_16x16x32_bf16 v[16:19], v[0:3], v[4:7], 0
	ds_read_b128 v[0:3], v64 offset:56576
	s_waitcnt lgkmcnt(1)
	v_mfma_f32_16x16x32_bf16 v[12:15], v[8:11], v[4:7], 0
	s_waitcnt lgkmcnt(0)
	v_mfma_f32_16x16x32_bf16 v[8:11], v[0:3], v[4:7], 0
	v_mfma_f32_16x16x32_bf16 v[0:3], v[74:77], v[4:7], 0
	v_mfma_f32_16x16x32_bf16 v[4:7], v[78:81], v[4:7], 0
	s_cbranch_vccnz .LBB0_555
	global_load_dwordx4 v[74:77], v[66:67], off offset:64
	global_load_dwordx4 v[78:81], v[68:69], off offset:64
	ds_read_b128 v[82:85], v64 offset:64
	ds_read_b128 v[86:89], v64 offset:4416
	s_waitcnt vmcnt(1) lgkmcnt(1)
	v_mfma_f32_16x16x32_bf16 v[56:59], v[82:85], v[74:77], v[56:59]
	ds_read_b128 v[82:85], v64 offset:8768
	s_waitcnt lgkmcnt(1)
	v_mfma_f32_16x16x32_bf16 v[60:63], v[86:89], v[74:77], v[60:63]
	ds_read_b128 v[86:89], v64 offset:13120
	s_waitcnt lgkmcnt(1)
	v_mfma_f32_16x16x32_bf16 v[52:55], v[82:85], v[74:77], v[52:55]
	ds_read_b128 v[82:85], v64 offset:17472
	s_waitcnt lgkmcnt(1)
	v_mfma_f32_16x16x32_bf16 v[48:51], v[86:89], v[74:77], v[48:51]
	ds_read_b128 v[86:89], v64 offset:21824
	s_waitcnt lgkmcnt(1)
	v_mfma_f32_16x16x32_bf16 v[44:47], v[82:85], v[74:77], v[44:47]
	ds_read_b128 v[82:85], v64 offset:26176
	s_waitcnt lgkmcnt(1)
	v_mfma_f32_16x16x32_bf16 v[40:43], v[86:89], v[74:77], v[40:43]
	ds_read_b128 v[86:89], v64 offset:30528
	s_waitcnt lgkmcnt(1)
	v_mfma_f32_16x16x32_bf16 v[36:39], v[82:85], v[74:77], v[36:39]
	ds_read_b128 v[82:85], v64 offset:34880
	s_waitcnt lgkmcnt(1)
	v_mfma_f32_16x16x32_bf16 v[32:35], v[86:89], v[74:77], v[32:35]
	ds_read_b128 v[74:77], v64 offset:39232
	s_waitcnt vmcnt(0) lgkmcnt(1)
	v_mfma_f32_16x16x32_bf16 v[28:31], v[82:85], v[78:81], v[28:31]
	ds_read_b128 v[82:85], v64 offset:43584
	s_waitcnt lgkmcnt(1)
	v_mfma_f32_16x16x32_bf16 v[24:27], v[74:77], v[78:81], v[24:27]
	ds_read_b128 v[74:77], v64 offset:47936
	s_waitcnt lgkmcnt(1)
	v_mfma_f32_16x16x32_bf16 v[20:23], v[82:85], v[78:81], v[20:23]
	ds_read_b128 v[82:85], v64 offset:52288
	s_waitcnt lgkmcnt(1)
	v_mfma_f32_16x16x32_bf16 v[16:19], v[74:77], v[78:81], v[16:19]
	ds_read_b128 v[74:77], v64 offset:56640
	s_waitcnt lgkmcnt(1)
	v_mfma_f32_16x16x32_bf16 v[12:15], v[82:85], v[78:81], v[12:15]
	ds_read_b128 v[82:85], v64 offset:60992
	s_waitcnt lgkmcnt(1)
	v_mfma_f32_16x16x32_bf16 v[8:11], v[74:77], v[78:81], v[8:11]
	ds_read_b128 v[74:77], v64 offset:65344
	s_waitcnt lgkmcnt(1)
	v_mfma_f32_16x16x32_bf16 v[0:3], v[82:85], v[78:81], v[0:3]
	s_waitcnt lgkmcnt(0)
	v_mfma_f32_16x16x32_bf16 v[4:7], v[74:77], v[78:81], v[4:7]
	s_andn2_b64 vcc, exec, s[8:9]
	s_cbranch_vccz .LBB0_556

; __device__ __forceinline__ int lane_fresh() { int l; asm volatile("v_mbcnt_lo_u32_b32 %0, -1, 0\n\tv_mbcnt_hi_u32_b32 %0, -1, %0" : "=v"(l)); return l; }
; #define WAIT_V(n) asm volatile("s_waitcnt vmcnt(" #n ")" ::: "memory")
; #define WAIT_L(n) asm volatile("s_waitcnt lgkmcnt(" #n ")" ::: "memory")
; template <int PART  , bool SYNC_FIRST = true>
; __device__ __forceinline__ void kloop_t(const u16* __restrict__ A, int lda, const u16* __restrict__ Bt, int ldb, int K, Acc& acc, const int wv) {
;     ...
;   const int wid = wv, lane = lane_fresh(), ktid = wv * 64 + lane, wr = wid >> 2, wc = wid & 3, fr = lane & 15, fq = lane >> 4;
;   bf16x8 At[4][2], B0[2][2], B1[2][2];
;   const int nt = K / BK;
;   unsigned oA0, oA1, oB0, oB1;
;   { int r_, c_; stage_rc(ktid * 16, r_, c_); oA0 = (unsigned)(r_ * lda + c_) * 2u; oB0 = (unsigned)(r_ * ldb + c_) * 2u;
;     stage_rc(ktid * 16 + 8192, r_, c_); oA1 = (unsigned)(r_ * lda + c_) * 2u; oB1 = (unsigned)(r_ * ldb + c_) * 2u; }
;   if (PART != 2) {
;     if (SYNC_FIRST) { WAIT_V(0); WAIT_L(0); __syncthreads(); }
;     STAGE(SB(0, 0), Bt, ldb, 0, 0); STAGE(SA(0, 0), A, lda, 0, 0);
;     STAGE(SB(0, 1), Bt, ldb, HALF, 0); STAGE(SA(0, 1), A, lda, HALF, 0);
;   }
;   if (PART == 1) return;
.LBB0_977:
	v_mbcnt_lo_u32_b32 v0, -1, 0
	v_mbcnt_hi_u32_b32 v0, -1, v0
	s_lshl_b32 s10, s70, 8
	s_waitcnt lgkmcnt(0)
	v_lshl_add_u32 v1, v0, 4, s42
	v_ashrrev_i32_e32 v2, 31, v1
	v_lshrrev_b32_e32 v2, 22, v2
	v_add_u32_e32 v2, v1, v2
	v_ashrrev_i32_e32 v2, 10, v2
	v_mul_i32_i24_e32 v3, 0x400, v2
	v_sub_u32_e32 v3, v1, v3
	v_lshrrev_b32_e32 v4, 4, v3
	v_bitop3_b32 v3, v4, v3, 32 bitop3:0x6c
	v_ashrrev_i32_e32 v5, 31, v3
	v_lshrrev_b32_e32 v5, 26, v5
	v_add_u32_e32 v5, v3, v5
	v_lshrrev_b32_e32 v6, 6, v5
	v_and_b32_e32 v5, 0xc0, v5
	v_lshlrev_b32_e32 v4, 3, v2
	v_lshlrev_b32_e32 v2, 5, v2
	v_sub_u32_e32 v3, v3, v5
	v_and_b32_e32 v4, 0x1ffff0, v4
	v_and_b32_e32 v2, 32, v2
	v_ashrrev_i16_sdwa v3, v134, sext(v3) dst_sel:DWORD dst_unused:UNUSED_PAD src0_sel:DWORD src1_sel:BYTE_0
	v_add_u32_sdwa v2, v2, sext(v3) dst_sel:DWORD dst_unused:UNUSED_PAD src0_sel:DWORD src1_sel:WORD_0
	v_add_lshl_u32 v3, v6, v4, 11
	v_lshl_add_u32 v130, v2, 1, v3
	v_add_u32_e32 v2, 0x2000, v1
	v_ashrrev_i32_e32 v3, 31, v2
	v_lshrrev_b32_e32 v3, 22, v3
	v_add_u32_e32 v3, v2, v3
	v_ashrrev_i32_e32 v3, 10, v3
	v_mul_i32_i24_e32 v4, 0x400, v3
	v_sub_u32_e32 v2, v2, v4
	v_lshrrev_b32_e32 v4, 4, v2
	v_bitop3_b32 v2, v4, v2, 32 bitop3:0x6c
	v_ashrrev_i32_e32 v5, 31, v2
	v_lshrrev_b32_e32 v5, 26, v5
	v_add_u32_e32 v5, v2, v5
	v_lshrrev_b32_e32 v6, 6, v5
	v_and_b32_e32 v5, 0xffc0, v5
	v_sub_u32_e32 v2, v2, v5
	v_lshrrev_b16_e32 v5, 7, v2
	s_and_b32 s71, s10, 0x3f00
	v_and_b32_e32 v5, 1, v5
	s_bfe_u32 s10, s70, 0x20006
	s_lshl_b32 s30, s71, 11
	v_lshlrev_b32_e32 v4, 3, v3
	v_lshlrev_b32_e32 v3, 5, v3
	v_add_u16_e32 v2, v2, v5
	s_add_u32 s30, s2, s30
	v_and_b32_e32 v4, 0x1ffff0, v4
	v_and_b32_e32 v3, 32, v3
	v_ashrrev_i16_sdwa v2, v134, sext(v2) dst_sel:DWORD dst_unused:UNUSED_PAD src0_sel:DWORD src1_sel:BYTE_0
	s_addc_u32 s31, s3, 0
	s_lshl_b32 s34, s10, 19
	v_add_u32_sdwa v2, v3, sext(v2) dst_sel:DWORD dst_unused:UNUSED_PAD src0_sel:DWORD src1_sel:WORD_0
	v_add_lshl_u32 v3, v6, v4, 11
	v_add_u32_e32 v141, s65, v1
	s_add_u32 s34, s33, s34
	v_lshl_add_u32 v131, v2, 1, v3
	v_readfirstlane_b32 s36, v141
	v_add_u32_e32 v142, 0x2000, v141
	s_addc_u32 s35, s40, 0
	s_waitcnt vmcnt(0)
	v_mov_b32_e32 v2, v130
	v_mov_b32_e32 v3, v131
	s_mov_b32 m0, s36
	v_readfirstlane_b32 s36, v142
	v_add_u32_e32 v143, 16, v1
	s_barrier
	v_add_u32_e32 v144, 0x2000, v143
	global_load_lds_dwordx4 v2, s[34:35]
	s_mov_b32 m0, s36
	v_readfirstlane_b32 s36, v143
	global_load_lds_dwordx4 v3, s[34:35]
	v_mov_b32_e32 v2, v130
	v_mov_b32_e32 v3, v131
	s_mov_b32 m0, s36
	v_readfirstlane_b32 s36, v144
	v_add_u32_e32 v145, s66, v1
	v_add_u32_e32 v146, 0x2000, v145
	global_load_lds_dwordx4 v2, s[30:31]
	s_mov_b32 m0, s36
	s_add_u32 s36, s34, 0x40000
	v_readfirstlane_b32 s38, v145
	global_load_lds_dwordx4 v3, s[30:31]
	s_addc_u32 s37, s35, 0
	v_mov_b32_e32 v2, v130
	v_mov_b32_e32 v3, v131
	s_mov_b32 m0, s38
	v_readfirstlane_b32 s38, v146
	v_add_u32_e32 v147, 0x4000, v143
	global_load_lds_dwordx4 v2, s[36:37]
	s_mov_b32 m0, s38
	v_readfirstlane_b32 s38, v147
	global_load_lds_dwordx4 v3, s[36:37]
	s_add_u32 s36, s30, 0x40000
	v_add_u32_e32 v148, 0x6000, v143
	s_addc_u32 s37, s31, 0
	v_mov_b32_e32 v2, v130
	v_mov_b32_e32 v3, v131
	s_mov_b32 m0, s38
	v_readfirstlane_b32 s38, v148
	s_and_b64 vcc, exec, s[4:5]
	global_load_lds_dwordx4 v2, s[36:37]
	s_mov_b32 m0, s38
	s_nop 0
	global_load_lds_dwordx4 v3, s[36:37]
	s_cbranch_vccnz .LBB0_979
	s_barrier

; __device__ __forceinline__ float shfl_xor_f(float v, int mask) { const int l = lane_fresh(); return __int_as_float(__builtin_amdgcn_ds_bpermute((l ^ mask) << 2, __float_as_int(v))); }
; __device__ __forceinline__ void phaseG(const Params& p, const int wv, const int rep, unsigned* bar, const bool fused) {
;     ...
;       if (last_l[0]) {
;         __builtin_amdgcn_fence(__ATOMIC_ACQUIRE, "agent");
;         const int r = tid >> 5, c32 = tid & 31;
;         float* yrow = p.out + O_Y + (size_t)(TP + mt * 16 + r) * 1024;
;         float sq = __hip_atomic_load(XSS + (size_t)(mt * 16 + r) * 64 + c32 * 2, __ATOMIC_RELAXED, __HIP_MEMORY_SCOPE_AGENT)
;                  + __hip_atomic_load(XSS + (size_t)(mt * 16 + r) * 64 + c32 * 2 + 1, __ATOMIC_RELAXED, __HIP_MEMORY_SCOPE_AGENT);
;         sq += shfl_xor_f(sq, 16); sq += shfl_xor_f(sq, 8); sq += shfl_xor_f(sq, 4); sq += shfl_xor_f(sq, 2); sq += shfl_xor_f(sq, 1);
;         const float rs = rsqrtf(sq * (1.f / 1024.f) + EPS);
; #pragma unroll
;         for (int i = 0; i < 8; ++i) {
;           const int col = i * 128 + c32 * 4;
;           f32x4 v = *(const f32x4*)(yrow + col);
;           *(f32x4*)(yrow + col) = v * rs * *(const f32x4*)(wfin + col);
;         }
;       }
.LBB0_1200:
	s_or_b64 exec, exec, s[24:25]
	s_waitcnt lgkmcnt(0)
	s_barrier
	ds_read_b32 v2, v15 offset:32768
	s_waitcnt lgkmcnt(0)
	v_cmp_eq_u32_e32 vcc, 0, v2
	s_cbranch_vccnz .LBB0_1182
	v_ashrrev_i32_e32 v2, 5, v1
	v_and_b32_e32 v3, 31, v0
	v_add_u32_e32 v0, s22, v2
	v_ashrrev_i32_e32 v1, 31, v0
	v_lshlrev_b64 v[0:1], 8, v[0:1]
	v_lshl_add_u64 v[0:1], s[10:11], 0, v[0:1]
	v_lshlrev_b32_e32 v4, 3, v3
	v_lshl_add_u64 v[0:1], v[0:1], 0, v[4:5]
	s_waitcnt vmcnt(0)
	buffer_inv sc1
	global_load_dword v10, v[0:1], off sc1
	global_load_dword v11, v[0:1], off offset:4 sc1
	v_add_u32_e32 v0, s20, v2
	v_ashrrev_i32_e32 v1, 31, v0
	v_lshlrev_b64 v[0:1], 12, v[0:1]
	v_lshl_add_u64 v[0:1], s[48:49], 0, v[0:1]
	v_lshlrev_b32_e32 v4, 4, v3
	v_lshl_add_u64 v[16:17], v[0:1], 0, v[4:5]
	v_mbcnt_lo_u32_b32 v12, -1, 0
	v_mbcnt_hi_u32_b32 v12, -1, v12
	v_mbcnt_lo_u32_b32 v13, -1, 0
	v_mbcnt_hi_u32_b32 v13, -1, v13
	v_mbcnt_lo_u32_b32 v18, -1, 0
	v_mbcnt_hi_u32_b32 v18, -1, v18
	v_mbcnt_lo_u32_b32 v19, -1, 0
	v_mbcnt_hi_u32_b32 v19, -1, v19
	v_mbcnt_lo_u32_b32 v20, -1, 0
	v_mbcnt_hi_u32_b32 v20, -1, v20
	global_load_dwordx4 v[60:63], v[16:17], off
	global_load_dwordx4 v[92:95], v4, s[46:47]
	global_load_dwordx4 v[64:67], v[16:17], off offset:512
	global_load_dwordx4 v[96:99], v4, s[46:47] offset:512
	global_load_dwordx4 v[68:71], v[16:17], off offset:1024
	global_load_dwordx4 v[100:103], v4, s[46:47] offset:1024
	global_load_dwordx4 v[72:75], v[16:17], off offset:1536
	global_load_dwordx4 v[104:107], v4, s[46:47] offset:1536
	global_load_dwordx4 v[76:79], v[16:17], off offset:2048
	global_load_dwordx4 v[108:111], v4, s[46:47] offset:2048
	global_load_dwordx4 v[80:83], v[16:17], off offset:2560
	global_load_dwordx4 v[112:115], v4, s[46:47] offset:2560
	global_load_dwordx4 v[84:87], v[16:17], off offset:3072
	global_load_dwordx4 v[116:119], v4, s[46:47] offset:3072
	global_load_dwordx4 v[88:91], v[16:17], off offset:3584
	global_load_dwordx4 v[120:123], v4, s[46:47] offset:3584
	v_lshlrev_b32_e32 v12, 2, v12
	v_xor_b32_e32 v12, 64, v12
	s_waitcnt vmcnt(16)
	v_add_f32_e32 v10, v11, v10
	ds_bpermute_b32 v11, v12, v10
	v_lshlrev_b32_e32 v12, 2, v13
	v_xor_b32_e32 v12, 32, v12
	s_waitcnt lgkmcnt(0)
	v_add_f32_e32 v10, v10, v11
	s_nop 1
	v_mov_b32_dpp v11, v10 row_ror:8 row_mask:0xf bank_mask:0xf
	v_lshlrev_b32_e32 v12, 2, v18
	v_xor_b32_e32 v12, 16, v12
	v_add_f32_e32 v10, v10, v11
	s_nop 1
	v_mov_b32_dpp v11, v10 row_shl:4 row_mask:0xf bank_mask:0x5
	v_mov_b32_dpp v11, v10 row_shr:4 row_mask:0xf bank_mask:0xa
	v_lshlrev_b32_e32 v12, 2, v19
	v_xor_b32_e32 v12, 8, v12
	v_add_f32_e32 v10, v10, v11
	s_nop 1
	v_mov_b32_dpp v11, v10 quad_perm:[2,3,0,1] row_mask:0xf bank_mask:0xf
	v_lshlrev_b32_e32 v12, 2, v20
	v_xor_b32_e32 v12, 4, v12
	v_add_f32_e32 v10, v10, v11
	s_nop 1
	v_mov_b32_dpp v11, v10 quad_perm:[1,0,3,2] row_mask:0xf bank_mask:0xf
	v_add_f32_e32 v10, v10, v11
	v_fmamk_f32 v10, v10, 0x3a800000, v14
	v_mul_f32_e32 v11, 0x4b800000, v10
	v_cmp_gt_f32_e32 vcc, s37, v10
	s_nop 1
	v_cndmask_b32_e32 v10, v10, v11, vcc
	v_rsq_f32_e32 v18, v10
	v_mul_f32_e32 v19, 0x45800000, v18
	v_cndmask_b32_e32 v18, v18, v19, vcc
	s_waitcnt vmcnt(14)
	v_pk_mul_f32 v[60:61], v[60:61], v[18:19] op_sel_hi:[1,0]
	v_pk_mul_f32 v[62:63], v[62:63], v[18:19] op_sel_hi:[1,0]
	v_pk_mul_f32 v[60:61], v[92:93], v[60:61]
	v_pk_mul_f32 v[62:63], v[94:95], v[62:63]
	global_store_dwordx4 v[16:17], v[60:63], off sc1
	s_waitcnt vmcnt(13)
	v_pk_mul_f32 v[64:65], v[64:65], v[18:19] op_sel_hi:[1,0]
	v_pk_mul_f32 v[66:67], v[66:67], v[18:19] op_sel_hi:[1,0]
	v_pk_mul_f32 v[64:65], v[96:97], v[64:65]
	v_pk_mul_f32 v[66:67], v[98:99], v[66:67]
	global_store_dwordx4 v[16:17], v[64:67], off offset:512 sc1
	s_waitcnt vmcnt(12)
	v_pk_mul_f32 v[68:69], v[68:69], v[18:19] op_sel_hi:[1,0]
	v_pk_mul_f32 v[70:71], v[70:71], v[18:19] op_sel_hi:[1,0]
	v_pk_mul_f32 v[68:69], v[100:101], v[68:69]
	v_pk_mul_f32 v[70:71], v[102:103], v[70:71]
	global_store_dwordx4 v[16:17], v[68:71], off offset:1024 sc1
	s_waitcnt vmcnt(11)
	v_pk_mul_f32 v[72:73], v[72:73], v[18:19] op_sel_hi:[1,0]
	v_pk_mul_f32 v[74:75], v[74:75], v[18:19] op_sel_hi:[1,0]
	v_pk_mul_f32 v[72:73], v[104:105], v[72:73]
	v_pk_mul_f32 v[74:75], v[106:107], v[74:75]
	global_store_dwordx4 v[16:17], v[72:75], off offset:1536 sc1
	s_waitcnt vmcnt(10)
	v_pk_mul_f32 v[76:77], v[76:77], v[18:19] op_sel_hi:[1,0]
	v_pk_mul_f32 v[78:79], v[78:79], v[18:19] op_sel_hi:[1,0]
	v_pk_mul_f32 v[76:77], v[108:109], v[76:77]
	v_pk_mul_f32 v[78:79], v[110:111], v[78:79]
	global_store_dwordx4 v[16:17], v[76:79], off offset:2048 sc1
	s_waitcnt vmcnt(9)
	v_pk_mul_f32 v[80:81], v[80:81], v[18:19] op_sel_hi:[1,0]
	v_pk_mul_f32 v[82:83], v[82:83], v[18:19] op_sel_hi:[1,0]
	v_pk_mul_f32 v[80:81], v[112:113], v[80:81]
	v_pk_mul_f32 v[82:83], v[114:115], v[82:83]
	global_store_dwordx4 v[16:17], v[80:83], off offset:2560 sc1
	s_waitcnt vmcnt(8)
	v_pk_mul_f32 v[84:85], v[84:85], v[18:19] op_sel_hi:[1,0]
	v_pk_mul_f32 v[86:87], v[86:87], v[18:19] op_sel_hi:[1,0]
	v_pk_mul_f32 v[84:85], v[116:117], v[84:85]
	v_pk_mul_f32 v[86:87], v[118:119], v[86:87]
	global_store_dwordx4 v[16:17], v[84:87], off offset:3072 sc1
	s_waitcnt vmcnt(7)
	v_pk_mul_f32 v[88:89], v[88:89], v[18:19] op_sel_hi:[1,0]
	v_pk_mul_f32 v[90:91], v[90:91], v[18:19] op_sel_hi:[1,0]
	v_pk_mul_f32 v[88:89], v[120:121], v[88:89]
	v_pk_mul_f32 v[90:91], v[122:123], v[90:91]
	global_store_dwordx4 v[16:17], v[88:91], off offset:3584 sc1
	s_branch .LBB0_1182

; __device__ __forceinline__ void phaseH(const Params& p, const int wv, const int rep) {
;     ...
;   for (int r_ = gw; r_ < T * rep; r_ += nw) {
;     const int r = r_ >= T ? r_ - T : r_;
;     float* x = p.out + O_Y + (size_t)r * 1024;
;     f32x4 v[4]; float ss = 0.f;
; #pragma unroll
;     for (int i = 0; i < 4; ++i) { v[i] = *(const f32x4*)(x + (i * 64 + lane) * 4); ss += v[i][0] * v[i][0] + v[i][1] * v[i][1] + v[i][2] * v[i][2] + v[i][3] * v[i][3]; }
;     ss = wave_sum(ss);
;     const float rstd = rsqrtf(ss * (1.f / 1024.f) + EPS);
; #pragma unroll
;     for (int i = 0; i < 4; ++i) { f32x4 wv = *(const f32x4*)(w + (i * 64 + lane) * 4); *(f32x4*)(x + (i * 64 + lane) * 4) = v[i] * rstd * wv; }
;   }
.LBB0_1259:
	global_load_dwordx4 v[6:9], v[2:3], off offset:-3072
	global_load_dwordx4 v[10:13], v[2:3], off offset:-2048
	global_load_dwordx4 v[14:17], v[2:3], off offset:-1024
	global_load_dwordx4 v[18:21], v[2:3], off
	v_mbcnt_lo_u32_b32 v5, -1, 0
	v_mbcnt_hi_u32_b32 v5, -1, v5
	v_mbcnt_lo_u32_b32 v42, -1, 0
	v_mbcnt_hi_u32_b32 v42, -1, v42
	v_mbcnt_lo_u32_b32 v43, -1, 0
	v_mbcnt_hi_u32_b32 v43, -1, v43
	v_mbcnt_lo_u32_b32 v44, -1, 0
	v_mbcnt_hi_u32_b32 v44, -1, v44
	v_mbcnt_lo_u32_b32 v45, -1, 0
	v_mbcnt_hi_u32_b32 v45, -1, v45
	v_mbcnt_lo_u32_b32 v46, -1, 0
	v_mbcnt_hi_u32_b32 v46, -1, v46
	global_load_dwordx4 v[22:25], v[0:1], off
	v_lshlrev_b32_e32 v5, 2, v5
	v_xor_b32_e32 v5, 0x80, v5
	s_add_i32 s4, s4, s6
	s_cmpk_lt_i32 s4, 0x4080
	s_waitcnt vmcnt(4)
	v_mov_b32_e32 v28, v7
	s_waitcnt vmcnt(3)
	v_mov_b32_e32 v29, v11
	v_mov_b32_e32 v26, v6
	v_mov_b32_e32 v27, v10
	s_waitcnt vmcnt(2)
	v_mov_b32_e32 v36, v15
	s_waitcnt vmcnt(1)
	v_mov_b32_e32 v37, v19
	v_pk_mul_f32 v[28:29], v[28:29], v[28:29]
	v_mov_b32_e32 v30, v8
	v_mov_b32_e32 v31, v12
	v_mov_b32_e32 v34, v14
	v_mov_b32_e32 v35, v18
	v_pk_mul_f32 v[36:37], v[36:37], v[36:37]
	v_pk_fma_f32 v[26:27], v[26:27], v[26:27], v[28:29]
	v_mov_b32_e32 v32, v9
	v_mov_b32_e32 v33, v13
	v_mov_b32_e32 v38, v16
	v_mov_b32_e32 v39, v20
	v_pk_fma_f32 v[28:29], v[34:35], v[34:35], v[36:37]
	v_pk_fma_f32 v[26:27], v[30:31], v[30:31], v[26:27]
	v_mov_b32_e32 v40, v17
	v_mov_b32_e32 v41, v21
	v_pk_fma_f32 v[28:29], v[38:39], v[38:39], v[28:29]
	v_pk_fma_f32 v[26:27], v[32:33], v[32:33], v[26:27]
	v_pk_fma_f32 v[28:29], v[40:41], v[40:41], v[28:29]
	v_add_f32_e32 v26, v26, v27
	v_add_f32_e32 v26, v26, v28
	v_add_f32_e32 v26, v26, v29
	ds_bpermute_b32 v5, v5, v26
	v_lshlrev_b32_e32 v27, 2, v42
	v_xor_b32_e32 v27, 64, v27
	s_waitcnt lgkmcnt(0)
	v_add_f32_e32 v5, v26, v5
	ds_bpermute_b32 v26, v27, v5
	v_lshlrev_b32_e32 v27, 2, v43
	v_xor_b32_e32 v27, 32, v27
	s_waitcnt lgkmcnt(0)
	v_add_f32_e32 v5, v5, v26
	s_nop 1
	v_mov_b32_dpp v26, v5 row_ror:8 row_mask:0xf bank_mask:0xf
	v_lshlrev_b32_e32 v27, 2, v44
	v_xor_b32_e32 v27, 16, v27
	v_add_f32_e32 v5, v5, v26
	s_nop 1
	v_mov_b32_dpp v26, v5 row_shl:4 row_mask:0xf bank_mask:0x5
	v_mov_b32_dpp v26, v5 row_shr:4 row_mask:0xf bank_mask:0xa
	v_lshlrev_b32_e32 v27, 2, v45
	v_xor_b32_e32 v27, 8, v27
	v_add_f32_e32 v5, v5, v26
	s_nop 1
	v_mov_b32_dpp v26, v5 quad_perm:[2,3,0,1] row_mask:0xf bank_mask:0xf
	v_lshlrev_b32_e32 v27, 2, v46
	v_xor_b32_e32 v27, 4, v27
	v_add_f32_e32 v5, v5, v26
	s_nop 1
	v_mov_b32_dpp v26, v5 quad_perm:[1,0,3,2] row_mask:0xf bank_mask:0xf
	v_add_f32_e32 v5, v5, v26
	v_fmamk_f32 v5, v5, 0x3a800000, v4
	v_mul_f32_e32 v26, 0x4b800000, v5
	v_cmp_gt_f32_e32 vcc, s2, v5
	s_nop 1
	v_cndmask_b32_e32 v5, v5, v26, vcc
	v_rsq_f32_e32 v5, v5
	s_nop 0
	v_mul_f32_e32 v26, 0x45800000, v5
	v_cndmask_b32_e32 v26, v5, v26, vcc
	v_pk_mul_f32 v[6:7], v[6:7], v[26:27] op_sel_hi:[1,0]
	v_pk_mul_f32 v[8:9], v[8:9], v[26:27] op_sel_hi:[1,0]
	s_waitcnt vmcnt(0)
	v_pk_mul_f32 v[6:7], v[22:23], v[6:7]
	v_pk_mul_f32 v[8:9], v[24:25], v[8:9]
	global_store_dwordx4 v[2:3], v[6:9], off offset:-3072 sc1
	global_load_dwordx4 v[6:9], v[0:1], off offset:1024
	v_pk_mul_f32 v[12:13], v[12:13], v[26:27] op_sel_hi:[1,0]
	v_pk_mul_f32 v[10:11], v[10:11], v[26:27] op_sel_hi:[1,0]
	s_waitcnt vmcnt(0)
	v_pk_mul_f32 v[8:9], v[8:9], v[12:13]
	v_pk_mul_f32 v[6:7], v[6:7], v[10:11]
	global_store_dwordx4 v[2:3], v[6:9], off offset:-2048 sc1
	global_load_dwordx4 v[6:9], v[0:1], off offset:2048
	v_pk_mul_f32 v[10:11], v[16:17], v[26:27] op_sel_hi:[1,0]
	v_pk_mul_f32 v[12:13], v[14:15], v[26:27] op_sel_hi:[1,0]
	s_waitcnt vmcnt(0)
	v_pk_mul_f32 v[8:9], v[8:9], v[10:11]
	v_pk_mul_f32 v[6:7], v[6:7], v[12:13]
	global_store_dwordx4 v[2:3], v[6:9], off offset:-1024 sc1
	global_load_dwordx4 v[6:9], v[0:1], off offset:3072
	v_pk_mul_f32 v[10:11], v[20:21], v[26:27] op_sel_hi:[1,0]
	v_pk_mul_f32 v[12:13], v[18:19], v[26:27] op_sel_hi:[1,0]
	s_waitcnt vmcnt(0)
	v_pk_mul_f32 v[8:9], v[8:9], v[10:11]
	v_pk_mul_f32 v[6:7], v[6:7], v[12:13]
	global_store_dwordx4 v[2:3], v[6:9], off sc1
	v_lshl_add_u64 v[2:3], v[2:3], 0, s[0:1]
	s_cbranch_scc1 .LBB0_1259
